# GEMM K loops: first iteration peeled with C=0 MFMAs instead of zeroing accumulators with v_mov; attention unmasked stage software-pipelined
# speedup vs baseline: 1.0510x; 1.0064x over previous
.LBB0_202:
	s_add_u32 s94, s68, 0x84080
	s_addc_u32 s95, s69, 0
	s_add_u32 s28, s70, 0x100
	s_addc_u32 s29, s71, 0
	s_mov_b32 s34, -2
	s_mov_b64 s[16:17], 0x58000
	s_mov_b64 s[18:19], 0xb0000
	s_mov_b64 s[20:21], 0x108000
	s_mov_b64 s[22:23], 0x84000
	s_mov_b64 s[24:25], 0xdc000
	s_mov_b64 s[26:27], 0xb0080
	s_mov_b64 s[30:31], 0x108080
	ds_read_b128 v[100:103], v116
	ds_read_b128 v[104:107], v116 offset:1024
	ds_read_b128 v[108:111], v116 offset:2048
	ds_read_b128 v[112:115], v116 offset:3072
	ds_read_b128 v[124:127], v117
	ds_read_b128 v[128:131], v117 offset:1024
	ds_read_b128 v[132:135], v117 offset:2048
	ds_read_b128 v[136:139], v117 offset:3072
	s_add_u32 s35, s94, 0xfff7c080
	s_addc_u32 s36, s95, -1
	s_cmp_eq_u32 s34, 40
	s_cselect_b32 s37, s89, s36
	s_cselect_b32 s36, s88, s35
	s_cselect_b32 s39, s91, s29
	s_cselect_b32 s38, s90, s28
	v_lshl_add_u64 v[170:171], s[94:95], 0, v[98:99]
	s_add_i32 m0, s76, 0xc000
	ds_read_b128 v[140:143], v118
	ds_read_b128 v[144:147], v118 offset:1024
	ds_read_b128 v[148:151], v119
	ds_read_b128 v[158:161], v119 offset:1024
	ds_read_b128 v[162:165], v120
	ds_read_b128 v[166:169], v120 offset:1024
	global_load_lds_dwordx4 v[170:171], off
	v_lshl_add_u64 v[170:171], v[170:171], 0, s[16:17]
	s_add_i32 m0, s76, 0xe000
	s_nop 0
	global_load_lds_dwordx4 v[170:171], off
	s_waitcnt vmcnt(8)
	s_waitcnt lgkmcnt(0)
	s_barrier
	s_setprio 1
	s_waitcnt lgkmcnt(0)
	v_mfma_f32_16x16x32_bf16 v[92:95], v[100:103], v[140:143], 0
	v_mfma_f32_16x16x32_bf16 v[88:91], v[108:111], v[140:143], 0
	v_mfma_f32_16x16x32_bf16 v[76:79], v[100:103], v[148:151], 0
	v_mfma_f32_16x16x32_bf16 v[72:75], v[108:111], v[148:151], 0
	v_mfma_f32_16x16x32_bf16 v[60:63], v[100:103], v[162:165], 0
	v_mfma_f32_16x16x32_bf16 v[56:59], v[108:111], v[162:165], 0
	v_mfma_f32_16x16x32_bf16 v[92:95], v[104:107], v[144:147], v[92:95]
	v_mfma_f32_16x16x32_bf16 v[88:91], v[112:115], v[144:147], v[88:91]
	v_mfma_f32_16x16x32_bf16 v[76:79], v[104:107], v[158:161], v[76:79]
	v_mfma_f32_16x16x32_bf16 v[72:75], v[112:115], v[158:161], v[72:75]
	v_mfma_f32_16x16x32_bf16 v[60:63], v[104:107], v[166:169], v[60:63]
	v_mfma_f32_16x16x32_bf16 v[56:59], v[112:115], v[166:169], v[56:59]
	s_setprio 0
	s_setprio 1
	v_mfma_f32_16x16x32_bf16 v[84:87], v[124:127], v[140:143], 0
	v_mfma_f32_16x16x32_bf16 v[80:83], v[132:135], v[140:143], 0
	v_mfma_f32_16x16x32_bf16 v[68:71], v[124:127], v[148:151], 0
	v_mfma_f32_16x16x32_bf16 v[64:67], v[132:135], v[148:151], 0
	v_mfma_f32_16x16x32_bf16 v[52:55], v[124:127], v[162:165], 0
	v_mfma_f32_16x16x32_bf16 v[48:51], v[132:135], v[162:165], 0
	v_mfma_f32_16x16x32_bf16 v[84:87], v[128:131], v[144:147], v[84:87]
	v_mfma_f32_16x16x32_bf16 v[80:83], v[136:139], v[144:147], v[80:83]
	v_mfma_f32_16x16x32_bf16 v[68:71], v[128:131], v[158:161], v[68:71]
	v_mfma_f32_16x16x32_bf16 v[64:67], v[136:139], v[158:161], v[64:67]
	v_mfma_f32_16x16x32_bf16 v[52:55], v[128:131], v[166:169], v[52:55]
	v_mfma_f32_16x16x32_bf16 v[48:51], v[136:139], v[166:169], v[48:51]
	s_setprio 0
	s_barrier
	s_mov_b32 m0, s78
	v_lshl_add_u64 v[170:171], s[38:39], 0, v[96:97]
	ds_read_b128 v[140:143], v118 offset:16384
	ds_read_b128 v[144:147], v118 offset:17408
	ds_read_b128 v[148:151], v119 offset:16384
	ds_read_b128 v[158:161], v119 offset:17408
	ds_read_b128 v[162:165], v120 offset:16384
	ds_read_b128 v[166:169], v120 offset:17408
	global_load_lds_dwordx4 v[170:171], off
	v_lshl_add_u64 v[172:173], v[170:171], 0, s[16:17]
	s_mov_b32 m0, s79
	s_nop 0
	global_load_lds_dwordx4 v[172:173], off
	v_lshl_add_u64 v[172:173], v[170:171], 0, s[18:19]
	s_mov_b32 m0, s74
	s_nop 0
	global_load_lds_dwordx4 v[172:173], off
	v_lshl_add_u64 v[172:173], v[170:171], 0, s[20:21]
	s_mov_b32 m0, s83
	s_nop 0
	global_load_lds_dwordx4 v[172:173], off
	v_lshl_add_u64 v[172:173], s[36:37], 0, v[96:97]
	s_mov_b32 m0, s76
	v_lshl_add_u64 v[174:175], v[172:173], 0, s[16:17]
	global_load_lds_dwordx4 v[172:173], off
	s_mov_b32 m0, s85
	s_nop 0
	global_load_lds_dwordx4 v[174:175], off
	s_waitcnt vmcnt(8)
	s_waitcnt lgkmcnt(0)
	s_barrier
	s_setprio 1
	s_waitcnt lgkmcnt(0)
	v_mfma_f32_16x16x32_bf16 v[44:47], v[100:103], v[140:143], 0
	v_mfma_f32_16x16x32_bf16 v[40:43], v[108:111], v[140:143], 0
	v_mfma_f32_16x16x32_bf16 v[28:31], v[100:103], v[148:151], 0
	v_mfma_f32_16x16x32_bf16 v[24:27], v[108:111], v[148:151], 0
	v_mfma_f32_16x16x32_bf16 v[12:15], v[100:103], v[162:165], 0
	v_mfma_f32_16x16x32_bf16 v[8:11], v[108:111], v[162:165], 0
	v_mfma_f32_16x16x32_bf16 v[44:47], v[104:107], v[144:147], v[44:47]
	v_mfma_f32_16x16x32_bf16 v[40:43], v[112:115], v[144:147], v[40:43]
	v_mfma_f32_16x16x32_bf16 v[28:31], v[104:107], v[158:161], v[28:31]
	v_mfma_f32_16x16x32_bf16 v[24:27], v[112:115], v[158:161], v[24:27]
	v_mfma_f32_16x16x32_bf16 v[12:15], v[104:107], v[166:169], v[12:15]
	v_mfma_f32_16x16x32_bf16 v[8:11], v[112:115], v[166:169], v[8:11]
	s_setprio 0
	s_setprio 1
	v_mfma_f32_16x16x32_bf16 v[36:39], v[124:127], v[140:143], 0
	v_mfma_f32_16x16x32_bf16 v[32:35], v[132:135], v[140:143], 0
	v_mfma_f32_16x16x32_bf16 v[20:23], v[124:127], v[148:151], 0
	v_mfma_f32_16x16x32_bf16 v[16:19], v[132:135], v[148:151], 0
	v_mfma_f32_16x16x32_bf16 v[4:7], v[124:127], v[162:165], 0
	v_mfma_f32_16x16x32_bf16 v[0:3], v[132:135], v[162:165], 0
	v_mfma_f32_16x16x32_bf16 v[36:39], v[128:131], v[144:147], v[36:39]
	v_mfma_f32_16x16x32_bf16 v[32:35], v[136:139], v[144:147], v[32:35]
	v_mfma_f32_16x16x32_bf16 v[20:23], v[128:131], v[158:161], v[20:23]
	v_mfma_f32_16x16x32_bf16 v[16:19], v[136:139], v[158:161], v[16:19]
	v_mfma_f32_16x16x32_bf16 v[4:7], v[128:131], v[166:169], v[4:7]
	v_mfma_f32_16x16x32_bf16 v[0:3], v[136:139], v[166:169], v[0:3]
	s_setprio 0
	s_barrier
	ds_read_b128 v[100:103], v121
	ds_read_b128 v[104:107], v121 offset:1024
	ds_read_b128 v[108:111], v121 offset:2048
	ds_read_b128 v[112:115], v121 offset:3072
	ds_read_b128 v[124:127], v122
	ds_read_b128 v[128:131], v122 offset:1024
	ds_read_b128 v[132:135], v122 offset:2048
	ds_read_b128 v[136:139], v122 offset:3072
	s_mov_b32 m0, s33
	v_lshl_add_u64 v[174:175], v[172:173], 0, s[22:23]
	ds_read_b128 v[140:143], v118 offset:32768
	ds_read_b128 v[144:147], v118 offset:33792
	ds_read_b128 v[148:151], v119 offset:32768
	ds_read_b128 v[158:161], v119 offset:33792
	ds_read_b128 v[162:165], v120 offset:32768
	ds_read_b128 v[166:169], v120 offset:33792
	global_load_lds_dwordx4 v[174:175], off
	v_lshl_add_u64 v[174:175], v[172:173], 0, s[24:25]
	s_mov_b32 m0, s72
	s_nop 0
	global_load_lds_dwordx4 v[174:175], off
	s_waitcnt vmcnt(8)
	s_waitcnt lgkmcnt(0)
	s_barrier
	s_setprio 1
	s_waitcnt lgkmcnt(0)
	v_mfma_f32_16x16x32_bf16 v[92:95], v[100:103], v[140:143], v[92:95]
	v_mfma_f32_16x16x32_bf16 v[88:91], v[108:111], v[140:143], v[88:91]
	v_mfma_f32_16x16x32_bf16 v[76:79], v[100:103], v[148:151], v[76:79]
	v_mfma_f32_16x16x32_bf16 v[72:75], v[108:111], v[148:151], v[72:75]
	v_mfma_f32_16x16x32_bf16 v[60:63], v[100:103], v[162:165], v[60:63]
	v_mfma_f32_16x16x32_bf16 v[56:59], v[108:111], v[162:165], v[56:59]
	v_mfma_f32_16x16x32_bf16 v[92:95], v[104:107], v[144:147], v[92:95]
	v_mfma_f32_16x16x32_bf16 v[88:91], v[112:115], v[144:147], v[88:91]
	v_mfma_f32_16x16x32_bf16 v[76:79], v[104:107], v[158:161], v[76:79]
	v_mfma_f32_16x16x32_bf16 v[72:75], v[112:115], v[158:161], v[72:75]
	v_mfma_f32_16x16x32_bf16 v[60:63], v[104:107], v[166:169], v[60:63]
	v_mfma_f32_16x16x32_bf16 v[56:59], v[112:115], v[166:169], v[56:59]
	s_setprio 0
	s_setprio 1
	v_mfma_f32_16x16x32_bf16 v[84:87], v[124:127], v[140:143], v[84:87]
	v_mfma_f32_16x16x32_bf16 v[80:83], v[132:135], v[140:143], v[80:83]
	v_mfma_f32_16x16x32_bf16 v[68:71], v[124:127], v[148:151], v[68:71]
	v_mfma_f32_16x16x32_bf16 v[64:67], v[132:135], v[148:151], v[64:67]
	v_mfma_f32_16x16x32_bf16 v[52:55], v[124:127], v[162:165], v[52:55]
	v_mfma_f32_16x16x32_bf16 v[48:51], v[132:135], v[162:165], v[48:51]
	v_mfma_f32_16x16x32_bf16 v[84:87], v[128:131], v[144:147], v[84:87]
	v_mfma_f32_16x16x32_bf16 v[80:83], v[136:139], v[144:147], v[80:83]
	v_mfma_f32_16x16x32_bf16 v[68:71], v[128:131], v[158:161], v[68:71]
	v_mfma_f32_16x16x32_bf16 v[64:67], v[136:139], v[158:161], v[64:67]
	v_mfma_f32_16x16x32_bf16 v[52:55], v[128:131], v[166:169], v[52:55]
	v_mfma_f32_16x16x32_bf16 v[48:51], v[136:139], v[166:169], v[48:51]
	s_setprio 0
	s_barrier
	v_lshl_add_u64 v[174:175], v[170:171], 0, s[48:49]
	s_add_i32 m0, s76, 0x18000
	ds_read_b128 v[140:143], v118 offset:49152
	ds_read_b128 v[144:147], v118 offset:50176
	ds_read_b128 v[148:151], v119 offset:49152
	ds_read_b128 v[158:161], v119 offset:50176
	ds_read_b128 v[162:165], v120 offset:49152
	ds_read_b128 v[166:169], v120 offset:50176
	global_load_lds_dwordx4 v[174:175], off
	v_lshl_add_u64 v[174:175], v[170:171], 0, s[4:5]
	s_add_i32 m0, s76, 0x1a000
	s_nop 0
	global_load_lds_dwordx4 v[174:175], off
	v_lshl_add_u64 v[174:175], v[170:171], 0, s[26:27]
	s_add_i32 m0, s76, 0x1c000
	v_lshl_add_u64 v[170:171], v[170:171], 0, s[30:31]
	global_load_lds_dwordx4 v[174:175], off
	s_add_i32 m0, s76, 0x1e000
	s_nop 0
	global_load_lds_dwordx4 v[170:171], off
	v_lshl_add_u64 v[170:171], v[172:173], 0, s[48:49]
	s_mov_b32 m0, s73
	s_nop 0
	global_load_lds_dwordx4 v[170:171], off
	v_lshl_add_u64 v[170:171], v[172:173], 0, s[4:5]
	s_mov_b32 m0, s75
	s_nop 0
	global_load_lds_dwordx4 v[170:171], off
	s_waitcnt vmcnt(8)
	s_waitcnt lgkmcnt(0)
	s_barrier
	s_setprio 1
	s_waitcnt lgkmcnt(0)
	v_mfma_f32_16x16x32_bf16 v[44:47], v[100:103], v[140:143], v[44:47]
	v_mfma_f32_16x16x32_bf16 v[40:43], v[108:111], v[140:143], v[40:43]
	v_mfma_f32_16x16x32_bf16 v[28:31], v[100:103], v[148:151], v[28:31]
	v_mfma_f32_16x16x32_bf16 v[24:27], v[108:111], v[148:151], v[24:27]
	v_mfma_f32_16x16x32_bf16 v[12:15], v[100:103], v[162:165], v[12:15]
	v_mfma_f32_16x16x32_bf16 v[8:11], v[108:111], v[162:165], v[8:11]
	v_mfma_f32_16x16x32_bf16 v[44:47], v[104:107], v[144:147], v[44:47]
	v_mfma_f32_16x16x32_bf16 v[40:43], v[112:115], v[144:147], v[40:43]
	v_mfma_f32_16x16x32_bf16 v[28:31], v[104:107], v[158:161], v[28:31]
	v_mfma_f32_16x16x32_bf16 v[24:27], v[112:115], v[158:161], v[24:27]
	v_mfma_f32_16x16x32_bf16 v[12:15], v[104:107], v[166:169], v[12:15]
	v_mfma_f32_16x16x32_bf16 v[8:11], v[112:115], v[166:169], v[8:11]
	s_setprio 0
	s_setprio 1
	v_mfma_f32_16x16x32_bf16 v[36:39], v[124:127], v[140:143], v[36:39]
	v_mfma_f32_16x16x32_bf16 v[32:35], v[132:135], v[140:143], v[32:35]
	v_mfma_f32_16x16x32_bf16 v[20:23], v[124:127], v[148:151], v[20:23]
	v_mfma_f32_16x16x32_bf16 v[16:19], v[132:135], v[148:151], v[16:19]
	v_mfma_f32_16x16x32_bf16 v[4:7], v[124:127], v[162:165], v[4:7]
	v_mfma_f32_16x16x32_bf16 v[0:3], v[132:135], v[162:165], v[0:3]
	v_mfma_f32_16x16x32_bf16 v[36:39], v[128:131], v[144:147], v[36:39]
	v_mfma_f32_16x16x32_bf16 v[32:35], v[136:139], v[144:147], v[32:35]
	v_mfma_f32_16x16x32_bf16 v[20:23], v[128:131], v[158:161], v[20:23]
	v_mfma_f32_16x16x32_bf16 v[16:19], v[136:139], v[158:161], v[16:19]
	v_mfma_f32_16x16x32_bf16 v[4:7], v[128:131], v[166:169], v[4:7]
	v_mfma_f32_16x16x32_bf16 v[0:3], v[136:139], v[166:169], v[0:3]
	s_setprio 0
	s_barrier
	s_add_i32 s34, s34, 2
	s_add_u32 s94, s94, 0x100
	s_addc_u32 s95, s95, 0
	s_add_u32 s28, s28, 0x100
	s_addc_u32 s29, s29, 0
	s_cmp_lt_u32 s34, 42

.LBB0_224:
	s_add_u32 s94, s68, 0x40080
	s_addc_u32 s95, s69, 0
	s_add_u32 s53, s70, 0x100
	s_addc_u32 s68, s71, 0
	s_mov_b32 s69, -2
	ds_read_b128 v[140:143], v132
	ds_read_b128 v[144:147], v132 offset:1024
	ds_read_b128 v[148:151], v132 offset:2048
	ds_read_b128 v[158:161], v132 offset:3072
	ds_read_b128 v[162:165], v133
	ds_read_b128 v[166:169], v133 offset:1024
	ds_read_b128 v[170:173], v133 offset:2048
	ds_read_b128 v[174:177], v133 offset:3072
	s_add_u32 s70, s94, 0xfffc0080
	s_addc_u32 s71, s95, -1
	s_cmp_eq_u32 s69, 12
	s_cselect_b32 s71, s55, s71
	s_cselect_b32 s70, s54, s70
	s_cselect_b32 vcc_hi, s89, s68
	s_cselect_b32 vcc_lo, s88, s53
	v_lshl_add_u64 v[190:191], s[94:95], 0, v[130:131]
	s_add_i32 m0, s29, 0xc000
	ds_read_b128 v[178:181], v134
	ds_read_b128 v[182:185], v134 offset:1024
	ds_read_b128 v[186:189], v135
	ds_read_b128 v[202:205], v135 offset:1024
	ds_read_b128 v[206:209], v136
	ds_read_b128 v[210:213], v136 offset:1024
	ds_read_b128 v[214:217], v137
	ds_read_b128 v[218:221], v137 offset:1024
	global_load_lds_dwordx4 v[190:191], off
	v_lshl_add_u64 v[190:191], v[190:191], 0, s[8:9]
	s_add_i32 m0, s29, 0xe000
	s_nop 0
	global_load_lds_dwordx4 v[190:191], off
	s_waitcnt vmcnt(8)
	s_waitcnt lgkmcnt(0)
	s_barrier
	s_setprio 1
	s_waitcnt lgkmcnt(0)
	v_mfma_f32_16x16x32_bf16 v[124:127], v[140:143], v[178:181], 0
	v_mfma_f32_16x16x32_bf16 v[120:123], v[148:151], v[178:181], 0
	v_mfma_f32_16x16x32_bf16 v[108:111], v[140:143], v[186:189], 0
	v_mfma_f32_16x16x32_bf16 v[104:107], v[148:151], v[186:189], 0
	v_mfma_f32_16x16x32_bf16 v[92:95], v[140:143], v[206:209], 0
	v_mfma_f32_16x16x32_bf16 v[88:91], v[148:151], v[206:209], 0
	v_mfma_f32_16x16x32_bf16 v[76:79], v[140:143], v[214:217], 0
	v_mfma_f32_16x16x32_bf16 v[72:75], v[148:151], v[214:217], 0
	v_mfma_f32_16x16x32_bf16 v[124:127], v[144:147], v[182:185], v[124:127]
	v_mfma_f32_16x16x32_bf16 v[120:123], v[158:161], v[182:185], v[120:123]
	v_mfma_f32_16x16x32_bf16 v[108:111], v[144:147], v[202:205], v[108:111]
	v_mfma_f32_16x16x32_bf16 v[104:107], v[158:161], v[202:205], v[104:107]
	v_mfma_f32_16x16x32_bf16 v[92:95], v[144:147], v[210:213], v[92:95]
	v_mfma_f32_16x16x32_bf16 v[88:91], v[158:161], v[210:213], v[88:91]
	v_mfma_f32_16x16x32_bf16 v[76:79], v[144:147], v[218:221], v[76:79]
	v_mfma_f32_16x16x32_bf16 v[72:75], v[158:161], v[218:221], v[72:75]
	s_setprio 0
	s_setprio 1
	v_mfma_f32_16x16x32_bf16 v[116:119], v[162:165], v[178:181], 0
	v_mfma_f32_16x16x32_bf16 v[112:115], v[170:173], v[178:181], 0
	v_mfma_f32_16x16x32_bf16 v[100:103], v[162:165], v[186:189], 0
	v_mfma_f32_16x16x32_bf16 v[96:99], v[170:173], v[186:189], 0
	v_mfma_f32_16x16x32_bf16 v[84:87], v[162:165], v[206:209], 0
	v_mfma_f32_16x16x32_bf16 v[80:83], v[170:173], v[206:209], 0
	v_mfma_f32_16x16x32_bf16 v[68:71], v[162:165], v[214:217], 0
	v_mfma_f32_16x16x32_bf16 v[64:67], v[170:173], v[214:217], 0
	v_mfma_f32_16x16x32_bf16 v[116:119], v[166:169], v[182:185], v[116:119]
	v_mfma_f32_16x16x32_bf16 v[112:115], v[174:177], v[182:185], v[112:115]
	v_mfma_f32_16x16x32_bf16 v[100:103], v[166:169], v[202:205], v[100:103]
	v_mfma_f32_16x16x32_bf16 v[96:99], v[174:177], v[202:205], v[96:99]
	v_mfma_f32_16x16x32_bf16 v[84:87], v[166:169], v[210:213], v[84:87]
	v_mfma_f32_16x16x32_bf16 v[80:83], v[174:177], v[210:213], v[80:83]
	v_mfma_f32_16x16x32_bf16 v[68:71], v[166:169], v[218:221], v[68:71]
	v_mfma_f32_16x16x32_bf16 v[64:67], v[174:177], v[218:221], v[64:67]
	s_setprio 0
	s_barrier
	s_mov_b32 m0, s34
	v_lshl_add_u64 v[190:191], vcc, 0, v[128:129]
	ds_read_b128 v[178:181], v134 offset:16384
	ds_read_b128 v[182:185], v134 offset:17408
	ds_read_b128 v[186:189], v135 offset:16384
	ds_read_b128 v[202:205], v135 offset:17408
	ds_read_b128 v[206:209], v136 offset:16384
	ds_read_b128 v[210:213], v136 offset:17408
	ds_read_b128 v[214:217], v137 offset:16384
	ds_read_b128 v[218:221], v137 offset:17408
	global_load_lds_dwordx4 v[190:191], off
	v_lshl_add_u64 v[192:193], v[190:191], 0, s[8:9]
	s_mov_b32 m0, s35
	s_nop 0
	global_load_lds_dwordx4 v[192:193], off
	v_lshl_add_u64 v[192:193], v[190:191], 0, s[10:11]
	s_mov_b32 m0, s36
	s_nop 0
	global_load_lds_dwordx4 v[192:193], off
	v_lshl_add_u64 v[192:193], v[190:191], 0, s[12:13]
	s_mov_b32 m0, s37
	s_nop 0
	global_load_lds_dwordx4 v[192:193], off
	v_lshl_add_u64 v[192:193], s[70:71], 0, v[128:129]
	s_mov_b32 m0, s29
	v_lshl_add_u64 v[222:223], v[192:193], 0, s[8:9]
	global_load_lds_dwordx4 v[192:193], off
	s_mov_b32 m0, s38
	s_nop 0
	global_load_lds_dwordx4 v[222:223], off
	s_waitcnt vmcnt(8)
	s_waitcnt lgkmcnt(0)
	s_barrier
	s_setprio 1
	s_waitcnt lgkmcnt(0)
	v_mfma_f32_16x16x32_bf16 v[60:63], v[140:143], v[178:181], 0
	v_mfma_f32_16x16x32_bf16 v[56:59], v[148:151], v[178:181], 0
	v_mfma_f32_16x16x32_bf16 v[44:47], v[140:143], v[186:189], 0
	v_mfma_f32_16x16x32_bf16 v[40:43], v[148:151], v[186:189], 0
	v_mfma_f32_16x16x32_bf16 v[28:31], v[140:143], v[206:209], 0
	v_mfma_f32_16x16x32_bf16 v[24:27], v[148:151], v[206:209], 0
	v_mfma_f32_16x16x32_bf16 v[12:15], v[140:143], v[214:217], 0
	v_mfma_f32_16x16x32_bf16 v[8:11], v[148:151], v[214:217], 0
	v_mfma_f32_16x16x32_bf16 v[60:63], v[144:147], v[182:185], v[60:63]
	v_mfma_f32_16x16x32_bf16 v[56:59], v[158:161], v[182:185], v[56:59]
	v_mfma_f32_16x16x32_bf16 v[44:47], v[144:147], v[202:205], v[44:47]
	v_mfma_f32_16x16x32_bf16 v[40:43], v[158:161], v[202:205], v[40:43]
	v_mfma_f32_16x16x32_bf16 v[28:31], v[144:147], v[210:213], v[28:31]
	v_mfma_f32_16x16x32_bf16 v[24:27], v[158:161], v[210:213], v[24:27]
	v_mfma_f32_16x16x32_bf16 v[12:15], v[144:147], v[218:221], v[12:15]
	v_mfma_f32_16x16x32_bf16 v[8:11], v[158:161], v[218:221], v[8:11]
	s_setprio 0
	s_setprio 1
	v_mfma_f32_16x16x32_bf16 v[52:55], v[162:165], v[178:181], 0
	v_mfma_f32_16x16x32_bf16 v[48:51], v[170:173], v[178:181], 0
	v_mfma_f32_16x16x32_bf16 v[36:39], v[162:165], v[186:189], 0
	v_mfma_f32_16x16x32_bf16 v[32:35], v[170:173], v[186:189], 0
	v_mfma_f32_16x16x32_bf16 v[20:23], v[162:165], v[206:209], 0
	v_mfma_f32_16x16x32_bf16 v[16:19], v[170:173], v[206:209], 0
	v_mfma_f32_16x16x32_bf16 v[4:7], v[162:165], v[214:217], 0
	v_mfma_f32_16x16x32_bf16 v[0:3], v[170:173], v[214:217], 0
	v_mfma_f32_16x16x32_bf16 v[52:55], v[166:169], v[182:185], v[52:55]
	v_mfma_f32_16x16x32_bf16 v[48:51], v[174:177], v[182:185], v[48:51]
	v_mfma_f32_16x16x32_bf16 v[36:39], v[166:169], v[202:205], v[36:39]
	v_mfma_f32_16x16x32_bf16 v[32:35], v[174:177], v[202:205], v[32:35]
	v_mfma_f32_16x16x32_bf16 v[20:23], v[166:169], v[210:213], v[20:23]
	v_mfma_f32_16x16x32_bf16 v[16:19], v[174:177], v[210:213], v[16:19]
	v_mfma_f32_16x16x32_bf16 v[4:7], v[166:169], v[218:221], v[4:7]
	v_mfma_f32_16x16x32_bf16 v[0:3], v[174:177], v[218:221], v[0:3]
	s_setprio 0
	s_barrier
	ds_read_b128 v[140:143], v138
	ds_read_b128 v[144:147], v138 offset:1024
	ds_read_b128 v[148:151], v138 offset:2048
	ds_read_b128 v[158:161], v138 offset:3072
	ds_read_b128 v[162:165], v139
	ds_read_b128 v[166:169], v139 offset:1024
	ds_read_b128 v[170:173], v139 offset:2048
	ds_read_b128 v[174:177], v139 offset:3072
	s_mov_b32 m0, s39
	v_lshl_add_u64 v[222:223], v[192:193], 0, s[10:11]
	ds_read_b128 v[178:181], v134 offset:32768
	ds_read_b128 v[182:185], v134 offset:33792
	ds_read_b128 v[186:189], v135 offset:32768
	ds_read_b128 v[202:205], v135 offset:33792
	ds_read_b128 v[206:209], v136 offset:32768
	ds_read_b128 v[210:213], v136 offset:33792
	ds_read_b128 v[214:217], v137 offset:32768
	ds_read_b128 v[218:221], v137 offset:33792
	global_load_lds_dwordx4 v[222:223], off
	v_lshl_add_u64 v[222:223], v[192:193], 0, s[12:13]
	s_mov_b32 m0, s74
	s_nop 0
	global_load_lds_dwordx4 v[222:223], off
	s_waitcnt vmcnt(8)
	s_waitcnt lgkmcnt(0)
	s_barrier
	s_setprio 1
	s_waitcnt lgkmcnt(0)
	v_mfma_f32_16x16x32_bf16 v[124:127], v[140:143], v[178:181], v[124:127]
	v_mfma_f32_16x16x32_bf16 v[120:123], v[148:151], v[178:181], v[120:123]
	v_mfma_f32_16x16x32_bf16 v[108:111], v[140:143], v[186:189], v[108:111]
	v_mfma_f32_16x16x32_bf16 v[104:107], v[148:151], v[186:189], v[104:107]
	v_mfma_f32_16x16x32_bf16 v[92:95], v[140:143], v[206:209], v[92:95]
	v_mfma_f32_16x16x32_bf16 v[88:91], v[148:151], v[206:209], v[88:91]
	v_mfma_f32_16x16x32_bf16 v[76:79], v[140:143], v[214:217], v[76:79]
	v_mfma_f32_16x16x32_bf16 v[72:75], v[148:151], v[214:217], v[72:75]
	v_mfma_f32_16x16x32_bf16 v[124:127], v[144:147], v[182:185], v[124:127]
	v_mfma_f32_16x16x32_bf16 v[120:123], v[158:161], v[182:185], v[120:123]
	v_mfma_f32_16x16x32_bf16 v[108:111], v[144:147], v[202:205], v[108:111]
	v_mfma_f32_16x16x32_bf16 v[104:107], v[158:161], v[202:205], v[104:107]
	v_mfma_f32_16x16x32_bf16 v[92:95], v[144:147], v[210:213], v[92:95]
	v_mfma_f32_16x16x32_bf16 v[88:91], v[158:161], v[210:213], v[88:91]
	v_mfma_f32_16x16x32_bf16 v[76:79], v[144:147], v[218:221], v[76:79]
	v_mfma_f32_16x16x32_bf16 v[72:75], v[158:161], v[218:221], v[72:75]
	s_setprio 0
	s_setprio 1
	v_mfma_f32_16x16x32_bf16 v[116:119], v[162:165], v[178:181], v[116:119]
	v_mfma_f32_16x16x32_bf16 v[112:115], v[170:173], v[178:181], v[112:115]
	v_mfma_f32_16x16x32_bf16 v[100:103], v[162:165], v[186:189], v[100:103]
	v_mfma_f32_16x16x32_bf16 v[96:99], v[170:173], v[186:189], v[96:99]
	v_mfma_f32_16x16x32_bf16 v[84:87], v[162:165], v[206:209], v[84:87]
	v_mfma_f32_16x16x32_bf16 v[80:83], v[170:173], v[206:209], v[80:83]
	v_mfma_f32_16x16x32_bf16 v[68:71], v[162:165], v[214:217], v[68:71]
	v_mfma_f32_16x16x32_bf16 v[64:67], v[170:173], v[214:217], v[64:67]
	v_mfma_f32_16x16x32_bf16 v[116:119], v[166:169], v[182:185], v[116:119]
	v_mfma_f32_16x16x32_bf16 v[112:115], v[174:177], v[182:185], v[112:115]
	v_mfma_f32_16x16x32_bf16 v[100:103], v[166:169], v[202:205], v[100:103]
	v_mfma_f32_16x16x32_bf16 v[96:99], v[174:177], v[202:205], v[96:99]
	v_mfma_f32_16x16x32_bf16 v[84:87], v[166:169], v[210:213], v[84:87]
	v_mfma_f32_16x16x32_bf16 v[80:83], v[174:177], v[210:213], v[80:83]
	v_mfma_f32_16x16x32_bf16 v[68:71], v[166:169], v[218:221], v[68:71]
	v_mfma_f32_16x16x32_bf16 v[64:67], v[174:177], v[218:221], v[64:67]
	s_setprio 0
	s_barrier
	v_lshl_add_u64 v[222:223], v[190:191], 0, s[48:49]
	s_add_i32 m0, s29, 0x18000
	ds_read_b128 v[178:181], v134 offset:49152
	ds_read_b128 v[182:185], v134 offset:50176
	ds_read_b128 v[186:189], v135 offset:49152
	ds_read_b128 v[202:205], v135 offset:50176
	ds_read_b128 v[206:209], v136 offset:49152
	ds_read_b128 v[210:213], v136 offset:50176
	ds_read_b128 v[214:217], v137 offset:49152
	ds_read_b128 v[218:221], v137 offset:50176
	global_load_lds_dwordx4 v[222:223], off
	v_lshl_add_u64 v[222:223], v[190:191], 0, s[14:15]
	s_add_i32 m0, s29, 0x1a000
	s_nop 0
	global_load_lds_dwordx4 v[222:223], off
	v_lshl_add_u64 v[222:223], v[190:191], 0, s[56:57]
	s_add_i32 m0, s29, 0x1c000
	v_lshl_add_u64 v[190:191], v[190:191], 0, s[62:63]
	global_load_lds_dwordx4 v[222:223], off
	s_add_i32 m0, s29, 0x1e000
	s_nop 0
	global_load_lds_dwordx4 v[190:191], off
	v_lshl_add_u64 v[190:191], v[192:193], 0, s[48:49]
	s_mov_b32 m0, s75
	s_nop 0
	global_load_lds_dwordx4 v[190:191], off
	v_lshl_add_u64 v[190:191], v[192:193], 0, s[14:15]
	s_mov_b32 m0, s76
	s_nop 0
	global_load_lds_dwordx4 v[190:191], off
	s_waitcnt vmcnt(8)
	s_waitcnt lgkmcnt(0)
	s_barrier
	s_setprio 1
	s_waitcnt lgkmcnt(0)
	v_mfma_f32_16x16x32_bf16 v[60:63], v[140:143], v[178:181], v[60:63]
	v_mfma_f32_16x16x32_bf16 v[56:59], v[148:151], v[178:181], v[56:59]
	v_mfma_f32_16x16x32_bf16 v[44:47], v[140:143], v[186:189], v[44:47]
	v_mfma_f32_16x16x32_bf16 v[40:43], v[148:151], v[186:189], v[40:43]
	v_mfma_f32_16x16x32_bf16 v[28:31], v[140:143], v[206:209], v[28:31]
	v_mfma_f32_16x16x32_bf16 v[24:27], v[148:151], v[206:209], v[24:27]
	v_mfma_f32_16x16x32_bf16 v[12:15], v[140:143], v[214:217], v[12:15]
	v_mfma_f32_16x16x32_bf16 v[8:11], v[148:151], v[214:217], v[8:11]
	v_mfma_f32_16x16x32_bf16 v[60:63], v[144:147], v[182:185], v[60:63]
	v_mfma_f32_16x16x32_bf16 v[56:59], v[158:161], v[182:185], v[56:59]
	v_mfma_f32_16x16x32_bf16 v[44:47], v[144:147], v[202:205], v[44:47]
	v_mfma_f32_16x16x32_bf16 v[40:43], v[158:161], v[202:205], v[40:43]
	v_mfma_f32_16x16x32_bf16 v[28:31], v[144:147], v[210:213], v[28:31]
	v_mfma_f32_16x16x32_bf16 v[24:27], v[158:161], v[210:213], v[24:27]
	v_mfma_f32_16x16x32_bf16 v[12:15], v[144:147], v[218:221], v[12:15]
	v_mfma_f32_16x16x32_bf16 v[8:11], v[158:161], v[218:221], v[8:11]
	s_setprio 0
	s_setprio 1
	v_mfma_f32_16x16x32_bf16 v[52:55], v[162:165], v[178:181], v[52:55]
	v_mfma_f32_16x16x32_bf16 v[48:51], v[170:173], v[178:181], v[48:51]
	v_mfma_f32_16x16x32_bf16 v[36:39], v[162:165], v[186:189], v[36:39]
	v_mfma_f32_16x16x32_bf16 v[32:35], v[170:173], v[186:189], v[32:35]
	v_mfma_f32_16x16x32_bf16 v[20:23], v[162:165], v[206:209], v[20:23]
	v_mfma_f32_16x16x32_bf16 v[16:19], v[170:173], v[206:209], v[16:19]
	v_mfma_f32_16x16x32_bf16 v[4:7], v[162:165], v[214:217], v[4:7]
	v_mfma_f32_16x16x32_bf16 v[0:3], v[170:173], v[214:217], v[0:3]
	v_mfma_f32_16x16x32_bf16 v[52:55], v[166:169], v[182:185], v[52:55]
	v_mfma_f32_16x16x32_bf16 v[48:51], v[174:177], v[182:185], v[48:51]
	v_mfma_f32_16x16x32_bf16 v[36:39], v[166:169], v[202:205], v[36:39]
	v_mfma_f32_16x16x32_bf16 v[32:35], v[174:177], v[202:205], v[32:35]
	v_mfma_f32_16x16x32_bf16 v[20:23], v[166:169], v[210:213], v[20:23]
	v_mfma_f32_16x16x32_bf16 v[16:19], v[174:177], v[210:213], v[16:19]
	v_mfma_f32_16x16x32_bf16 v[4:7], v[166:169], v[218:221], v[4:7]
	v_mfma_f32_16x16x32_bf16 v[0:3], v[174:177], v[218:221], v[0:3]
	s_setprio 0
	s_barrier
	s_add_i32 s69, s69, 2
	s_add_u32 s94, s94, 0x100
	s_addc_u32 s95, s95, 0
	s_add_u32 s53, s53, 0x100
	s_addc_u32 s68, s68, 0
	s_cmp_lt_u32 s69, 14

.LBB0_242:
	s_add_u32 s68, s68, 0x20080
	s_addc_u32 s69, s69, 0
	s_add_u32 s53, s70, 0x100
	s_addc_u32 s70, s71, 0
	s_mov_b32 s71, -2
	ds_read_b128 v[74:77], v68
	ds_read_b128 v[78:81], v68 offset:1024
	ds_read_b128 v[82:85], v68 offset:2048
	ds_read_b128 v[86:89], v68 offset:3072
	ds_read_b128 v[90:93], v69
	ds_read_b128 v[94:97], v69 offset:1024
	ds_read_b128 v[98:101], v69 offset:2048
	ds_read_b128 v[102:105], v69 offset:3072
	s_add_u32 s83, s68, 0xfffe0080
	s_addc_u32 s85, s69, -1
	s_cmp_eq_u32 s71, 12
	s_cselect_b32 s93, s55, s85
	s_cselect_b32 s92, s54, s83
	s_cselect_b32 s95, s89, s70
	s_cselect_b32 s94, s88, s53
	v_lshl_add_u64 v[122:123], s[68:69], 0, v[66:67]
	s_add_i32 m0, s29, 0xc000
	ds_read_b128 v[106:109], v70
	ds_read_b128 v[110:113], v70 offset:1024
	ds_read_b128 v[114:117], v71
	ds_read_b128 v[118:121], v71 offset:1024
	global_load_lds_dwordx4 v[122:123], off
	v_lshl_add_u64 v[122:123], v[122:123], 0, s[8:9]
	s_add_i32 m0, s29, 0xe000
	s_nop 0
	global_load_lds_dwordx4 v[122:123], off
	s_waitcnt vmcnt(8)
	s_waitcnt lgkmcnt(0)
	s_barrier
	s_setprio 1
	s_waitcnt lgkmcnt(0)
	v_mfma_f32_16x16x32_bf16 v[60:63], v[74:77], v[106:109], 0
	v_mfma_f32_16x16x32_bf16 v[56:59], v[82:85], v[106:109], 0
	v_mfma_f32_16x16x32_bf16 v[44:47], v[74:77], v[114:117], 0
	v_mfma_f32_16x16x32_bf16 v[40:43], v[82:85], v[114:117], 0
	v_mfma_f32_16x16x32_bf16 v[60:63], v[78:81], v[110:113], v[60:63]
	v_mfma_f32_16x16x32_bf16 v[56:59], v[86:89], v[110:113], v[56:59]
	v_mfma_f32_16x16x32_bf16 v[44:47], v[78:81], v[118:121], v[44:47]
	v_mfma_f32_16x16x32_bf16 v[40:43], v[86:89], v[118:121], v[40:43]
	s_setprio 0
	s_setprio 1
	v_mfma_f32_16x16x32_bf16 v[52:55], v[90:93], v[106:109], 0
	v_mfma_f32_16x16x32_bf16 v[48:51], v[98:101], v[106:109], 0
	v_mfma_f32_16x16x32_bf16 v[36:39], v[90:93], v[114:117], 0
	v_mfma_f32_16x16x32_bf16 v[32:35], v[98:101], v[114:117], 0
	v_mfma_f32_16x16x32_bf16 v[52:55], v[94:97], v[110:113], v[52:55]
	v_mfma_f32_16x16x32_bf16 v[48:51], v[102:105], v[110:113], v[48:51]
	v_mfma_f32_16x16x32_bf16 v[36:39], v[94:97], v[118:121], v[36:39]
	v_mfma_f32_16x16x32_bf16 v[32:35], v[102:105], v[118:121], v[32:35]
	s_setprio 0
	s_barrier
	s_mov_b32 m0, s34
	v_lshl_add_u64 v[122:123], s[94:95], 0, v[64:65]
	ds_read_b128 v[106:109], v70 offset:16384
	ds_read_b128 v[110:113], v70 offset:17408
	ds_read_b128 v[114:117], v71 offset:16384
	ds_read_b128 v[118:121], v71 offset:17408
	global_load_lds_dwordx4 v[122:123], off
	v_lshl_add_u64 v[124:125], v[122:123], 0, s[8:9]
	s_mov_b32 m0, s35
	s_nop 0
	global_load_lds_dwordx4 v[124:125], off
	v_lshl_add_u64 v[124:125], v[122:123], 0, s[10:11]
	s_mov_b32 m0, s36
	s_nop 0
	global_load_lds_dwordx4 v[124:125], off
	v_lshl_add_u64 v[124:125], v[122:123], 0, s[12:13]
	s_mov_b32 m0, s37
	s_nop 0
	global_load_lds_dwordx4 v[124:125], off
	v_lshl_add_u64 v[124:125], s[92:93], 0, v[64:65]
	s_mov_b32 m0, s29
	v_lshl_add_u64 v[126:127], v[124:125], 0, s[8:9]
	global_load_lds_dwordx4 v[124:125], off
	s_mov_b32 m0, s38
	s_nop 0
	global_load_lds_dwordx4 v[126:127], off
	s_waitcnt vmcnt(8)
	s_waitcnt lgkmcnt(0)
	s_barrier
	s_setprio 1
	s_waitcnt lgkmcnt(0)
	v_mfma_f32_16x16x32_bf16 v[28:31], v[74:77], v[106:109], 0
	v_mfma_f32_16x16x32_bf16 v[24:27], v[82:85], v[106:109], 0
	v_mfma_f32_16x16x32_bf16 v[12:15], v[74:77], v[114:117], 0
	v_mfma_f32_16x16x32_bf16 v[8:11], v[82:85], v[114:117], 0
	v_mfma_f32_16x16x32_bf16 v[28:31], v[78:81], v[110:113], v[28:31]
	v_mfma_f32_16x16x32_bf16 v[24:27], v[86:89], v[110:113], v[24:27]
	v_mfma_f32_16x16x32_bf16 v[12:15], v[78:81], v[118:121], v[12:15]
	v_mfma_f32_16x16x32_bf16 v[8:11], v[86:89], v[118:121], v[8:11]
	s_setprio 0
	s_setprio 1
	v_mfma_f32_16x16x32_bf16 v[20:23], v[90:93], v[106:109], 0
	v_mfma_f32_16x16x32_bf16 v[16:19], v[98:101], v[106:109], 0
	v_mfma_f32_16x16x32_bf16 v[4:7], v[90:93], v[114:117], 0
	v_mfma_f32_16x16x32_bf16 v[0:3], v[98:101], v[114:117], 0
	v_mfma_f32_16x16x32_bf16 v[20:23], v[94:97], v[110:113], v[20:23]
	v_mfma_f32_16x16x32_bf16 v[16:19], v[102:105], v[110:113], v[16:19]
	v_mfma_f32_16x16x32_bf16 v[4:7], v[94:97], v[118:121], v[4:7]
	v_mfma_f32_16x16x32_bf16 v[0:3], v[102:105], v[118:121], v[0:3]
	s_setprio 0
	s_barrier
	ds_read_b128 v[74:77], v72
	ds_read_b128 v[78:81], v72 offset:1024
	ds_read_b128 v[82:85], v72 offset:2048
	ds_read_b128 v[86:89], v72 offset:3072
	ds_read_b128 v[90:93], v73
	ds_read_b128 v[94:97], v73 offset:1024
	ds_read_b128 v[98:101], v73 offset:2048
	ds_read_b128 v[102:105], v73 offset:3072
	s_mov_b32 m0, s39
	ds_read_b128 v[106:109], v70 offset:32768
	ds_read_b128 v[110:113], v70 offset:33792
	ds_read_b128 v[114:117], v71 offset:32768
	ds_read_b128 v[118:121], v71 offset:33792
	global_load_lds_dwordx4 v[126:127], off
	v_lshl_add_u64 v[126:127], v[124:125], 0, s[10:11]
	s_mov_b32 m0, s74
	s_nop 0
	global_load_lds_dwordx4 v[126:127], off
	s_waitcnt vmcnt(8)
	s_waitcnt lgkmcnt(0)
	s_barrier
	s_setprio 1
	s_waitcnt lgkmcnt(0)
	v_mfma_f32_16x16x32_bf16 v[60:63], v[74:77], v[106:109], v[60:63]
	v_mfma_f32_16x16x32_bf16 v[56:59], v[82:85], v[106:109], v[56:59]
	v_mfma_f32_16x16x32_bf16 v[44:47], v[74:77], v[114:117], v[44:47]
	v_mfma_f32_16x16x32_bf16 v[40:43], v[82:85], v[114:117], v[40:43]
	v_mfma_f32_16x16x32_bf16 v[60:63], v[78:81], v[110:113], v[60:63]
	v_mfma_f32_16x16x32_bf16 v[56:59], v[86:89], v[110:113], v[56:59]
	v_mfma_f32_16x16x32_bf16 v[44:47], v[78:81], v[118:121], v[44:47]
	v_mfma_f32_16x16x32_bf16 v[40:43], v[86:89], v[118:121], v[40:43]
	s_setprio 0
	s_setprio 1
	v_mfma_f32_16x16x32_bf16 v[52:55], v[90:93], v[106:109], v[52:55]
	v_mfma_f32_16x16x32_bf16 v[48:51], v[98:101], v[106:109], v[48:51]
	v_mfma_f32_16x16x32_bf16 v[36:39], v[90:93], v[114:117], v[36:39]
	v_mfma_f32_16x16x32_bf16 v[32:35], v[98:101], v[114:117], v[32:35]
	v_mfma_f32_16x16x32_bf16 v[52:55], v[94:97], v[110:113], v[52:55]
	v_mfma_f32_16x16x32_bf16 v[48:51], v[102:105], v[110:113], v[48:51]
	v_mfma_f32_16x16x32_bf16 v[36:39], v[94:97], v[118:121], v[36:39]
	v_mfma_f32_16x16x32_bf16 v[32:35], v[102:105], v[118:121], v[32:35]
	s_setprio 0
	s_barrier
	v_lshl_add_u64 v[126:127], v[122:123], 0, s[48:49]
	s_add_i32 m0, s29, 0x18000
	ds_read_b128 v[106:109], v70 offset:49152
	ds_read_b128 v[110:113], v70 offset:50176
	ds_read_b128 v[114:117], v71 offset:49152
	ds_read_b128 v[118:121], v71 offset:50176
	global_load_lds_dwordx4 v[126:127], off
	v_lshl_add_u64 v[126:127], v[122:123], 0, s[14:15]
	s_add_i32 m0, s29, 0x1a000
	s_nop 0
	global_load_lds_dwordx4 v[126:127], off
	v_lshl_add_u64 v[126:127], v[122:123], 0, s[56:57]
	s_add_i32 m0, s29, 0x1c000
	v_lshl_add_u64 v[122:123], v[122:123], 0, s[62:63]
	global_load_lds_dwordx4 v[126:127], off
	s_add_i32 m0, s29, 0x1e000
	s_nop 0
	global_load_lds_dwordx4 v[122:123], off
	v_lshl_add_u64 v[122:123], v[124:125], 0, s[48:49]
	s_mov_b32 m0, s75
	s_nop 0
	global_load_lds_dwordx4 v[122:123], off
	v_lshl_add_u64 v[122:123], v[124:125], 0, s[14:15]
	s_mov_b32 m0, s76
	s_nop 0
	global_load_lds_dwordx4 v[122:123], off
	s_waitcnt vmcnt(8)
	s_waitcnt lgkmcnt(0)
	s_barrier
	s_setprio 1
	s_waitcnt lgkmcnt(0)
	v_mfma_f32_16x16x32_bf16 v[28:31], v[74:77], v[106:109], v[28:31]
	v_mfma_f32_16x16x32_bf16 v[24:27], v[82:85], v[106:109], v[24:27]
	v_mfma_f32_16x16x32_bf16 v[12:15], v[74:77], v[114:117], v[12:15]
	v_mfma_f32_16x16x32_bf16 v[8:11], v[82:85], v[114:117], v[8:11]
	v_mfma_f32_16x16x32_bf16 v[28:31], v[78:81], v[110:113], v[28:31]
	v_mfma_f32_16x16x32_bf16 v[24:27], v[86:89], v[110:113], v[24:27]
	v_mfma_f32_16x16x32_bf16 v[12:15], v[78:81], v[118:121], v[12:15]
	v_mfma_f32_16x16x32_bf16 v[8:11], v[86:89], v[118:121], v[8:11]
	s_setprio 0
	s_setprio 1
	v_mfma_f32_16x16x32_bf16 v[20:23], v[90:93], v[106:109], v[20:23]
	v_mfma_f32_16x16x32_bf16 v[16:19], v[98:101], v[106:109], v[16:19]
	v_mfma_f32_16x16x32_bf16 v[4:7], v[90:93], v[114:117], v[4:7]
	v_mfma_f32_16x16x32_bf16 v[0:3], v[98:101], v[114:117], v[0:3]
	v_mfma_f32_16x16x32_bf16 v[20:23], v[94:97], v[110:113], v[20:23]
	v_mfma_f32_16x16x32_bf16 v[16:19], v[102:105], v[110:113], v[16:19]
	v_mfma_f32_16x16x32_bf16 v[4:7], v[94:97], v[118:121], v[4:7]
	v_mfma_f32_16x16x32_bf16 v[0:3], v[102:105], v[118:121], v[0:3]
	s_setprio 0
	s_barrier
	s_add_i32 s71, s71, 2
	s_add_u32 s68, s68, 0x100
	s_addc_u32 s69, s69, 0
	s_add_u32 s53, s53, 0x100
	s_addc_u32 s70, s70, 0
	s_cmp_lt_u32 s71, 14

.LBB0_262:
	s_add_u32 s92, s68, 0x40080
	s_addc_u32 s93, s69, 0
	s_add_u32 s51, s70, 0x100
	s_addc_u32 s68, s71, 0
	s_mov_b32 s69, -2
	ds_read_b128 v[140:143], v132
	ds_read_b128 v[144:147], v132 offset:1024
	ds_read_b128 v[148:151], v132 offset:2048
	ds_read_b128 v[158:161], v132 offset:3072
	ds_read_b128 v[162:165], v133
	ds_read_b128 v[166:169], v133 offset:1024
	ds_read_b128 v[170:173], v133 offset:2048
	ds_read_b128 v[174:177], v133 offset:3072
	s_add_u32 s70, s92, 0xfffc0080
	s_addc_u32 s71, s93, -1
	s_cmp_eq_u32 s69, 12
	s_cselect_b32 s71, s53, s71
	s_cselect_b32 s70, s52, s70
	s_cselect_b32 s79, s55, s68
	s_cselect_b32 s78, s54, s51
	v_lshl_add_u64 v[190:191], s[92:93], 0, v[130:131]
	s_add_i32 m0, s1, 0xc000
	ds_read_b128 v[178:181], v134
	ds_read_b128 v[182:185], v134 offset:1024
	ds_read_b128 v[186:189], v135
	ds_read_b128 v[202:205], v135 offset:1024
	ds_read_b128 v[206:209], v136
	ds_read_b128 v[210:213], v136 offset:1024
	ds_read_b128 v[214:217], v137
	ds_read_b128 v[218:221], v137 offset:1024
	global_load_lds_dwordx4 v[190:191], off
	v_lshl_add_u64 v[190:191], v[190:191], 0, s[8:9]
	s_add_i32 m0, s1, 0xe000
	s_nop 0
	global_load_lds_dwordx4 v[190:191], off
	s_waitcnt vmcnt(8)
	s_waitcnt lgkmcnt(0)
	s_barrier
	s_setprio 1
	s_waitcnt lgkmcnt(0)
	v_mfma_f32_16x16x32_bf16 v[124:127], v[140:143], v[178:181], 0
	v_mfma_f32_16x16x32_bf16 v[120:123], v[148:151], v[178:181], 0
	v_mfma_f32_16x16x32_bf16 v[108:111], v[140:143], v[186:189], 0
	v_mfma_f32_16x16x32_bf16 v[104:107], v[148:151], v[186:189], 0
	v_mfma_f32_16x16x32_bf16 v[92:95], v[140:143], v[206:209], 0
	v_mfma_f32_16x16x32_bf16 v[88:91], v[148:151], v[206:209], 0
	v_mfma_f32_16x16x32_bf16 v[76:79], v[140:143], v[214:217], 0
	v_mfma_f32_16x16x32_bf16 v[72:75], v[148:151], v[214:217], 0
	v_mfma_f32_16x16x32_bf16 v[124:127], v[144:147], v[182:185], v[124:127]
	v_mfma_f32_16x16x32_bf16 v[120:123], v[158:161], v[182:185], v[120:123]
	v_mfma_f32_16x16x32_bf16 v[108:111], v[144:147], v[202:205], v[108:111]
	v_mfma_f32_16x16x32_bf16 v[104:107], v[158:161], v[202:205], v[104:107]
	v_mfma_f32_16x16x32_bf16 v[92:95], v[144:147], v[210:213], v[92:95]
	v_mfma_f32_16x16x32_bf16 v[88:91], v[158:161], v[210:213], v[88:91]
	v_mfma_f32_16x16x32_bf16 v[76:79], v[144:147], v[218:221], v[76:79]
	v_mfma_f32_16x16x32_bf16 v[72:75], v[158:161], v[218:221], v[72:75]
	s_setprio 0
	s_setprio 1
	v_mfma_f32_16x16x32_bf16 v[116:119], v[162:165], v[178:181], 0
	v_mfma_f32_16x16x32_bf16 v[112:115], v[170:173], v[178:181], 0
	v_mfma_f32_16x16x32_bf16 v[100:103], v[162:165], v[186:189], 0
	v_mfma_f32_16x16x32_bf16 v[96:99], v[170:173], v[186:189], 0
	v_mfma_f32_16x16x32_bf16 v[84:87], v[162:165], v[206:209], 0
	v_mfma_f32_16x16x32_bf16 v[80:83], v[170:173], v[206:209], 0
	v_mfma_f32_16x16x32_bf16 v[68:71], v[162:165], v[214:217], 0
	v_mfma_f32_16x16x32_bf16 v[64:67], v[170:173], v[214:217], 0
	v_mfma_f32_16x16x32_bf16 v[116:119], v[166:169], v[182:185], v[116:119]
	v_mfma_f32_16x16x32_bf16 v[112:115], v[174:177], v[182:185], v[112:115]
	v_mfma_f32_16x16x32_bf16 v[100:103], v[166:169], v[202:205], v[100:103]
	v_mfma_f32_16x16x32_bf16 v[96:99], v[174:177], v[202:205], v[96:99]
	v_mfma_f32_16x16x32_bf16 v[84:87], v[166:169], v[210:213], v[84:87]
	v_mfma_f32_16x16x32_bf16 v[80:83], v[174:177], v[210:213], v[80:83]
	v_mfma_f32_16x16x32_bf16 v[68:71], v[166:169], v[218:221], v[68:71]
	v_mfma_f32_16x16x32_bf16 v[64:67], v[174:177], v[218:221], v[64:67]
	s_setprio 0
	s_barrier
	s_mov_b32 m0, s28
	v_lshl_add_u64 v[190:191], s[78:79], 0, v[128:129]
	ds_read_b128 v[178:181], v134 offset:16384
	ds_read_b128 v[182:185], v134 offset:17408
	ds_read_b128 v[186:189], v135 offset:16384
	ds_read_b128 v[202:205], v135 offset:17408
	ds_read_b128 v[206:209], v136 offset:16384
	ds_read_b128 v[210:213], v136 offset:17408
	ds_read_b128 v[214:217], v137 offset:16384
	ds_read_b128 v[218:221], v137 offset:17408
	global_load_lds_dwordx4 v[190:191], off
	v_lshl_add_u64 v[192:193], v[190:191], 0, s[8:9]
	s_mov_b32 m0, s29
	s_nop 0
	global_load_lds_dwordx4 v[192:193], off
	v_lshl_add_u64 v[192:193], v[190:191], 0, s[10:11]
	s_mov_b32 m0, s34
	s_nop 0
	global_load_lds_dwordx4 v[192:193], off
	v_lshl_add_u64 v[192:193], v[190:191], 0, s[12:13]
	s_mov_b32 m0, s35
	s_nop 0
	global_load_lds_dwordx4 v[192:193], off
	v_lshl_add_u64 v[192:193], s[70:71], 0, v[128:129]
	s_mov_b32 m0, s1
	v_lshl_add_u64 v[222:223], v[192:193], 0, s[8:9]
	global_load_lds_dwordx4 v[192:193], off
	s_mov_b32 m0, s36
	s_nop 0
	global_load_lds_dwordx4 v[222:223], off
	s_waitcnt vmcnt(8)
	s_waitcnt lgkmcnt(0)
	s_barrier
	s_setprio 1
	s_waitcnt lgkmcnt(0)
	v_mfma_f32_16x16x32_bf16 v[60:63], v[140:143], v[178:181], 0
	v_mfma_f32_16x16x32_bf16 v[56:59], v[148:151], v[178:181], 0
	v_mfma_f32_16x16x32_bf16 v[44:47], v[140:143], v[186:189], 0
	v_mfma_f32_16x16x32_bf16 v[40:43], v[148:151], v[186:189], 0
	v_mfma_f32_16x16x32_bf16 v[28:31], v[140:143], v[206:209], 0
	v_mfma_f32_16x16x32_bf16 v[24:27], v[148:151], v[206:209], 0
	v_mfma_f32_16x16x32_bf16 v[12:15], v[140:143], v[214:217], 0
	v_mfma_f32_16x16x32_bf16 v[8:11], v[148:151], v[214:217], 0
	v_mfma_f32_16x16x32_bf16 v[60:63], v[144:147], v[182:185], v[60:63]
	v_mfma_f32_16x16x32_bf16 v[56:59], v[158:161], v[182:185], v[56:59]
	v_mfma_f32_16x16x32_bf16 v[44:47], v[144:147], v[202:205], v[44:47]
	v_mfma_f32_16x16x32_bf16 v[40:43], v[158:161], v[202:205], v[40:43]
	v_mfma_f32_16x16x32_bf16 v[28:31], v[144:147], v[210:213], v[28:31]
	v_mfma_f32_16x16x32_bf16 v[24:27], v[158:161], v[210:213], v[24:27]
	v_mfma_f32_16x16x32_bf16 v[12:15], v[144:147], v[218:221], v[12:15]
	v_mfma_f32_16x16x32_bf16 v[8:11], v[158:161], v[218:221], v[8:11]
	s_setprio 0
	s_setprio 1
	v_mfma_f32_16x16x32_bf16 v[52:55], v[162:165], v[178:181], 0
	v_mfma_f32_16x16x32_bf16 v[48:51], v[170:173], v[178:181], 0
	v_mfma_f32_16x16x32_bf16 v[36:39], v[162:165], v[186:189], 0
	v_mfma_f32_16x16x32_bf16 v[32:35], v[170:173], v[186:189], 0
	v_mfma_f32_16x16x32_bf16 v[20:23], v[162:165], v[206:209], 0
	v_mfma_f32_16x16x32_bf16 v[16:19], v[170:173], v[206:209], 0
	v_mfma_f32_16x16x32_bf16 v[4:7], v[162:165], v[214:217], 0
	v_mfma_f32_16x16x32_bf16 v[0:3], v[170:173], v[214:217], 0
	v_mfma_f32_16x16x32_bf16 v[52:55], v[166:169], v[182:185], v[52:55]
	v_mfma_f32_16x16x32_bf16 v[48:51], v[174:177], v[182:185], v[48:51]
	v_mfma_f32_16x16x32_bf16 v[36:39], v[166:169], v[202:205], v[36:39]
	v_mfma_f32_16x16x32_bf16 v[32:35], v[174:177], v[202:205], v[32:35]
	v_mfma_f32_16x16x32_bf16 v[20:23], v[166:169], v[210:213], v[20:23]
	v_mfma_f32_16x16x32_bf16 v[16:19], v[174:177], v[210:213], v[16:19]
	v_mfma_f32_16x16x32_bf16 v[4:7], v[166:169], v[218:221], v[4:7]
	v_mfma_f32_16x16x32_bf16 v[0:3], v[174:177], v[218:221], v[0:3]
	s_setprio 0
	s_barrier
	ds_read_b128 v[140:143], v138
	ds_read_b128 v[144:147], v138 offset:1024
	ds_read_b128 v[148:151], v138 offset:2048
	ds_read_b128 v[158:161], v138 offset:3072
	ds_read_b128 v[162:165], v139
	ds_read_b128 v[166:169], v139 offset:1024
	ds_read_b128 v[170:173], v139 offset:2048
	ds_read_b128 v[174:177], v139 offset:3072
	s_mov_b32 m0, s37
	v_lshl_add_u64 v[222:223], v[192:193], 0, s[10:11]
	ds_read_b128 v[178:181], v134 offset:32768
	ds_read_b128 v[182:185], v134 offset:33792
	ds_read_b128 v[186:189], v135 offset:32768
	ds_read_b128 v[202:205], v135 offset:33792
	ds_read_b128 v[206:209], v136 offset:32768
	ds_read_b128 v[210:213], v136 offset:33792
	ds_read_b128 v[214:217], v137 offset:32768
	ds_read_b128 v[218:221], v137 offset:33792
	global_load_lds_dwordx4 v[222:223], off
	v_lshl_add_u64 v[222:223], v[192:193], 0, s[12:13]
	s_mov_b32 m0, s38
	s_nop 0
	global_load_lds_dwordx4 v[222:223], off
	s_waitcnt vmcnt(8)
	s_waitcnt lgkmcnt(0)
	s_barrier
	s_setprio 1
	s_waitcnt lgkmcnt(0)
	v_mfma_f32_16x16x32_bf16 v[124:127], v[140:143], v[178:181], v[124:127]
	v_mfma_f32_16x16x32_bf16 v[120:123], v[148:151], v[178:181], v[120:123]
	v_mfma_f32_16x16x32_bf16 v[108:111], v[140:143], v[186:189], v[108:111]
	v_mfma_f32_16x16x32_bf16 v[104:107], v[148:151], v[186:189], v[104:107]
	v_mfma_f32_16x16x32_bf16 v[92:95], v[140:143], v[206:209], v[92:95]
	v_mfma_f32_16x16x32_bf16 v[88:91], v[148:151], v[206:209], v[88:91]
	v_mfma_f32_16x16x32_bf16 v[76:79], v[140:143], v[214:217], v[76:79]
	v_mfma_f32_16x16x32_bf16 v[72:75], v[148:151], v[214:217], v[72:75]
	v_mfma_f32_16x16x32_bf16 v[124:127], v[144:147], v[182:185], v[124:127]
	v_mfma_f32_16x16x32_bf16 v[120:123], v[158:161], v[182:185], v[120:123]
	v_mfma_f32_16x16x32_bf16 v[108:111], v[144:147], v[202:205], v[108:111]
	v_mfma_f32_16x16x32_bf16 v[104:107], v[158:161], v[202:205], v[104:107]
	v_mfma_f32_16x16x32_bf16 v[92:95], v[144:147], v[210:213], v[92:95]
	v_mfma_f32_16x16x32_bf16 v[88:91], v[158:161], v[210:213], v[88:91]
	v_mfma_f32_16x16x32_bf16 v[76:79], v[144:147], v[218:221], v[76:79]
	v_mfma_f32_16x16x32_bf16 v[72:75], v[158:161], v[218:221], v[72:75]
	s_setprio 0
	s_setprio 1
	v_mfma_f32_16x16x32_bf16 v[116:119], v[162:165], v[178:181], v[116:119]
	v_mfma_f32_16x16x32_bf16 v[112:115], v[170:173], v[178:181], v[112:115]
	v_mfma_f32_16x16x32_bf16 v[100:103], v[162:165], v[186:189], v[100:103]
	v_mfma_f32_16x16x32_bf16 v[96:99], v[170:173], v[186:189], v[96:99]
	v_mfma_f32_16x16x32_bf16 v[84:87], v[162:165], v[206:209], v[84:87]
	v_mfma_f32_16x16x32_bf16 v[80:83], v[170:173], v[206:209], v[80:83]
	v_mfma_f32_16x16x32_bf16 v[68:71], v[162:165], v[214:217], v[68:71]
	v_mfma_f32_16x16x32_bf16 v[64:67], v[170:173], v[214:217], v[64:67]
	v_mfma_f32_16x16x32_bf16 v[116:119], v[166:169], v[182:185], v[116:119]
	v_mfma_f32_16x16x32_bf16 v[112:115], v[174:177], v[182:185], v[112:115]
	v_mfma_f32_16x16x32_bf16 v[100:103], v[166:169], v[202:205], v[100:103]
	v_mfma_f32_16x16x32_bf16 v[96:99], v[174:177], v[202:205], v[96:99]
	v_mfma_f32_16x16x32_bf16 v[84:87], v[166:169], v[210:213], v[84:87]
	v_mfma_f32_16x16x32_bf16 v[80:83], v[174:177], v[210:213], v[80:83]
	v_mfma_f32_16x16x32_bf16 v[68:71], v[166:169], v[218:221], v[68:71]
	v_mfma_f32_16x16x32_bf16 v[64:67], v[174:177], v[218:221], v[64:67]
	s_setprio 0
	s_barrier
	v_lshl_add_u64 v[222:223], v[190:191], 0, s[48:49]
	s_add_i32 m0, s1, 0x18000
	ds_read_b128 v[178:181], v134 offset:49152
	ds_read_b128 v[182:185], v134 offset:50176
	ds_read_b128 v[186:189], v135 offset:49152
	ds_read_b128 v[202:205], v135 offset:50176
	ds_read_b128 v[206:209], v136 offset:49152
	ds_read_b128 v[210:213], v136 offset:50176
	ds_read_b128 v[214:217], v137 offset:49152
	ds_read_b128 v[218:221], v137 offset:50176
	global_load_lds_dwordx4 v[222:223], off
	v_lshl_add_u64 v[222:223], v[190:191], 0, s[14:15]
	s_add_i32 m0, s1, 0x1a000
	s_nop 0
	global_load_lds_dwordx4 v[222:223], off
	v_lshl_add_u64 v[222:223], v[190:191], 0, s[56:57]
	s_add_i32 m0, s1, 0x1c000
	v_lshl_add_u64 v[190:191], v[190:191], 0, s[62:63]
	global_load_lds_dwordx4 v[222:223], off
	s_add_i32 m0, s1, 0x1e000
	s_nop 0
	global_load_lds_dwordx4 v[190:191], off
	v_lshl_add_u64 v[190:191], v[192:193], 0, s[48:49]
	s_mov_b32 m0, s39
	s_nop 0
	global_load_lds_dwordx4 v[190:191], off
	v_lshl_add_u64 v[190:191], v[192:193], 0, s[14:15]
	s_mov_b32 m0, s74
	s_nop 0
	global_load_lds_dwordx4 v[190:191], off
	s_waitcnt vmcnt(8)
	s_waitcnt lgkmcnt(0)
	s_barrier
	s_setprio 1
	s_waitcnt lgkmcnt(0)
	v_mfma_f32_16x16x32_bf16 v[60:63], v[140:143], v[178:181], v[60:63]
	v_mfma_f32_16x16x32_bf16 v[56:59], v[148:151], v[178:181], v[56:59]
	v_mfma_f32_16x16x32_bf16 v[44:47], v[140:143], v[186:189], v[44:47]
	v_mfma_f32_16x16x32_bf16 v[40:43], v[148:151], v[186:189], v[40:43]
	v_mfma_f32_16x16x32_bf16 v[28:31], v[140:143], v[206:209], v[28:31]
	v_mfma_f32_16x16x32_bf16 v[24:27], v[148:151], v[206:209], v[24:27]
	v_mfma_f32_16x16x32_bf16 v[12:15], v[140:143], v[214:217], v[12:15]
	v_mfma_f32_16x16x32_bf16 v[8:11], v[148:151], v[214:217], v[8:11]
	v_mfma_f32_16x16x32_bf16 v[60:63], v[144:147], v[182:185], v[60:63]
	v_mfma_f32_16x16x32_bf16 v[56:59], v[158:161], v[182:185], v[56:59]
	v_mfma_f32_16x16x32_bf16 v[44:47], v[144:147], v[202:205], v[44:47]
	v_mfma_f32_16x16x32_bf16 v[40:43], v[158:161], v[202:205], v[40:43]
	v_mfma_f32_16x16x32_bf16 v[28:31], v[144:147], v[210:213], v[28:31]
	v_mfma_f32_16x16x32_bf16 v[24:27], v[158:161], v[210:213], v[24:27]
	v_mfma_f32_16x16x32_bf16 v[12:15], v[144:147], v[218:221], v[12:15]
	v_mfma_f32_16x16x32_bf16 v[8:11], v[158:161], v[218:221], v[8:11]
	s_setprio 0
	s_setprio 1
	v_mfma_f32_16x16x32_bf16 v[52:55], v[162:165], v[178:181], v[52:55]
	v_mfma_f32_16x16x32_bf16 v[48:51], v[170:173], v[178:181], v[48:51]
	v_mfma_f32_16x16x32_bf16 v[36:39], v[162:165], v[186:189], v[36:39]
	v_mfma_f32_16x16x32_bf16 v[32:35], v[170:173], v[186:189], v[32:35]
	v_mfma_f32_16x16x32_bf16 v[20:23], v[162:165], v[206:209], v[20:23]
	v_mfma_f32_16x16x32_bf16 v[16:19], v[170:173], v[206:209], v[16:19]
	v_mfma_f32_16x16x32_bf16 v[4:7], v[162:165], v[214:217], v[4:7]
	v_mfma_f32_16x16x32_bf16 v[0:3], v[170:173], v[214:217], v[0:3]
	v_mfma_f32_16x16x32_bf16 v[52:55], v[166:169], v[182:185], v[52:55]
	v_mfma_f32_16x16x32_bf16 v[48:51], v[174:177], v[182:185], v[48:51]
	v_mfma_f32_16x16x32_bf16 v[36:39], v[166:169], v[202:205], v[36:39]
	v_mfma_f32_16x16x32_bf16 v[32:35], v[174:177], v[202:205], v[32:35]
	v_mfma_f32_16x16x32_bf16 v[20:23], v[166:169], v[210:213], v[20:23]
	v_mfma_f32_16x16x32_bf16 v[16:19], v[174:177], v[210:213], v[16:19]
	v_mfma_f32_16x16x32_bf16 v[4:7], v[166:169], v[218:221], v[4:7]
	v_mfma_f32_16x16x32_bf16 v[0:3], v[174:177], v[218:221], v[0:3]
	s_setprio 0
	s_barrier
	s_add_i32 s69, s69, 2
	s_add_u32 s92, s92, 0x100
	s_addc_u32 s93, s93, 0
	s_add_u32 s51, s51, 0x100
	s_addc_u32 s68, s68, 0
	s_cmp_lt_u32 s69, 14

.LBB0_300:
	s_add_u32 s94, s68, 0x40080
	s_addc_u32 s95, s69, 0
	s_add_u32 s53, s70, 0x100
	s_addc_u32 s68, s71, 0
	s_mov_b32 s69, -2
	ds_read_b128 v[142:145], v134
	ds_read_b128 v[146:149], v134 offset:1024
	ds_read_b128 v[158:161], v134 offset:2048
	ds_read_b128 v[162:165], v134 offset:3072
	ds_read_b128 v[166:169], v135
	ds_read_b128 v[170:173], v135 offset:1024
	ds_read_b128 v[174:177], v135 offset:2048
	ds_read_b128 v[178:181], v135 offset:3072
	s_add_u32 s70, s94, 0xfffc0080
	s_addc_u32 s71, s95, -1
	s_cmp_eq_u32 s69, 12
	s_cselect_b32 s71, s55, s71
	s_cselect_b32 s70, s54, s70
	s_cselect_b32 vcc_hi, s89, s68
	s_cselect_b32 vcc_lo, s88, s53
	v_lshl_add_u64 v[132:133], s[94:95], 0, v[130:131]
	s_add_i32 m0, s29, 0xc000
	ds_read_b128 v[182:185], v136
	ds_read_b128 v[186:189], v136 offset:1024
	ds_read_b128 v[202:205], v137
	ds_read_b128 v[206:209], v137 offset:1024
	ds_read_b128 v[210:213], v138
	ds_read_b128 v[214:217], v138 offset:1024
	ds_read_b128 v[218:221], v139
	ds_read_b128 v[222:225], v139 offset:1024
	global_load_lds_dwordx4 v[132:133], off
	v_lshl_add_u64 v[132:133], v[132:133], 0, s[8:9]
	s_add_i32 m0, s29, 0xe000
	s_nop 0
	global_load_lds_dwordx4 v[132:133], off
	s_waitcnt vmcnt(8)
	s_waitcnt lgkmcnt(0)
	s_barrier
	s_setprio 1
	s_waitcnt lgkmcnt(0)
	v_mfma_f32_16x16x32_bf16 v[120:123], v[142:145], v[182:185], 0
	v_mfma_f32_16x16x32_bf16 v[116:119], v[158:161], v[182:185], 0
	v_mfma_f32_16x16x32_bf16 v[104:107], v[142:145], v[202:205], 0
	v_mfma_f32_16x16x32_bf16 v[100:103], v[158:161], v[202:205], 0
	v_mfma_f32_16x16x32_bf16 v[88:91], v[142:145], v[210:213], 0
	v_mfma_f32_16x16x32_bf16 v[84:87], v[158:161], v[210:213], 0
	v_mfma_f32_16x16x32_bf16 v[72:75], v[142:145], v[218:221], 0
	v_mfma_f32_16x16x32_bf16 v[68:71], v[158:161], v[218:221], 0
	v_mfma_f32_16x16x32_bf16 v[120:123], v[146:149], v[186:189], v[120:123]
	v_mfma_f32_16x16x32_bf16 v[116:119], v[162:165], v[186:189], v[116:119]
	v_mfma_f32_16x16x32_bf16 v[104:107], v[146:149], v[206:209], v[104:107]
	v_mfma_f32_16x16x32_bf16 v[100:103], v[162:165], v[206:209], v[100:103]
	v_mfma_f32_16x16x32_bf16 v[88:91], v[146:149], v[214:217], v[88:91]
	v_mfma_f32_16x16x32_bf16 v[84:87], v[162:165], v[214:217], v[84:87]
	v_mfma_f32_16x16x32_bf16 v[72:75], v[146:149], v[222:225], v[72:75]
	v_mfma_f32_16x16x32_bf16 v[68:71], v[162:165], v[222:225], v[68:71]
	s_setprio 0
	s_setprio 1
	v_mfma_f32_16x16x32_bf16 v[124:127], v[166:169], v[182:185], 0
	v_mfma_f32_16x16x32_bf16 v[112:115], v[174:177], v[182:185], 0
	v_mfma_f32_16x16x32_bf16 v[108:111], v[166:169], v[202:205], 0
	v_mfma_f32_16x16x32_bf16 v[96:99], v[174:177], v[202:205], 0
	v_mfma_f32_16x16x32_bf16 v[92:95], v[166:169], v[210:213], 0
	v_mfma_f32_16x16x32_bf16 v[80:83], v[174:177], v[210:213], 0
	v_mfma_f32_16x16x32_bf16 v[76:79], v[166:169], v[218:221], 0
	v_mfma_f32_16x16x32_bf16 v[64:67], v[174:177], v[218:221], 0
	v_mfma_f32_16x16x32_bf16 v[124:127], v[170:173], v[186:189], v[124:127]
	v_mfma_f32_16x16x32_bf16 v[112:115], v[178:181], v[186:189], v[112:115]
	v_mfma_f32_16x16x32_bf16 v[108:111], v[170:173], v[206:209], v[108:111]
	v_mfma_f32_16x16x32_bf16 v[96:99], v[178:181], v[206:209], v[96:99]
	v_mfma_f32_16x16x32_bf16 v[92:95], v[170:173], v[214:217], v[92:95]
	v_mfma_f32_16x16x32_bf16 v[80:83], v[178:181], v[214:217], v[80:83]
	v_mfma_f32_16x16x32_bf16 v[76:79], v[170:173], v[222:225], v[76:79]
	v_mfma_f32_16x16x32_bf16 v[64:67], v[178:181], v[222:225], v[64:67]
	s_setprio 0
	s_barrier
	s_mov_b32 m0, s34
	v_lshl_add_u64 v[132:133], vcc, 0, v[128:129]
	ds_read_b128 v[182:185], v136 offset:16384
	ds_read_b128 v[186:189], v136 offset:17408
	ds_read_b128 v[202:205], v137 offset:16384
	ds_read_b128 v[206:209], v137 offset:17408
	ds_read_b128 v[210:213], v138 offset:16384
	ds_read_b128 v[214:217], v138 offset:17408
	ds_read_b128 v[218:221], v139 offset:16384
	ds_read_b128 v[222:225], v139 offset:17408
	global_load_lds_dwordx4 v[132:133], off
	v_lshl_add_u64 v[150:151], v[132:133], 0, s[8:9]
	s_mov_b32 m0, s35
	s_nop 0
	global_load_lds_dwordx4 v[150:151], off
	v_lshl_add_u64 v[150:151], v[132:133], 0, s[10:11]
	s_mov_b32 m0, s36
	s_nop 0
	global_load_lds_dwordx4 v[150:151], off
	v_lshl_add_u64 v[150:151], v[132:133], 0, s[12:13]
	s_mov_b32 m0, s37
	s_nop 0
	global_load_lds_dwordx4 v[150:151], off
	v_lshl_add_u64 v[150:151], s[70:71], 0, v[128:129]
	s_mov_b32 m0, s29
	v_lshl_add_u64 v[190:191], v[150:151], 0, s[8:9]
	global_load_lds_dwordx4 v[150:151], off
	s_mov_b32 m0, s38
	s_nop 0
	global_load_lds_dwordx4 v[190:191], off
	s_waitcnt vmcnt(8)
	s_waitcnt lgkmcnt(0)
	s_barrier
	s_setprio 1
	s_waitcnt lgkmcnt(0)
	v_mfma_f32_16x16x32_bf16 v[56:59], v[142:145], v[182:185], 0
	v_mfma_f32_16x16x32_bf16 v[52:55], v[158:161], v[182:185], 0
	v_mfma_f32_16x16x32_bf16 v[40:43], v[142:145], v[202:205], 0
	v_mfma_f32_16x16x32_bf16 v[36:39], v[158:161], v[202:205], 0
	v_mfma_f32_16x16x32_bf16 v[24:27], v[142:145], v[210:213], 0
	v_mfma_f32_16x16x32_bf16 v[20:23], v[158:161], v[210:213], 0
	v_mfma_f32_16x16x32_bf16 v[8:11], v[142:145], v[218:221], 0
	v_mfma_f32_16x16x32_bf16 v[4:7], v[158:161], v[218:221], 0
	v_mfma_f32_16x16x32_bf16 v[56:59], v[146:149], v[186:189], v[56:59]
	v_mfma_f32_16x16x32_bf16 v[52:55], v[162:165], v[186:189], v[52:55]
	v_mfma_f32_16x16x32_bf16 v[40:43], v[146:149], v[206:209], v[40:43]
	v_mfma_f32_16x16x32_bf16 v[36:39], v[162:165], v[206:209], v[36:39]
	v_mfma_f32_16x16x32_bf16 v[24:27], v[146:149], v[214:217], v[24:27]
	v_mfma_f32_16x16x32_bf16 v[20:23], v[162:165], v[214:217], v[20:23]
	v_mfma_f32_16x16x32_bf16 v[8:11], v[146:149], v[222:225], v[8:11]
	v_mfma_f32_16x16x32_bf16 v[4:7], v[162:165], v[222:225], v[4:7]
	s_setprio 0
	s_setprio 1
	v_mfma_f32_16x16x32_bf16 v[60:63], v[166:169], v[182:185], 0
	v_mfma_f32_16x16x32_bf16 v[48:51], v[174:177], v[182:185], 0
	v_mfma_f32_16x16x32_bf16 v[44:47], v[166:169], v[202:205], 0
	v_mfma_f32_16x16x32_bf16 v[32:35], v[174:177], v[202:205], 0
	v_mfma_f32_16x16x32_bf16 v[28:31], v[166:169], v[210:213], 0
	v_mfma_f32_16x16x32_bf16 v[16:19], v[174:177], v[210:213], 0
	v_mfma_f32_16x16x32_bf16 v[12:15], v[166:169], v[218:221], 0
	v_mfma_f32_16x16x32_bf16 v[0:3], v[174:177], v[218:221], 0
	v_mfma_f32_16x16x32_bf16 v[60:63], v[170:173], v[186:189], v[60:63]
	v_mfma_f32_16x16x32_bf16 v[48:51], v[178:181], v[186:189], v[48:51]
	v_mfma_f32_16x16x32_bf16 v[44:47], v[170:173], v[206:209], v[44:47]
	v_mfma_f32_16x16x32_bf16 v[32:35], v[178:181], v[206:209], v[32:35]
	v_mfma_f32_16x16x32_bf16 v[28:31], v[170:173], v[214:217], v[28:31]
	v_mfma_f32_16x16x32_bf16 v[16:19], v[178:181], v[214:217], v[16:19]
	v_mfma_f32_16x16x32_bf16 v[12:15], v[170:173], v[222:225], v[12:15]
	v_mfma_f32_16x16x32_bf16 v[0:3], v[178:181], v[222:225], v[0:3]
	s_setprio 0
	s_barrier
	ds_read_b128 v[142:145], v140
	ds_read_b128 v[146:149], v140 offset:1024
	ds_read_b128 v[158:161], v140 offset:2048
	ds_read_b128 v[162:165], v140 offset:3072
	ds_read_b128 v[166:169], v141
	ds_read_b128 v[170:173], v141 offset:1024
	ds_read_b128 v[174:177], v141 offset:2048
	ds_read_b128 v[178:181], v141 offset:3072
	s_mov_b32 m0, s39
	v_lshl_add_u64 v[190:191], v[150:151], 0, s[10:11]
	ds_read_b128 v[182:185], v136 offset:32768
	ds_read_b128 v[186:189], v136 offset:33792
	ds_read_b128 v[202:205], v137 offset:32768
	ds_read_b128 v[206:209], v137 offset:33792
	ds_read_b128 v[210:213], v138 offset:32768
	ds_read_b128 v[214:217], v138 offset:33792
	ds_read_b128 v[218:221], v139 offset:32768
	ds_read_b128 v[222:225], v139 offset:33792
	global_load_lds_dwordx4 v[190:191], off
	v_lshl_add_u64 v[190:191], v[150:151], 0, s[12:13]
	s_mov_b32 m0, s74
	s_nop 0
	global_load_lds_dwordx4 v[190:191], off
	s_waitcnt vmcnt(8)
	s_waitcnt lgkmcnt(0)
	s_barrier
	s_setprio 1
	s_waitcnt lgkmcnt(0)
	v_mfma_f32_16x16x32_bf16 v[120:123], v[142:145], v[182:185], v[120:123]
	v_mfma_f32_16x16x32_bf16 v[116:119], v[158:161], v[182:185], v[116:119]
	v_mfma_f32_16x16x32_bf16 v[104:107], v[142:145], v[202:205], v[104:107]
	v_mfma_f32_16x16x32_bf16 v[100:103], v[158:161], v[202:205], v[100:103]
	v_mfma_f32_16x16x32_bf16 v[88:91], v[142:145], v[210:213], v[88:91]
	v_mfma_f32_16x16x32_bf16 v[84:87], v[158:161], v[210:213], v[84:87]
	v_mfma_f32_16x16x32_bf16 v[72:75], v[142:145], v[218:221], v[72:75]
	v_mfma_f32_16x16x32_bf16 v[68:71], v[158:161], v[218:221], v[68:71]
	v_mfma_f32_16x16x32_bf16 v[120:123], v[146:149], v[186:189], v[120:123]
	v_mfma_f32_16x16x32_bf16 v[116:119], v[162:165], v[186:189], v[116:119]
	v_mfma_f32_16x16x32_bf16 v[104:107], v[146:149], v[206:209], v[104:107]
	v_mfma_f32_16x16x32_bf16 v[100:103], v[162:165], v[206:209], v[100:103]
	v_mfma_f32_16x16x32_bf16 v[88:91], v[146:149], v[214:217], v[88:91]
	v_mfma_f32_16x16x32_bf16 v[84:87], v[162:165], v[214:217], v[84:87]
	v_mfma_f32_16x16x32_bf16 v[72:75], v[146:149], v[222:225], v[72:75]
	v_mfma_f32_16x16x32_bf16 v[68:71], v[162:165], v[222:225], v[68:71]
	s_setprio 0
	s_setprio 1
	v_mfma_f32_16x16x32_bf16 v[124:127], v[166:169], v[182:185], v[124:127]
	v_mfma_f32_16x16x32_bf16 v[112:115], v[174:177], v[182:185], v[112:115]
	v_mfma_f32_16x16x32_bf16 v[108:111], v[166:169], v[202:205], v[108:111]
	v_mfma_f32_16x16x32_bf16 v[96:99], v[174:177], v[202:205], v[96:99]
	v_mfma_f32_16x16x32_bf16 v[92:95], v[166:169], v[210:213], v[92:95]
	v_mfma_f32_16x16x32_bf16 v[80:83], v[174:177], v[210:213], v[80:83]
	v_mfma_f32_16x16x32_bf16 v[76:79], v[166:169], v[218:221], v[76:79]
	v_mfma_f32_16x16x32_bf16 v[64:67], v[174:177], v[218:221], v[64:67]
	v_mfma_f32_16x16x32_bf16 v[124:127], v[170:173], v[186:189], v[124:127]
	v_mfma_f32_16x16x32_bf16 v[112:115], v[178:181], v[186:189], v[112:115]
	v_mfma_f32_16x16x32_bf16 v[108:111], v[170:173], v[206:209], v[108:111]
	v_mfma_f32_16x16x32_bf16 v[96:99], v[178:181], v[206:209], v[96:99]
	v_mfma_f32_16x16x32_bf16 v[92:95], v[170:173], v[214:217], v[92:95]
	v_mfma_f32_16x16x32_bf16 v[80:83], v[178:181], v[214:217], v[80:83]
	v_mfma_f32_16x16x32_bf16 v[76:79], v[170:173], v[222:225], v[76:79]
	v_mfma_f32_16x16x32_bf16 v[64:67], v[178:181], v[222:225], v[64:67]
	s_setprio 0
	s_barrier
	v_lshl_add_u64 v[190:191], v[132:133], 0, s[48:49]
	s_add_i32 m0, s29, 0x18000
	ds_read_b128 v[182:185], v136 offset:49152
	ds_read_b128 v[186:189], v136 offset:50176
	ds_read_b128 v[202:205], v137 offset:49152
	ds_read_b128 v[206:209], v137 offset:50176
	ds_read_b128 v[210:213], v138 offset:49152
	ds_read_b128 v[214:217], v138 offset:50176
	ds_read_b128 v[218:221], v139 offset:49152
	ds_read_b128 v[222:225], v139 offset:50176
	global_load_lds_dwordx4 v[190:191], off
	v_lshl_add_u64 v[190:191], v[132:133], 0, s[14:15]
	s_add_i32 m0, s29, 0x1a000
	s_nop 0
	global_load_lds_dwordx4 v[190:191], off
	v_lshl_add_u64 v[190:191], v[132:133], 0, s[56:57]
	s_add_i32 m0, s29, 0x1c000
	v_lshl_add_u64 v[132:133], v[132:133], 0, s[62:63]
	global_load_lds_dwordx4 v[190:191], off
	s_add_i32 m0, s29, 0x1e000
	s_nop 0
	global_load_lds_dwordx4 v[132:133], off
	v_lshl_add_u64 v[132:133], v[150:151], 0, s[48:49]
	s_mov_b32 m0, s75
	s_nop 0
	global_load_lds_dwordx4 v[132:133], off
	v_lshl_add_u64 v[132:133], v[150:151], 0, s[14:15]
	s_mov_b32 m0, s76
	s_nop 0
	global_load_lds_dwordx4 v[132:133], off
	s_waitcnt vmcnt(8)
	s_waitcnt lgkmcnt(0)
	s_barrier
	s_setprio 1
	s_waitcnt lgkmcnt(0)
	v_mfma_f32_16x16x32_bf16 v[56:59], v[142:145], v[182:185], v[56:59]
	v_mfma_f32_16x16x32_bf16 v[52:55], v[158:161], v[182:185], v[52:55]
	v_mfma_f32_16x16x32_bf16 v[40:43], v[142:145], v[202:205], v[40:43]
	v_mfma_f32_16x16x32_bf16 v[36:39], v[158:161], v[202:205], v[36:39]
	v_mfma_f32_16x16x32_bf16 v[24:27], v[142:145], v[210:213], v[24:27]
	v_mfma_f32_16x16x32_bf16 v[20:23], v[158:161], v[210:213], v[20:23]
	v_mfma_f32_16x16x32_bf16 v[8:11], v[142:145], v[218:221], v[8:11]
	v_mfma_f32_16x16x32_bf16 v[4:7], v[158:161], v[218:221], v[4:7]
	v_mfma_f32_16x16x32_bf16 v[56:59], v[146:149], v[186:189], v[56:59]
	v_mfma_f32_16x16x32_bf16 v[52:55], v[162:165], v[186:189], v[52:55]
	v_mfma_f32_16x16x32_bf16 v[40:43], v[146:149], v[206:209], v[40:43]
	v_mfma_f32_16x16x32_bf16 v[36:39], v[162:165], v[206:209], v[36:39]
	v_mfma_f32_16x16x32_bf16 v[24:27], v[146:149], v[214:217], v[24:27]
	v_mfma_f32_16x16x32_bf16 v[20:23], v[162:165], v[214:217], v[20:23]
	v_mfma_f32_16x16x32_bf16 v[8:11], v[146:149], v[222:225], v[8:11]
	v_mfma_f32_16x16x32_bf16 v[4:7], v[162:165], v[222:225], v[4:7]
	s_setprio 0
	s_setprio 1
	v_mfma_f32_16x16x32_bf16 v[60:63], v[166:169], v[182:185], v[60:63]
	v_mfma_f32_16x16x32_bf16 v[48:51], v[174:177], v[182:185], v[48:51]
	v_mfma_f32_16x16x32_bf16 v[44:47], v[166:169], v[202:205], v[44:47]
	v_mfma_f32_16x16x32_bf16 v[32:35], v[174:177], v[202:205], v[32:35]
	v_mfma_f32_16x16x32_bf16 v[28:31], v[166:169], v[210:213], v[28:31]
	v_mfma_f32_16x16x32_bf16 v[16:19], v[174:177], v[210:213], v[16:19]
	v_mfma_f32_16x16x32_bf16 v[12:15], v[166:169], v[218:221], v[12:15]
	v_mfma_f32_16x16x32_bf16 v[0:3], v[174:177], v[218:221], v[0:3]
	v_mfma_f32_16x16x32_bf16 v[60:63], v[170:173], v[186:189], v[60:63]
	v_mfma_f32_16x16x32_bf16 v[48:51], v[178:181], v[186:189], v[48:51]
	v_mfma_f32_16x16x32_bf16 v[44:47], v[170:173], v[206:209], v[44:47]
	v_mfma_f32_16x16x32_bf16 v[32:35], v[178:181], v[206:209], v[32:35]
	v_mfma_f32_16x16x32_bf16 v[28:31], v[170:173], v[214:217], v[28:31]
	v_mfma_f32_16x16x32_bf16 v[16:19], v[178:181], v[214:217], v[16:19]
	v_mfma_f32_16x16x32_bf16 v[12:15], v[170:173], v[222:225], v[12:15]
	v_mfma_f32_16x16x32_bf16 v[0:3], v[178:181], v[222:225], v[0:3]
	s_setprio 0
	s_barrier
	s_add_i32 s69, s69, 2
	s_add_u32 s94, s94, 0x100
	s_addc_u32 s95, s95, 0
	s_add_u32 s53, s53, 0x100
	s_addc_u32 s68, s68, 0
	s_cmp_lt_u32 s69, 14

.LBB0_318:
	s_add_u32 s68, s68, 0x20080
	s_addc_u32 s69, s69, 0
	s_add_u32 s53, s70, 0x100
	s_addc_u32 s70, s71, 0
	s_mov_b32 s71, -2
	ds_read_b128 v[76:79], v70
	ds_read_b128 v[80:83], v70 offset:1024
	ds_read_b128 v[84:87], v70 offset:2048
	ds_read_b128 v[88:91], v70 offset:3072
	ds_read_b128 v[92:95], v71
	ds_read_b128 v[96:99], v71 offset:1024
	ds_read_b128 v[100:103], v71 offset:2048
	ds_read_b128 v[104:107], v71 offset:3072
	s_add_u32 s83, s68, 0xfffe0080
	s_addc_u32 s85, s69, -1
	s_cmp_eq_u32 s71, 12
	s_cselect_b32 s93, s55, s85
	s_cselect_b32 s92, s54, s83
	s_cselect_b32 s95, s89, s70
	s_cselect_b32 s94, s88, s53
	v_lshl_add_u64 v[68:69], s[68:69], 0, v[66:67]
	s_add_i32 m0, s29, 0xc000
	ds_read_b128 v[108:111], v72
	ds_read_b128 v[112:115], v72 offset:1024
	ds_read_b128 v[116:119], v73
	ds_read_b128 v[120:123], v73 offset:1024
	global_load_lds_dwordx4 v[68:69], off
	v_lshl_add_u64 v[68:69], v[68:69], 0, s[8:9]
	s_add_i32 m0, s29, 0xe000
	s_nop 0
	global_load_lds_dwordx4 v[68:69], off
	s_waitcnt vmcnt(8)
	s_waitcnt lgkmcnt(0)
	s_barrier
	s_setprio 1
	s_waitcnt lgkmcnt(0)
	v_mfma_f32_16x16x32_bf16 v[56:59], v[76:79], v[108:111], 0
	v_mfma_f32_16x16x32_bf16 v[52:55], v[84:87], v[108:111], 0
	v_mfma_f32_16x16x32_bf16 v[40:43], v[76:79], v[116:119], 0
	v_mfma_f32_16x16x32_bf16 v[36:39], v[84:87], v[116:119], 0
	v_mfma_f32_16x16x32_bf16 v[56:59], v[80:83], v[112:115], v[56:59]
	v_mfma_f32_16x16x32_bf16 v[52:55], v[88:91], v[112:115], v[52:55]
	v_mfma_f32_16x16x32_bf16 v[40:43], v[80:83], v[120:123], v[40:43]
	v_mfma_f32_16x16x32_bf16 v[36:39], v[88:91], v[120:123], v[36:39]
	s_setprio 0
	s_setprio 1
	v_mfma_f32_16x16x32_bf16 v[60:63], v[92:95], v[108:111], 0
	v_mfma_f32_16x16x32_bf16 v[48:51], v[100:103], v[108:111], 0
	v_mfma_f32_16x16x32_bf16 v[44:47], v[92:95], v[116:119], 0
	v_mfma_f32_16x16x32_bf16 v[32:35], v[100:103], v[116:119], 0
	v_mfma_f32_16x16x32_bf16 v[60:63], v[96:99], v[112:115], v[60:63]
	v_mfma_f32_16x16x32_bf16 v[48:51], v[104:107], v[112:115], v[48:51]
	v_mfma_f32_16x16x32_bf16 v[44:47], v[96:99], v[120:123], v[44:47]
	v_mfma_f32_16x16x32_bf16 v[32:35], v[104:107], v[120:123], v[32:35]
	s_setprio 0
	s_barrier
	s_mov_b32 m0, s34
	v_lshl_add_u64 v[68:69], s[94:95], 0, v[64:65]
	ds_read_b128 v[108:111], v72 offset:16384
	ds_read_b128 v[112:115], v72 offset:17408
	ds_read_b128 v[116:119], v73 offset:16384
	ds_read_b128 v[120:123], v73 offset:17408
	global_load_lds_dwordx4 v[68:69], off
	v_lshl_add_u64 v[124:125], v[68:69], 0, s[8:9]
	s_mov_b32 m0, s35
	s_nop 0
	global_load_lds_dwordx4 v[124:125], off
	v_lshl_add_u64 v[124:125], v[68:69], 0, s[10:11]
	s_mov_b32 m0, s36
	s_nop 0
	global_load_lds_dwordx4 v[124:125], off
	v_lshl_add_u64 v[124:125], v[68:69], 0, s[12:13]
	s_mov_b32 m0, s37
	s_nop 0
	global_load_lds_dwordx4 v[124:125], off
	v_lshl_add_u64 v[124:125], s[92:93], 0, v[64:65]
	s_mov_b32 m0, s29
	v_lshl_add_u64 v[126:127], v[124:125], 0, s[8:9]
	global_load_lds_dwordx4 v[124:125], off
	s_mov_b32 m0, s38
	s_nop 0
	global_load_lds_dwordx4 v[126:127], off
	s_waitcnt vmcnt(8)
	s_waitcnt lgkmcnt(0)
	s_barrier
	s_setprio 1
	s_waitcnt lgkmcnt(0)
	v_mfma_f32_16x16x32_bf16 v[24:27], v[76:79], v[108:111], 0
	v_mfma_f32_16x16x32_bf16 v[20:23], v[84:87], v[108:111], 0
	v_mfma_f32_16x16x32_bf16 v[8:11], v[76:79], v[116:119], 0
	v_mfma_f32_16x16x32_bf16 v[4:7], v[84:87], v[116:119], 0
	v_mfma_f32_16x16x32_bf16 v[24:27], v[80:83], v[112:115], v[24:27]
	v_mfma_f32_16x16x32_bf16 v[20:23], v[88:91], v[112:115], v[20:23]
	v_mfma_f32_16x16x32_bf16 v[8:11], v[80:83], v[120:123], v[8:11]
	v_mfma_f32_16x16x32_bf16 v[4:7], v[88:91], v[120:123], v[4:7]
	s_setprio 0
	s_setprio 1
	v_mfma_f32_16x16x32_bf16 v[28:31], v[92:95], v[108:111], 0
	v_mfma_f32_16x16x32_bf16 v[16:19], v[100:103], v[108:111], 0
	v_mfma_f32_16x16x32_bf16 v[12:15], v[92:95], v[116:119], 0
	v_mfma_f32_16x16x32_bf16 v[0:3], v[100:103], v[116:119], 0
	v_mfma_f32_16x16x32_bf16 v[28:31], v[96:99], v[112:115], v[28:31]
	v_mfma_f32_16x16x32_bf16 v[16:19], v[104:107], v[112:115], v[16:19]
	v_mfma_f32_16x16x32_bf16 v[12:15], v[96:99], v[120:123], v[12:15]
	v_mfma_f32_16x16x32_bf16 v[0:3], v[104:107], v[120:123], v[0:3]
	s_setprio 0
	s_barrier
	ds_read_b128 v[76:79], v74
	ds_read_b128 v[80:83], v74 offset:1024
	ds_read_b128 v[84:87], v74 offset:2048
	ds_read_b128 v[88:91], v74 offset:3072
	ds_read_b128 v[92:95], v75
	ds_read_b128 v[96:99], v75 offset:1024
	ds_read_b128 v[100:103], v75 offset:2048
	ds_read_b128 v[104:107], v75 offset:3072
	s_mov_b32 m0, s39
	ds_read_b128 v[108:111], v72 offset:32768
	ds_read_b128 v[112:115], v72 offset:33792
	ds_read_b128 v[116:119], v73 offset:32768
	ds_read_b128 v[120:123], v73 offset:33792
	global_load_lds_dwordx4 v[126:127], off
	v_lshl_add_u64 v[126:127], v[124:125], 0, s[10:11]
	s_mov_b32 m0, s74
	s_nop 0
	global_load_lds_dwordx4 v[126:127], off
	s_waitcnt vmcnt(8)
	s_waitcnt lgkmcnt(0)
	s_barrier
	s_setprio 1
	s_waitcnt lgkmcnt(0)
	v_mfma_f32_16x16x32_bf16 v[56:59], v[76:79], v[108:111], v[56:59]
	v_mfma_f32_16x16x32_bf16 v[52:55], v[84:87], v[108:111], v[52:55]
	v_mfma_f32_16x16x32_bf16 v[40:43], v[76:79], v[116:119], v[40:43]
	v_mfma_f32_16x16x32_bf16 v[36:39], v[84:87], v[116:119], v[36:39]
	v_mfma_f32_16x16x32_bf16 v[56:59], v[80:83], v[112:115], v[56:59]
	v_mfma_f32_16x16x32_bf16 v[52:55], v[88:91], v[112:115], v[52:55]
	v_mfma_f32_16x16x32_bf16 v[40:43], v[80:83], v[120:123], v[40:43]
	v_mfma_f32_16x16x32_bf16 v[36:39], v[88:91], v[120:123], v[36:39]
	s_setprio 0
	s_setprio 1
	v_mfma_f32_16x16x32_bf16 v[60:63], v[92:95], v[108:111], v[60:63]
	v_mfma_f32_16x16x32_bf16 v[48:51], v[100:103], v[108:111], v[48:51]
	v_mfma_f32_16x16x32_bf16 v[44:47], v[92:95], v[116:119], v[44:47]
	v_mfma_f32_16x16x32_bf16 v[32:35], v[100:103], v[116:119], v[32:35]
	v_mfma_f32_16x16x32_bf16 v[60:63], v[96:99], v[112:115], v[60:63]
	v_mfma_f32_16x16x32_bf16 v[48:51], v[104:107], v[112:115], v[48:51]
	v_mfma_f32_16x16x32_bf16 v[44:47], v[96:99], v[120:123], v[44:47]
	v_mfma_f32_16x16x32_bf16 v[32:35], v[104:107], v[120:123], v[32:35]
	s_setprio 0
	s_barrier
	v_lshl_add_u64 v[126:127], v[68:69], 0, s[48:49]
	s_add_i32 m0, s29, 0x18000
	ds_read_b128 v[108:111], v72 offset:49152
	ds_read_b128 v[112:115], v72 offset:50176
	ds_read_b128 v[116:119], v73 offset:49152
	ds_read_b128 v[120:123], v73 offset:50176
	global_load_lds_dwordx4 v[126:127], off
	v_lshl_add_u64 v[126:127], v[68:69], 0, s[14:15]
	s_add_i32 m0, s29, 0x1a000
	s_nop 0
	global_load_lds_dwordx4 v[126:127], off
	v_lshl_add_u64 v[126:127], v[68:69], 0, s[56:57]
	s_add_i32 m0, s29, 0x1c000
	v_lshl_add_u64 v[68:69], v[68:69], 0, s[62:63]
	global_load_lds_dwordx4 v[126:127], off
	s_add_i32 m0, s29, 0x1e000
	s_nop 0
	global_load_lds_dwordx4 v[68:69], off
	v_lshl_add_u64 v[68:69], v[124:125], 0, s[48:49]
	s_mov_b32 m0, s75
	s_nop 0
	global_load_lds_dwordx4 v[68:69], off
	v_lshl_add_u64 v[68:69], v[124:125], 0, s[14:15]
	s_mov_b32 m0, s76
	s_nop 0
	global_load_lds_dwordx4 v[68:69], off
	s_waitcnt vmcnt(8)
	s_waitcnt lgkmcnt(0)
	s_barrier
	s_setprio 1
	s_waitcnt lgkmcnt(0)
	v_mfma_f32_16x16x32_bf16 v[24:27], v[76:79], v[108:111], v[24:27]
	v_mfma_f32_16x16x32_bf16 v[20:23], v[84:87], v[108:111], v[20:23]
	v_mfma_f32_16x16x32_bf16 v[8:11], v[76:79], v[116:119], v[8:11]
	v_mfma_f32_16x16x32_bf16 v[4:7], v[84:87], v[116:119], v[4:7]
	v_mfma_f32_16x16x32_bf16 v[24:27], v[80:83], v[112:115], v[24:27]
	v_mfma_f32_16x16x32_bf16 v[20:23], v[88:91], v[112:115], v[20:23]
	v_mfma_f32_16x16x32_bf16 v[8:11], v[80:83], v[120:123], v[8:11]
	v_mfma_f32_16x16x32_bf16 v[4:7], v[88:91], v[120:123], v[4:7]
	s_setprio 0
	s_setprio 1
	v_mfma_f32_16x16x32_bf16 v[28:31], v[92:95], v[108:111], v[28:31]
	v_mfma_f32_16x16x32_bf16 v[16:19], v[100:103], v[108:111], v[16:19]
	v_mfma_f32_16x16x32_bf16 v[12:15], v[92:95], v[116:119], v[12:15]
	v_mfma_f32_16x16x32_bf16 v[0:3], v[100:103], v[116:119], v[0:3]
	v_mfma_f32_16x16x32_bf16 v[28:31], v[96:99], v[112:115], v[28:31]
	v_mfma_f32_16x16x32_bf16 v[16:19], v[104:107], v[112:115], v[16:19]
	v_mfma_f32_16x16x32_bf16 v[12:15], v[96:99], v[120:123], v[12:15]
	v_mfma_f32_16x16x32_bf16 v[0:3], v[104:107], v[120:123], v[0:3]
	s_setprio 0
	s_barrier
	s_add_i32 s71, s71, 2
	s_add_u32 s68, s68, 0x100
	s_addc_u32 s69, s69, 0
	s_add_u32 s53, s53, 0x100
	s_addc_u32 s70, s70, 0
	s_cmp_lt_u32 s71, 14

.LBB0_338:
	s_add_u32 s92, s68, 0x40080
	s_addc_u32 s93, s69, 0
	s_add_u32 s51, s70, 0x100
	s_addc_u32 s68, s71, 0
	s_mov_b32 s69, -2
	ds_read_b128 v[142:145], v134
	ds_read_b128 v[146:149], v134 offset:1024
	ds_read_b128 v[158:161], v134 offset:2048
	ds_read_b128 v[162:165], v134 offset:3072
	ds_read_b128 v[166:169], v135
	ds_read_b128 v[170:173], v135 offset:1024
	ds_read_b128 v[174:177], v135 offset:2048
	ds_read_b128 v[178:181], v135 offset:3072
	s_add_u32 s70, s92, 0xfffc0080
	s_addc_u32 s71, s93, -1
	s_cmp_eq_u32 s69, 12
	s_cselect_b32 s71, s53, s71
	s_cselect_b32 s70, s52, s70
	s_cselect_b32 s79, s55, s68
	s_cselect_b32 s78, s54, s51
	v_lshl_add_u64 v[132:133], s[92:93], 0, v[130:131]
	s_add_i32 m0, s1, 0xc000
	ds_read_b128 v[182:185], v136
	ds_read_b128 v[186:189], v136 offset:1024
	ds_read_b128 v[202:205], v137
	ds_read_b128 v[206:209], v137 offset:1024
	ds_read_b128 v[210:213], v138
	ds_read_b128 v[214:217], v138 offset:1024
	ds_read_b128 v[218:221], v139
	ds_read_b128 v[222:225], v139 offset:1024
	global_load_lds_dwordx4 v[132:133], off
	v_lshl_add_u64 v[132:133], v[132:133], 0, s[8:9]
	s_add_i32 m0, s1, 0xe000
	s_nop 0
	global_load_lds_dwordx4 v[132:133], off
	s_waitcnt vmcnt(8)
	s_waitcnt lgkmcnt(0)
	s_barrier
	s_setprio 1
	s_waitcnt lgkmcnt(0)
	v_mfma_f32_16x16x32_bf16 v[120:123], v[142:145], v[182:185], 0
	v_mfma_f32_16x16x32_bf16 v[116:119], v[158:161], v[182:185], 0
	v_mfma_f32_16x16x32_bf16 v[104:107], v[142:145], v[202:205], 0
	v_mfma_f32_16x16x32_bf16 v[100:103], v[158:161], v[202:205], 0
	v_mfma_f32_16x16x32_bf16 v[88:91], v[142:145], v[210:213], 0
	v_mfma_f32_16x16x32_bf16 v[84:87], v[158:161], v[210:213], 0
	v_mfma_f32_16x16x32_bf16 v[72:75], v[142:145], v[218:221], 0
	v_mfma_f32_16x16x32_bf16 v[68:71], v[158:161], v[218:221], 0
	v_mfma_f32_16x16x32_bf16 v[120:123], v[146:149], v[186:189], v[120:123]
	v_mfma_f32_16x16x32_bf16 v[116:119], v[162:165], v[186:189], v[116:119]
	v_mfma_f32_16x16x32_bf16 v[104:107], v[146:149], v[206:209], v[104:107]
	v_mfma_f32_16x16x32_bf16 v[100:103], v[162:165], v[206:209], v[100:103]
	v_mfma_f32_16x16x32_bf16 v[88:91], v[146:149], v[214:217], v[88:91]
	v_mfma_f32_16x16x32_bf16 v[84:87], v[162:165], v[214:217], v[84:87]
	v_mfma_f32_16x16x32_bf16 v[72:75], v[146:149], v[222:225], v[72:75]
	v_mfma_f32_16x16x32_bf16 v[68:71], v[162:165], v[222:225], v[68:71]
	s_setprio 0
	s_setprio 1
	v_mfma_f32_16x16x32_bf16 v[124:127], v[166:169], v[182:185], 0
	v_mfma_f32_16x16x32_bf16 v[112:115], v[174:177], v[182:185], 0
	v_mfma_f32_16x16x32_bf16 v[108:111], v[166:169], v[202:205], 0
	v_mfma_f32_16x16x32_bf16 v[96:99], v[174:177], v[202:205], 0
	v_mfma_f32_16x16x32_bf16 v[92:95], v[166:169], v[210:213], 0
	v_mfma_f32_16x16x32_bf16 v[80:83], v[174:177], v[210:213], 0
	v_mfma_f32_16x16x32_bf16 v[76:79], v[166:169], v[218:221], 0
	v_mfma_f32_16x16x32_bf16 v[64:67], v[174:177], v[218:221], 0
	v_mfma_f32_16x16x32_bf16 v[124:127], v[170:173], v[186:189], v[124:127]
	v_mfma_f32_16x16x32_bf16 v[112:115], v[178:181], v[186:189], v[112:115]
	v_mfma_f32_16x16x32_bf16 v[108:111], v[170:173], v[206:209], v[108:111]
	v_mfma_f32_16x16x32_bf16 v[96:99], v[178:181], v[206:209], v[96:99]
	v_mfma_f32_16x16x32_bf16 v[92:95], v[170:173], v[214:217], v[92:95]
	v_mfma_f32_16x16x32_bf16 v[80:83], v[178:181], v[214:217], v[80:83]
	v_mfma_f32_16x16x32_bf16 v[76:79], v[170:173], v[222:225], v[76:79]
	v_mfma_f32_16x16x32_bf16 v[64:67], v[178:181], v[222:225], v[64:67]
	s_setprio 0
	s_barrier
	s_mov_b32 m0, s28
	v_lshl_add_u64 v[132:133], s[78:79], 0, v[128:129]
	ds_read_b128 v[182:185], v136 offset:16384
	ds_read_b128 v[186:189], v136 offset:17408
	ds_read_b128 v[202:205], v137 offset:16384
	ds_read_b128 v[206:209], v137 offset:17408
	ds_read_b128 v[210:213], v138 offset:16384
	ds_read_b128 v[214:217], v138 offset:17408
	ds_read_b128 v[218:221], v139 offset:16384
	ds_read_b128 v[222:225], v139 offset:17408
	global_load_lds_dwordx4 v[132:133], off
	v_lshl_add_u64 v[150:151], v[132:133], 0, s[8:9]
	s_mov_b32 m0, s29
	s_nop 0
	global_load_lds_dwordx4 v[150:151], off
	v_lshl_add_u64 v[150:151], v[132:133], 0, s[10:11]
	s_mov_b32 m0, s34
	s_nop 0
	global_load_lds_dwordx4 v[150:151], off
	v_lshl_add_u64 v[150:151], v[132:133], 0, s[12:13]
	s_mov_b32 m0, s35
	s_nop 0
	global_load_lds_dwordx4 v[150:151], off
	v_lshl_add_u64 v[150:151], s[70:71], 0, v[128:129]
	s_mov_b32 m0, s1
	v_lshl_add_u64 v[190:191], v[150:151], 0, s[8:9]
	global_load_lds_dwordx4 v[150:151], off
	s_mov_b32 m0, s36
	s_nop 0
	global_load_lds_dwordx4 v[190:191], off
	s_waitcnt vmcnt(8)
	s_waitcnt lgkmcnt(0)
	s_barrier
	s_setprio 1
	s_waitcnt lgkmcnt(0)
	v_mfma_f32_16x16x32_bf16 v[56:59], v[142:145], v[182:185], 0
	v_mfma_f32_16x16x32_bf16 v[52:55], v[158:161], v[182:185], 0
	v_mfma_f32_16x16x32_bf16 v[40:43], v[142:145], v[202:205], 0
	v_mfma_f32_16x16x32_bf16 v[36:39], v[158:161], v[202:205], 0
	v_mfma_f32_16x16x32_bf16 v[24:27], v[142:145], v[210:213], 0
	v_mfma_f32_16x16x32_bf16 v[20:23], v[158:161], v[210:213], 0
	v_mfma_f32_16x16x32_bf16 v[8:11], v[142:145], v[218:221], 0
	v_mfma_f32_16x16x32_bf16 v[4:7], v[158:161], v[218:221], 0
	v_mfma_f32_16x16x32_bf16 v[56:59], v[146:149], v[186:189], v[56:59]
	v_mfma_f32_16x16x32_bf16 v[52:55], v[162:165], v[186:189], v[52:55]
	v_mfma_f32_16x16x32_bf16 v[40:43], v[146:149], v[206:209], v[40:43]
	v_mfma_f32_16x16x32_bf16 v[36:39], v[162:165], v[206:209], v[36:39]
	v_mfma_f32_16x16x32_bf16 v[24:27], v[146:149], v[214:217], v[24:27]
	v_mfma_f32_16x16x32_bf16 v[20:23], v[162:165], v[214:217], v[20:23]
	v_mfma_f32_16x16x32_bf16 v[8:11], v[146:149], v[222:225], v[8:11]
	v_mfma_f32_16x16x32_bf16 v[4:7], v[162:165], v[222:225], v[4:7]
	s_setprio 0
	s_setprio 1
	v_mfma_f32_16x16x32_bf16 v[60:63], v[166:169], v[182:185], 0
	v_mfma_f32_16x16x32_bf16 v[48:51], v[174:177], v[182:185], 0
	v_mfma_f32_16x16x32_bf16 v[44:47], v[166:169], v[202:205], 0
	v_mfma_f32_16x16x32_bf16 v[32:35], v[174:177], v[202:205], 0
	v_mfma_f32_16x16x32_bf16 v[28:31], v[166:169], v[210:213], 0
	v_mfma_f32_16x16x32_bf16 v[16:19], v[174:177], v[210:213], 0
	v_mfma_f32_16x16x32_bf16 v[12:15], v[166:169], v[218:221], 0
	v_mfma_f32_16x16x32_bf16 v[0:3], v[174:177], v[218:221], 0
	v_mfma_f32_16x16x32_bf16 v[60:63], v[170:173], v[186:189], v[60:63]
	v_mfma_f32_16x16x32_bf16 v[48:51], v[178:181], v[186:189], v[48:51]
	v_mfma_f32_16x16x32_bf16 v[44:47], v[170:173], v[206:209], v[44:47]
	v_mfma_f32_16x16x32_bf16 v[32:35], v[178:181], v[206:209], v[32:35]
	v_mfma_f32_16x16x32_bf16 v[28:31], v[170:173], v[214:217], v[28:31]
	v_mfma_f32_16x16x32_bf16 v[16:19], v[178:181], v[214:217], v[16:19]
	v_mfma_f32_16x16x32_bf16 v[12:15], v[170:173], v[222:225], v[12:15]
	v_mfma_f32_16x16x32_bf16 v[0:3], v[178:181], v[222:225], v[0:3]
	s_setprio 0
	s_barrier
	ds_read_b128 v[142:145], v140
	ds_read_b128 v[146:149], v140 offset:1024
	ds_read_b128 v[158:161], v140 offset:2048
	ds_read_b128 v[162:165], v140 offset:3072
	ds_read_b128 v[166:169], v141
	ds_read_b128 v[170:173], v141 offset:1024
	ds_read_b128 v[174:177], v141 offset:2048
	ds_read_b128 v[178:181], v141 offset:3072
	s_mov_b32 m0, s37
	v_lshl_add_u64 v[190:191], v[150:151], 0, s[10:11]
	ds_read_b128 v[182:185], v136 offset:32768
	ds_read_b128 v[186:189], v136 offset:33792
	ds_read_b128 v[202:205], v137 offset:32768
	ds_read_b128 v[206:209], v137 offset:33792
	ds_read_b128 v[210:213], v138 offset:32768
	ds_read_b128 v[214:217], v138 offset:33792
	ds_read_b128 v[218:221], v139 offset:32768
	ds_read_b128 v[222:225], v139 offset:33792
	global_load_lds_dwordx4 v[190:191], off
	v_lshl_add_u64 v[190:191], v[150:151], 0, s[12:13]
	s_mov_b32 m0, s38
	s_nop 0
	global_load_lds_dwordx4 v[190:191], off
	s_waitcnt vmcnt(8)
	s_waitcnt lgkmcnt(0)
	s_barrier
	s_setprio 1
	s_waitcnt lgkmcnt(0)
	v_mfma_f32_16x16x32_bf16 v[120:123], v[142:145], v[182:185], v[120:123]
	v_mfma_f32_16x16x32_bf16 v[116:119], v[158:161], v[182:185], v[116:119]
	v_mfma_f32_16x16x32_bf16 v[104:107], v[142:145], v[202:205], v[104:107]
	v_mfma_f32_16x16x32_bf16 v[100:103], v[158:161], v[202:205], v[100:103]
	v_mfma_f32_16x16x32_bf16 v[88:91], v[142:145], v[210:213], v[88:91]
	v_mfma_f32_16x16x32_bf16 v[84:87], v[158:161], v[210:213], v[84:87]
	v_mfma_f32_16x16x32_bf16 v[72:75], v[142:145], v[218:221], v[72:75]
	v_mfma_f32_16x16x32_bf16 v[68:71], v[158:161], v[218:221], v[68:71]
	v_mfma_f32_16x16x32_bf16 v[120:123], v[146:149], v[186:189], v[120:123]
	v_mfma_f32_16x16x32_bf16 v[116:119], v[162:165], v[186:189], v[116:119]
	v_mfma_f32_16x16x32_bf16 v[104:107], v[146:149], v[206:209], v[104:107]
	v_mfma_f32_16x16x32_bf16 v[100:103], v[162:165], v[206:209], v[100:103]
	v_mfma_f32_16x16x32_bf16 v[88:91], v[146:149], v[214:217], v[88:91]
	v_mfma_f32_16x16x32_bf16 v[84:87], v[162:165], v[214:217], v[84:87]
	v_mfma_f32_16x16x32_bf16 v[72:75], v[146:149], v[222:225], v[72:75]
	v_mfma_f32_16x16x32_bf16 v[68:71], v[162:165], v[222:225], v[68:71]
	s_setprio 0
	s_setprio 1
	v_mfma_f32_16x16x32_bf16 v[124:127], v[166:169], v[182:185], v[124:127]
	v_mfma_f32_16x16x32_bf16 v[112:115], v[174:177], v[182:185], v[112:115]
	v_mfma_f32_16x16x32_bf16 v[108:111], v[166:169], v[202:205], v[108:111]
	v_mfma_f32_16x16x32_bf16 v[96:99], v[174:177], v[202:205], v[96:99]
	v_mfma_f32_16x16x32_bf16 v[92:95], v[166:169], v[210:213], v[92:95]
	v_mfma_f32_16x16x32_bf16 v[80:83], v[174:177], v[210:213], v[80:83]
	v_mfma_f32_16x16x32_bf16 v[76:79], v[166:169], v[218:221], v[76:79]
	v_mfma_f32_16x16x32_bf16 v[64:67], v[174:177], v[218:221], v[64:67]
	v_mfma_f32_16x16x32_bf16 v[124:127], v[170:173], v[186:189], v[124:127]
	v_mfma_f32_16x16x32_bf16 v[112:115], v[178:181], v[186:189], v[112:115]
	v_mfma_f32_16x16x32_bf16 v[108:111], v[170:173], v[206:209], v[108:111]
	v_mfma_f32_16x16x32_bf16 v[96:99], v[178:181], v[206:209], v[96:99]
	v_mfma_f32_16x16x32_bf16 v[92:95], v[170:173], v[214:217], v[92:95]
	v_mfma_f32_16x16x32_bf16 v[80:83], v[178:181], v[214:217], v[80:83]
	v_mfma_f32_16x16x32_bf16 v[76:79], v[170:173], v[222:225], v[76:79]
	v_mfma_f32_16x16x32_bf16 v[64:67], v[178:181], v[222:225], v[64:67]
	s_setprio 0
	s_barrier
	v_lshl_add_u64 v[190:191], v[132:133], 0, s[48:49]
	s_add_i32 m0, s1, 0x18000
	ds_read_b128 v[182:185], v136 offset:49152
	ds_read_b128 v[186:189], v136 offset:50176
	ds_read_b128 v[202:205], v137 offset:49152
	ds_read_b128 v[206:209], v137 offset:50176
	ds_read_b128 v[210:213], v138 offset:49152
	ds_read_b128 v[214:217], v138 offset:50176
	ds_read_b128 v[218:221], v139 offset:49152
	ds_read_b128 v[222:225], v139 offset:50176
	global_load_lds_dwordx4 v[190:191], off
	v_lshl_add_u64 v[190:191], v[132:133], 0, s[14:15]
	s_add_i32 m0, s1, 0x1a000
	s_nop 0
	global_load_lds_dwordx4 v[190:191], off
	v_lshl_add_u64 v[190:191], v[132:133], 0, s[56:57]
	s_add_i32 m0, s1, 0x1c000
	v_lshl_add_u64 v[132:133], v[132:133], 0, s[62:63]
	global_load_lds_dwordx4 v[190:191], off
	s_add_i32 m0, s1, 0x1e000
	s_nop 0
	global_load_lds_dwordx4 v[132:133], off
	v_lshl_add_u64 v[132:133], v[150:151], 0, s[48:49]
	s_mov_b32 m0, s39
	s_nop 0
	global_load_lds_dwordx4 v[132:133], off
	v_lshl_add_u64 v[132:133], v[150:151], 0, s[14:15]
	s_mov_b32 m0, s74
	s_nop 0
	global_load_lds_dwordx4 v[132:133], off
	s_waitcnt vmcnt(8)
	s_waitcnt lgkmcnt(0)
	s_barrier
	s_setprio 1
	s_waitcnt lgkmcnt(0)
	v_mfma_f32_16x16x32_bf16 v[56:59], v[142:145], v[182:185], v[56:59]
	v_mfma_f32_16x16x32_bf16 v[52:55], v[158:161], v[182:185], v[52:55]
	v_mfma_f32_16x16x32_bf16 v[40:43], v[142:145], v[202:205], v[40:43]
	v_mfma_f32_16x16x32_bf16 v[36:39], v[158:161], v[202:205], v[36:39]
	v_mfma_f32_16x16x32_bf16 v[24:27], v[142:145], v[210:213], v[24:27]
	v_mfma_f32_16x16x32_bf16 v[20:23], v[158:161], v[210:213], v[20:23]
	v_mfma_f32_16x16x32_bf16 v[8:11], v[142:145], v[218:221], v[8:11]
	v_mfma_f32_16x16x32_bf16 v[4:7], v[158:161], v[218:221], v[4:7]
	v_mfma_f32_16x16x32_bf16 v[56:59], v[146:149], v[186:189], v[56:59]
	v_mfma_f32_16x16x32_bf16 v[52:55], v[162:165], v[186:189], v[52:55]
	v_mfma_f32_16x16x32_bf16 v[40:43], v[146:149], v[206:209], v[40:43]
	v_mfma_f32_16x16x32_bf16 v[36:39], v[162:165], v[206:209], v[36:39]
	v_mfma_f32_16x16x32_bf16 v[24:27], v[146:149], v[214:217], v[24:27]
	v_mfma_f32_16x16x32_bf16 v[20:23], v[162:165], v[214:217], v[20:23]
	v_mfma_f32_16x16x32_bf16 v[8:11], v[146:149], v[222:225], v[8:11]
	v_mfma_f32_16x16x32_bf16 v[4:7], v[162:165], v[222:225], v[4:7]
	s_setprio 0
	s_setprio 1
	v_mfma_f32_16x16x32_bf16 v[60:63], v[166:169], v[182:185], v[60:63]
	v_mfma_f32_16x16x32_bf16 v[48:51], v[174:177], v[182:185], v[48:51]
	v_mfma_f32_16x16x32_bf16 v[44:47], v[166:169], v[202:205], v[44:47]
	v_mfma_f32_16x16x32_bf16 v[32:35], v[174:177], v[202:205], v[32:35]
	v_mfma_f32_16x16x32_bf16 v[28:31], v[166:169], v[210:213], v[28:31]
	v_mfma_f32_16x16x32_bf16 v[16:19], v[174:177], v[210:213], v[16:19]
	v_mfma_f32_16x16x32_bf16 v[12:15], v[166:169], v[218:221], v[12:15]
	v_mfma_f32_16x16x32_bf16 v[0:3], v[174:177], v[218:221], v[0:3]
	v_mfma_f32_16x16x32_bf16 v[60:63], v[170:173], v[186:189], v[60:63]
	v_mfma_f32_16x16x32_bf16 v[48:51], v[178:181], v[186:189], v[48:51]
	v_mfma_f32_16x16x32_bf16 v[44:47], v[170:173], v[206:209], v[44:47]
	v_mfma_f32_16x16x32_bf16 v[32:35], v[178:181], v[206:209], v[32:35]
	v_mfma_f32_16x16x32_bf16 v[28:31], v[170:173], v[214:217], v[28:31]
	v_mfma_f32_16x16x32_bf16 v[16:19], v[178:181], v[214:217], v[16:19]
	v_mfma_f32_16x16x32_bf16 v[12:15], v[170:173], v[222:225], v[12:15]
	v_mfma_f32_16x16x32_bf16 v[0:3], v[178:181], v[222:225], v[0:3]
	s_setprio 0
	s_barrier
	s_add_i32 s69, s69, 2
	s_add_u32 s92, s92, 0x100
	s_addc_u32 s93, s93, 0
	s_add_u32 s51, s51, 0x100
	s_addc_u32 s68, s68, 0
	s_cmp_lt_u32 s69, 14

.LBB0_417:
	s_add_u32 vcc_lo, s68, 0x30080
	s_addc_u32 vcc_hi, s69, 0
	s_add_u32 s0, s72, 0x100
	s_addc_u32 s1, s73, 0
	s_mov_b32 s2, -2
	ds_read_b128 v[100:103], v116
	ds_read_b128 v[104:107], v116 offset:1024
	ds_read_b128 v[108:111], v116 offset:2048
	ds_read_b128 v[112:115], v116 offset:3072
	ds_read_b128 v[124:127], v117
	ds_read_b128 v[128:131], v117 offset:1024
	ds_read_b128 v[132:135], v117 offset:2048
	ds_read_b128 v[136:139], v117 offset:3072
	s_add_u32 s28, vcc_lo, 0xfffd0080
	s_addc_u32 s29, vcc_hi, -1
	s_cmp_eq_u32 s2, 12
	s_cselect_b32 s29, s71, s29
	s_cselect_b32 s28, s70, s28
	s_cselect_b32 s35, s89, s1
	s_cselect_b32 s34, s88, s0
	v_lshl_add_u64 v[170:171], vcc, 0, v[98:99]
	s_add_i32 m0, s83, 0xc000
	ds_read_b128 v[140:143], v118
	ds_read_b128 v[144:147], v118 offset:1024
	ds_read_b128 v[148:151], v119
	ds_read_b128 v[158:161], v119 offset:1024
	ds_read_b128 v[162:165], v120
	ds_read_b128 v[166:169], v120 offset:1024
	global_load_lds_dwordx4 v[170:171], off
	v_lshl_add_u64 v[170:171], v[170:171], 0, s[8:9]
	s_add_i32 m0, s83, 0xe000
	s_nop 0
	global_load_lds_dwordx4 v[170:171], off
	s_waitcnt vmcnt(8)
	s_waitcnt lgkmcnt(0)
	s_barrier
	s_setprio 1
	s_waitcnt lgkmcnt(0)
	v_mfma_f32_16x16x32_bf16 v[92:95], v[100:103], v[140:143], 0
	v_mfma_f32_16x16x32_bf16 v[88:91], v[108:111], v[140:143], 0
	v_mfma_f32_16x16x32_bf16 v[76:79], v[100:103], v[148:151], 0
	v_mfma_f32_16x16x32_bf16 v[72:75], v[108:111], v[148:151], 0
	v_mfma_f32_16x16x32_bf16 v[60:63], v[100:103], v[162:165], 0
	v_mfma_f32_16x16x32_bf16 v[56:59], v[108:111], v[162:165], 0
	v_mfma_f32_16x16x32_bf16 v[92:95], v[104:107], v[144:147], v[92:95]
	v_mfma_f32_16x16x32_bf16 v[88:91], v[112:115], v[144:147], v[88:91]
	v_mfma_f32_16x16x32_bf16 v[76:79], v[104:107], v[158:161], v[76:79]
	v_mfma_f32_16x16x32_bf16 v[72:75], v[112:115], v[158:161], v[72:75]
	v_mfma_f32_16x16x32_bf16 v[60:63], v[104:107], v[166:169], v[60:63]
	v_mfma_f32_16x16x32_bf16 v[56:59], v[112:115], v[166:169], v[56:59]
	s_setprio 0
	s_setprio 1
	v_mfma_f32_16x16x32_bf16 v[84:87], v[124:127], v[140:143], 0
	v_mfma_f32_16x16x32_bf16 v[80:83], v[132:135], v[140:143], 0
	v_mfma_f32_16x16x32_bf16 v[68:71], v[124:127], v[148:151], 0
	v_mfma_f32_16x16x32_bf16 v[64:67], v[132:135], v[148:151], 0
	v_mfma_f32_16x16x32_bf16 v[52:55], v[124:127], v[162:165], 0
	v_mfma_f32_16x16x32_bf16 v[48:51], v[132:135], v[162:165], 0
	v_mfma_f32_16x16x32_bf16 v[84:87], v[128:131], v[144:147], v[84:87]
	v_mfma_f32_16x16x32_bf16 v[80:83], v[136:139], v[144:147], v[80:83]
	v_mfma_f32_16x16x32_bf16 v[68:71], v[128:131], v[158:161], v[68:71]
	v_mfma_f32_16x16x32_bf16 v[64:67], v[136:139], v[158:161], v[64:67]
	v_mfma_f32_16x16x32_bf16 v[52:55], v[128:131], v[166:169], v[52:55]
	v_mfma_f32_16x16x32_bf16 v[48:51], v[136:139], v[166:169], v[48:51]
	s_setprio 0
	s_barrier
	s_mov_b32 m0, s85
	v_lshl_add_u64 v[170:171], s[34:35], 0, v[96:97]
	ds_read_b128 v[140:143], v118 offset:16384
	ds_read_b128 v[144:147], v118 offset:17408
	ds_read_b128 v[148:151], v119 offset:16384
	ds_read_b128 v[158:161], v119 offset:17408
	ds_read_b128 v[162:165], v120 offset:16384
	ds_read_b128 v[166:169], v120 offset:17408
	global_load_lds_dwordx4 v[170:171], off
	v_lshl_add_u64 v[172:173], v[170:171], 0, s[8:9]
	s_mov_b32 m0, s93
	s_nop 0
	global_load_lds_dwordx4 v[172:173], off
	v_lshl_add_u64 v[172:173], v[170:171], 0, s[10:11]
	s_mov_b32 m0, s95
	s_nop 0
	global_load_lds_dwordx4 v[172:173], off
	v_lshl_add_u64 v[172:173], v[170:171], 0, s[12:13]
	s_mov_b32 m0, s74
	s_nop 0
	global_load_lds_dwordx4 v[172:173], off
	v_lshl_add_u64 v[172:173], s[28:29], 0, v[96:97]
	s_mov_b32 m0, s83
	v_lshl_add_u64 v[174:175], v[172:173], 0, s[8:9]
	global_load_lds_dwordx4 v[172:173], off
	s_mov_b32 m0, s75
	s_nop 0
	global_load_lds_dwordx4 v[174:175], off
	s_waitcnt vmcnt(8)
	s_waitcnt lgkmcnt(0)
	s_barrier
	s_setprio 1
	s_waitcnt lgkmcnt(0)
	v_mfma_f32_16x16x32_bf16 v[44:47], v[100:103], v[140:143], 0
	v_mfma_f32_16x16x32_bf16 v[40:43], v[108:111], v[140:143], 0
	v_mfma_f32_16x16x32_bf16 v[28:31], v[100:103], v[148:151], 0
	v_mfma_f32_16x16x32_bf16 v[24:27], v[108:111], v[148:151], 0
	v_mfma_f32_16x16x32_bf16 v[12:15], v[100:103], v[162:165], 0
	v_mfma_f32_16x16x32_bf16 v[8:11], v[108:111], v[162:165], 0
	v_mfma_f32_16x16x32_bf16 v[44:47], v[104:107], v[144:147], v[44:47]
	v_mfma_f32_16x16x32_bf16 v[40:43], v[112:115], v[144:147], v[40:43]
	v_mfma_f32_16x16x32_bf16 v[28:31], v[104:107], v[158:161], v[28:31]
	v_mfma_f32_16x16x32_bf16 v[24:27], v[112:115], v[158:161], v[24:27]
	v_mfma_f32_16x16x32_bf16 v[12:15], v[104:107], v[166:169], v[12:15]
	v_mfma_f32_16x16x32_bf16 v[8:11], v[112:115], v[166:169], v[8:11]
	s_setprio 0
	s_setprio 1
	v_mfma_f32_16x16x32_bf16 v[36:39], v[124:127], v[140:143], 0
	v_mfma_f32_16x16x32_bf16 v[32:35], v[132:135], v[140:143], 0
	v_mfma_f32_16x16x32_bf16 v[20:23], v[124:127], v[148:151], 0
	v_mfma_f32_16x16x32_bf16 v[16:19], v[132:135], v[148:151], 0
	v_mfma_f32_16x16x32_bf16 v[4:7], v[124:127], v[162:165], 0
	v_mfma_f32_16x16x32_bf16 v[0:3], v[132:135], v[162:165], 0
	v_mfma_f32_16x16x32_bf16 v[36:39], v[128:131], v[144:147], v[36:39]
	v_mfma_f32_16x16x32_bf16 v[32:35], v[136:139], v[144:147], v[32:35]
	v_mfma_f32_16x16x32_bf16 v[20:23], v[128:131], v[158:161], v[20:23]
	v_mfma_f32_16x16x32_bf16 v[16:19], v[136:139], v[158:161], v[16:19]
	v_mfma_f32_16x16x32_bf16 v[4:7], v[128:131], v[166:169], v[4:7]
	v_mfma_f32_16x16x32_bf16 v[0:3], v[136:139], v[166:169], v[0:3]
	s_setprio 0
	s_barrier
	ds_read_b128 v[100:103], v121
	ds_read_b128 v[104:107], v121 offset:1024
	ds_read_b128 v[108:111], v121 offset:2048
	ds_read_b128 v[112:115], v121 offset:3072
	ds_read_b128 v[124:127], v122
	ds_read_b128 v[128:131], v122 offset:1024
	ds_read_b128 v[132:135], v122 offset:2048
	ds_read_b128 v[136:139], v122 offset:3072
	s_mov_b32 m0, s76
	v_lshl_add_u64 v[174:175], v[172:173], 0, s[96:97]
	ds_read_b128 v[140:143], v118 offset:32768
	ds_read_b128 v[144:147], v118 offset:33792
	ds_read_b128 v[148:151], v119 offset:32768
	ds_read_b128 v[158:161], v119 offset:33792
	ds_read_b128 v[162:165], v120 offset:32768
	ds_read_b128 v[166:169], v120 offset:33792
	global_load_lds_dwordx4 v[174:175], off
	v_lshl_add_u64 v[174:175], v[172:173], 0, s[60:61]
	s_mov_b32 m0, s78
	s_nop 0
	global_load_lds_dwordx4 v[174:175], off
	s_waitcnt vmcnt(8)
	s_waitcnt lgkmcnt(0)
	s_barrier
	s_setprio 1
	s_waitcnt lgkmcnt(0)
	v_mfma_f32_16x16x32_bf16 v[92:95], v[100:103], v[140:143], v[92:95]
	v_mfma_f32_16x16x32_bf16 v[88:91], v[108:111], v[140:143], v[88:91]
	v_mfma_f32_16x16x32_bf16 v[76:79], v[100:103], v[148:151], v[76:79]
	v_mfma_f32_16x16x32_bf16 v[72:75], v[108:111], v[148:151], v[72:75]
	v_mfma_f32_16x16x32_bf16 v[60:63], v[100:103], v[162:165], v[60:63]
	v_mfma_f32_16x16x32_bf16 v[56:59], v[108:111], v[162:165], v[56:59]
	v_mfma_f32_16x16x32_bf16 v[92:95], v[104:107], v[144:147], v[92:95]
	v_mfma_f32_16x16x32_bf16 v[88:91], v[112:115], v[144:147], v[88:91]
	v_mfma_f32_16x16x32_bf16 v[76:79], v[104:107], v[158:161], v[76:79]
	v_mfma_f32_16x16x32_bf16 v[72:75], v[112:115], v[158:161], v[72:75]
	v_mfma_f32_16x16x32_bf16 v[60:63], v[104:107], v[166:169], v[60:63]
	v_mfma_f32_16x16x32_bf16 v[56:59], v[112:115], v[166:169], v[56:59]
	s_setprio 0
	s_setprio 1
	v_mfma_f32_16x16x32_bf16 v[84:87], v[124:127], v[140:143], v[84:87]
	v_mfma_f32_16x16x32_bf16 v[80:83], v[132:135], v[140:143], v[80:83]
	v_mfma_f32_16x16x32_bf16 v[68:71], v[124:127], v[148:151], v[68:71]
	v_mfma_f32_16x16x32_bf16 v[64:67], v[132:135], v[148:151], v[64:67]
	v_mfma_f32_16x16x32_bf16 v[52:55], v[124:127], v[162:165], v[52:55]
	v_mfma_f32_16x16x32_bf16 v[48:51], v[132:135], v[162:165], v[48:51]
	v_mfma_f32_16x16x32_bf16 v[84:87], v[128:131], v[144:147], v[84:87]
	v_mfma_f32_16x16x32_bf16 v[80:83], v[136:139], v[144:147], v[80:83]
	v_mfma_f32_16x16x32_bf16 v[68:71], v[128:131], v[158:161], v[68:71]
	v_mfma_f32_16x16x32_bf16 v[64:67], v[136:139], v[158:161], v[64:67]
	v_mfma_f32_16x16x32_bf16 v[52:55], v[128:131], v[166:169], v[52:55]
	v_mfma_f32_16x16x32_bf16 v[48:51], v[136:139], v[166:169], v[48:51]
	s_setprio 0
	s_barrier
	v_lshl_add_u64 v[174:175], v[170:171], 0, s[48:49]
	s_add_i32 m0, s83, 0x18000
	ds_read_b128 v[140:143], v118 offset:49152
	ds_read_b128 v[144:147], v118 offset:50176
	ds_read_b128 v[148:151], v119 offset:49152
	ds_read_b128 v[158:161], v119 offset:50176
	ds_read_b128 v[162:165], v120 offset:49152
	ds_read_b128 v[166:169], v120 offset:50176
	global_load_lds_dwordx4 v[174:175], off
	v_lshl_add_u64 v[174:175], v[170:171], 0, s[14:15]
	s_add_i32 m0, s83, 0x1a000
	s_nop 0
	global_load_lds_dwordx4 v[174:175], off
	v_lshl_add_u64 v[174:175], v[170:171], 0, s[56:57]
	s_add_i32 m0, s83, 0x1c000
	v_lshl_add_u64 v[170:171], v[170:171], 0, s[62:63]
	global_load_lds_dwordx4 v[174:175], off
	s_add_i32 m0, s83, 0x1e000
	s_nop 0
	global_load_lds_dwordx4 v[170:171], off
	v_lshl_add_u64 v[170:171], v[172:173], 0, s[48:49]
	s_mov_b32 m0, s79
	s_nop 0
	global_load_lds_dwordx4 v[170:171], off
	v_lshl_add_u64 v[170:171], v[172:173], 0, s[14:15]
	s_mov_b32 m0, s7
	s_nop 0
	global_load_lds_dwordx4 v[170:171], off
	s_waitcnt vmcnt(8)
	s_waitcnt lgkmcnt(0)
	s_barrier
	s_setprio 1
	s_waitcnt lgkmcnt(0)
	v_mfma_f32_16x16x32_bf16 v[44:47], v[100:103], v[140:143], v[44:47]
	v_mfma_f32_16x16x32_bf16 v[40:43], v[108:111], v[140:143], v[40:43]
	v_mfma_f32_16x16x32_bf16 v[28:31], v[100:103], v[148:151], v[28:31]
	v_mfma_f32_16x16x32_bf16 v[24:27], v[108:111], v[148:151], v[24:27]
	v_mfma_f32_16x16x32_bf16 v[12:15], v[100:103], v[162:165], v[12:15]
	v_mfma_f32_16x16x32_bf16 v[8:11], v[108:111], v[162:165], v[8:11]
	v_mfma_f32_16x16x32_bf16 v[44:47], v[104:107], v[144:147], v[44:47]
	v_mfma_f32_16x16x32_bf16 v[40:43], v[112:115], v[144:147], v[40:43]
	v_mfma_f32_16x16x32_bf16 v[28:31], v[104:107], v[158:161], v[28:31]
	v_mfma_f32_16x16x32_bf16 v[24:27], v[112:115], v[158:161], v[24:27]
	v_mfma_f32_16x16x32_bf16 v[12:15], v[104:107], v[166:169], v[12:15]
	v_mfma_f32_16x16x32_bf16 v[8:11], v[112:115], v[166:169], v[8:11]
	s_setprio 0
	s_setprio 1
	v_mfma_f32_16x16x32_bf16 v[36:39], v[124:127], v[140:143], v[36:39]
	v_mfma_f32_16x16x32_bf16 v[32:35], v[132:135], v[140:143], v[32:35]
	v_mfma_f32_16x16x32_bf16 v[20:23], v[124:127], v[148:151], v[20:23]
	v_mfma_f32_16x16x32_bf16 v[16:19], v[132:135], v[148:151], v[16:19]
	v_mfma_f32_16x16x32_bf16 v[4:7], v[124:127], v[162:165], v[4:7]
	v_mfma_f32_16x16x32_bf16 v[0:3], v[132:135], v[162:165], v[0:3]
	v_mfma_f32_16x16x32_bf16 v[36:39], v[128:131], v[144:147], v[36:39]
	v_mfma_f32_16x16x32_bf16 v[32:35], v[136:139], v[144:147], v[32:35]
	v_mfma_f32_16x16x32_bf16 v[20:23], v[128:131], v[158:161], v[20:23]
	v_mfma_f32_16x16x32_bf16 v[16:19], v[136:139], v[158:161], v[16:19]
	v_mfma_f32_16x16x32_bf16 v[4:7], v[128:131], v[166:169], v[4:7]
	v_mfma_f32_16x16x32_bf16 v[0:3], v[136:139], v[166:169], v[0:3]
	s_setprio 0
	s_barrier
	s_add_i32 s2, s2, 2
	s_add_u32 vcc_lo, vcc_lo, 0x100
	s_addc_u32 vcc_hi, vcc_hi, 0
	s_add_u32 s0, s0, 0x100
	s_addc_u32 s1, s1, 0
	s_cmp_lt_u32 s2, 14

.LBB0_437:
	s_add_u32 s90, s68, 0x30080
	s_addc_u32 s91, s69, 0
	s_add_u32 s47, s72, 0x100
	s_addc_u32 s51, s73, 0
	s_mov_b32 s68, -2
	ds_read_b128 v[108:111], v100
	ds_read_b128 v[112:115], v100 offset:1024
	ds_read_b128 v[116:119], v100 offset:2048
	ds_read_b128 v[120:123], v100 offset:3072
	ds_read_b128 v[124:127], v101
	ds_read_b128 v[128:131], v101 offset:1024
	ds_read_b128 v[132:135], v101 offset:2048
	ds_read_b128 v[136:139], v101 offset:3072
	s_add_u32 s69, s90, 0xfffd0080
	s_addc_u32 s72, s91, -1
	s_cmp_eq_u32 s68, 12
	s_cselect_b32 s73, s53, s72
	s_cselect_b32 s72, s52, s69
	s_cselect_b32 s79, s55, s51
	s_cselect_b32 s78, s54, s47
	v_lshl_add_u64 v[170:171], s[90:91], 0, v[98:99]
	s_add_i32 m0, s33, 0xc000
	ds_read_b128 v[140:143], v102
	ds_read_b128 v[144:147], v102 offset:1024
	ds_read_b128 v[148:151], v103
	ds_read_b128 v[158:161], v103 offset:1024
	ds_read_b128 v[162:165], v104
	ds_read_b128 v[166:169], v104 offset:1024
	global_load_lds_dwordx4 v[170:171], off
	v_lshl_add_u64 v[170:171], v[170:171], 0, s[8:9]
	s_add_i32 m0, s33, 0xe000
	s_nop 0
	global_load_lds_dwordx4 v[170:171], off
	s_waitcnt vmcnt(8)
	s_waitcnt lgkmcnt(0)
	s_barrier
	s_setprio 1
	s_waitcnt lgkmcnt(0)
	v_mfma_f32_16x16x32_bf16 v[92:95], v[108:111], v[140:143], 0
	v_mfma_f32_16x16x32_bf16 v[88:91], v[116:119], v[140:143], 0
	v_mfma_f32_16x16x32_bf16 v[84:87], v[108:111], v[148:151], 0
	v_mfma_f32_16x16x32_bf16 v[80:83], v[116:119], v[148:151], 0
	v_mfma_f32_16x16x32_bf16 v[76:79], v[108:111], v[162:165], 0
	v_mfma_f32_16x16x32_bf16 v[72:75], v[116:119], v[162:165], 0
	v_mfma_f32_16x16x32_bf16 v[92:95], v[112:115], v[144:147], v[92:95]
	v_mfma_f32_16x16x32_bf16 v[88:91], v[120:123], v[144:147], v[88:91]
	v_mfma_f32_16x16x32_bf16 v[84:87], v[112:115], v[158:161], v[84:87]
	v_mfma_f32_16x16x32_bf16 v[80:83], v[120:123], v[158:161], v[80:83]
	v_mfma_f32_16x16x32_bf16 v[76:79], v[112:115], v[166:169], v[76:79]
	v_mfma_f32_16x16x32_bf16 v[72:75], v[120:123], v[166:169], v[72:75]
	s_setprio 0
	s_setprio 1
	v_mfma_f32_16x16x32_bf16 v[68:71], v[124:127], v[140:143], 0
	v_mfma_f32_16x16x32_bf16 v[64:67], v[132:135], v[140:143], 0
	v_mfma_f32_16x16x32_bf16 v[60:63], v[124:127], v[148:151], 0
	v_mfma_f32_16x16x32_bf16 v[56:59], v[132:135], v[148:151], 0
	v_mfma_f32_16x16x32_bf16 v[52:55], v[124:127], v[162:165], 0
	v_mfma_f32_16x16x32_bf16 v[48:51], v[132:135], v[162:165], 0
	v_mfma_f32_16x16x32_bf16 v[68:71], v[128:131], v[144:147], v[68:71]
	v_mfma_f32_16x16x32_bf16 v[64:67], v[136:139], v[144:147], v[64:67]
	v_mfma_f32_16x16x32_bf16 v[60:63], v[128:131], v[158:161], v[60:63]
	v_mfma_f32_16x16x32_bf16 v[56:59], v[136:139], v[158:161], v[56:59]
	v_mfma_f32_16x16x32_bf16 v[52:55], v[128:131], v[166:169], v[52:55]
	v_mfma_f32_16x16x32_bf16 v[48:51], v[136:139], v[166:169], v[48:51]
	s_setprio 0
	s_barrier
	s_mov_b32 m0, s34
	v_lshl_add_u64 v[170:171], s[78:79], 0, v[96:97]
	ds_read_b128 v[140:143], v102 offset:16384
	ds_read_b128 v[144:147], v102 offset:17408
	ds_read_b128 v[148:151], v103 offset:16384
	ds_read_b128 v[158:161], v103 offset:17408
	ds_read_b128 v[162:165], v104 offset:16384
	ds_read_b128 v[166:169], v104 offset:17408
	global_load_lds_dwordx4 v[170:171], off
	v_lshl_add_u64 v[172:173], v[170:171], 0, s[8:9]
	s_mov_b32 m0, s35
	s_nop 0
	global_load_lds_dwordx4 v[172:173], off
	v_lshl_add_u64 v[172:173], v[170:171], 0, s[10:11]
	s_mov_b32 m0, s36
	s_nop 0
	global_load_lds_dwordx4 v[172:173], off
	v_lshl_add_u64 v[172:173], v[170:171], 0, s[12:13]
	s_mov_b32 m0, s37
	s_nop 0
	global_load_lds_dwordx4 v[172:173], off
	v_lshl_add_u64 v[172:173], s[72:73], 0, v[96:97]
	s_mov_b32 m0, s33
	v_lshl_add_u64 v[174:175], v[172:173], 0, s[8:9]
	global_load_lds_dwordx4 v[172:173], off
	s_mov_b32 m0, s38
	s_nop 0
	global_load_lds_dwordx4 v[174:175], off
	s_waitcnt vmcnt(8)
	s_waitcnt lgkmcnt(0)
	s_barrier
	s_setprio 1
	s_waitcnt lgkmcnt(0)
	v_mfma_f32_16x16x32_bf16 v[44:47], v[108:111], v[140:143], 0
	v_mfma_f32_16x16x32_bf16 v[40:43], v[116:119], v[140:143], 0
	v_mfma_f32_16x16x32_bf16 v[36:39], v[108:111], v[148:151], 0
	v_mfma_f32_16x16x32_bf16 v[32:35], v[116:119], v[148:151], 0
	v_mfma_f32_16x16x32_bf16 v[28:31], v[108:111], v[162:165], 0
	v_mfma_f32_16x16x32_bf16 v[24:27], v[116:119], v[162:165], 0
	v_mfma_f32_16x16x32_bf16 v[44:47], v[112:115], v[144:147], v[44:47]
	v_mfma_f32_16x16x32_bf16 v[40:43], v[120:123], v[144:147], v[40:43]
	v_mfma_f32_16x16x32_bf16 v[36:39], v[112:115], v[158:161], v[36:39]
	v_mfma_f32_16x16x32_bf16 v[32:35], v[120:123], v[158:161], v[32:35]
	v_mfma_f32_16x16x32_bf16 v[28:31], v[112:115], v[166:169], v[28:31]
	v_mfma_f32_16x16x32_bf16 v[24:27], v[120:123], v[166:169], v[24:27]
	s_setprio 0
	s_setprio 1
	v_mfma_f32_16x16x32_bf16 v[20:23], v[124:127], v[140:143], 0
	v_mfma_f32_16x16x32_bf16 v[16:19], v[132:135], v[140:143], 0
	v_mfma_f32_16x16x32_bf16 v[12:15], v[124:127], v[148:151], 0
	v_mfma_f32_16x16x32_bf16 v[8:11], v[132:135], v[148:151], 0
	v_mfma_f32_16x16x32_bf16 v[4:7], v[124:127], v[162:165], 0
	v_mfma_f32_16x16x32_bf16 v[0:3], v[132:135], v[162:165], 0
	v_mfma_f32_16x16x32_bf16 v[20:23], v[128:131], v[144:147], v[20:23]
	v_mfma_f32_16x16x32_bf16 v[16:19], v[136:139], v[144:147], v[16:19]
	v_mfma_f32_16x16x32_bf16 v[12:15], v[128:131], v[158:161], v[12:15]
	v_mfma_f32_16x16x32_bf16 v[8:11], v[136:139], v[158:161], v[8:11]
	v_mfma_f32_16x16x32_bf16 v[4:7], v[128:131], v[166:169], v[4:7]
	v_mfma_f32_16x16x32_bf16 v[0:3], v[136:139], v[166:169], v[0:3]
	s_setprio 0
	s_barrier
	ds_read_b128 v[108:111], v105
	ds_read_b128 v[112:115], v105 offset:1024
	ds_read_b128 v[116:119], v105 offset:2048
	ds_read_b128 v[120:123], v105 offset:3072
	ds_read_b128 v[124:127], v106
	ds_read_b128 v[128:131], v106 offset:1024
	ds_read_b128 v[132:135], v106 offset:2048
	ds_read_b128 v[136:139], v106 offset:3072
	s_mov_b32 m0, s39
	v_lshl_add_u64 v[174:175], v[172:173], 0, s[96:97]
	ds_read_b128 v[140:143], v102 offset:32768
	ds_read_b128 v[144:147], v102 offset:33792
	ds_read_b128 v[148:151], v103 offset:32768
	ds_read_b128 v[158:161], v103 offset:33792
	ds_read_b128 v[162:165], v104 offset:32768
	ds_read_b128 v[166:169], v104 offset:33792
	global_load_lds_dwordx4 v[174:175], off
	v_lshl_add_u64 v[174:175], v[172:173], 0, s[60:61]
	s_mov_b32 m0, s71
	s_nop 0
	global_load_lds_dwordx4 v[174:175], off
	s_waitcnt vmcnt(8)
	s_waitcnt lgkmcnt(0)
	s_barrier
	s_setprio 1
	s_waitcnt lgkmcnt(0)
	v_mfma_f32_16x16x32_bf16 v[92:95], v[108:111], v[140:143], v[92:95]
	v_mfma_f32_16x16x32_bf16 v[88:91], v[116:119], v[140:143], v[88:91]
	v_mfma_f32_16x16x32_bf16 v[84:87], v[108:111], v[148:151], v[84:87]
	v_mfma_f32_16x16x32_bf16 v[80:83], v[116:119], v[148:151], v[80:83]
	v_mfma_f32_16x16x32_bf16 v[76:79], v[108:111], v[162:165], v[76:79]
	v_mfma_f32_16x16x32_bf16 v[72:75], v[116:119], v[162:165], v[72:75]
	v_mfma_f32_16x16x32_bf16 v[92:95], v[112:115], v[144:147], v[92:95]
	v_mfma_f32_16x16x32_bf16 v[88:91], v[120:123], v[144:147], v[88:91]
	v_mfma_f32_16x16x32_bf16 v[84:87], v[112:115], v[158:161], v[84:87]
	v_mfma_f32_16x16x32_bf16 v[80:83], v[120:123], v[158:161], v[80:83]
	v_mfma_f32_16x16x32_bf16 v[76:79], v[112:115], v[166:169], v[76:79]
	v_mfma_f32_16x16x32_bf16 v[72:75], v[120:123], v[166:169], v[72:75]
	s_setprio 0
	s_setprio 1
	v_mfma_f32_16x16x32_bf16 v[68:71], v[124:127], v[140:143], v[68:71]
	v_mfma_f32_16x16x32_bf16 v[64:67], v[132:135], v[140:143], v[64:67]
	v_mfma_f32_16x16x32_bf16 v[60:63], v[124:127], v[148:151], v[60:63]
	v_mfma_f32_16x16x32_bf16 v[56:59], v[132:135], v[148:151], v[56:59]
	v_mfma_f32_16x16x32_bf16 v[52:55], v[124:127], v[162:165], v[52:55]
	v_mfma_f32_16x16x32_bf16 v[48:51], v[132:135], v[162:165], v[48:51]
	v_mfma_f32_16x16x32_bf16 v[68:71], v[128:131], v[144:147], v[68:71]
	v_mfma_f32_16x16x32_bf16 v[64:67], v[136:139], v[144:147], v[64:67]
	v_mfma_f32_16x16x32_bf16 v[60:63], v[128:131], v[158:161], v[60:63]
	v_mfma_f32_16x16x32_bf16 v[56:59], v[136:139], v[158:161], v[56:59]
	v_mfma_f32_16x16x32_bf16 v[52:55], v[128:131], v[166:169], v[52:55]
	v_mfma_f32_16x16x32_bf16 v[48:51], v[136:139], v[166:169], v[48:51]
	s_setprio 0
	s_barrier
	v_lshl_add_u64 v[174:175], v[170:171], 0, s[48:49]
	s_add_i32 m0, s33, 0x18000
	ds_read_b128 v[140:143], v102 offset:49152
	ds_read_b128 v[144:147], v102 offset:50176
	ds_read_b128 v[148:151], v103 offset:49152
	ds_read_b128 v[158:161], v103 offset:50176
	ds_read_b128 v[162:165], v104 offset:49152
	ds_read_b128 v[166:169], v104 offset:50176
	global_load_lds_dwordx4 v[174:175], off
	v_lshl_add_u64 v[174:175], v[170:171], 0, s[14:15]
	s_add_i32 m0, s33, 0x1a000
	s_nop 0
	global_load_lds_dwordx4 v[174:175], off
	v_lshl_add_u64 v[174:175], v[170:171], 0, s[56:57]
	s_add_i32 m0, s33, 0x1c000
	v_lshl_add_u64 v[170:171], v[170:171], 0, s[62:63]
	global_load_lds_dwordx4 v[174:175], off
	s_add_i32 m0, s33, 0x1e000
	s_nop 0
	global_load_lds_dwordx4 v[170:171], off
	v_lshl_add_u64 v[170:171], v[172:173], 0, s[48:49]
	s_mov_b32 m0, s74
	s_nop 0
	global_load_lds_dwordx4 v[170:171], off
	v_lshl_add_u64 v[170:171], v[172:173], 0, s[14:15]
	s_mov_b32 m0, s75
	s_nop 0
	global_load_lds_dwordx4 v[170:171], off
	s_waitcnt vmcnt(8)
	s_waitcnt lgkmcnt(0)
	s_barrier
	s_setprio 1
	s_waitcnt lgkmcnt(0)
	v_mfma_f32_16x16x32_bf16 v[44:47], v[108:111], v[140:143], v[44:47]
	v_mfma_f32_16x16x32_bf16 v[40:43], v[116:119], v[140:143], v[40:43]
	v_mfma_f32_16x16x32_bf16 v[36:39], v[108:111], v[148:151], v[36:39]
	v_mfma_f32_16x16x32_bf16 v[32:35], v[116:119], v[148:151], v[32:35]
	v_mfma_f32_16x16x32_bf16 v[28:31], v[108:111], v[162:165], v[28:31]
	v_mfma_f32_16x16x32_bf16 v[24:27], v[116:119], v[162:165], v[24:27]
	v_mfma_f32_16x16x32_bf16 v[44:47], v[112:115], v[144:147], v[44:47]
	v_mfma_f32_16x16x32_bf16 v[40:43], v[120:123], v[144:147], v[40:43]
	v_mfma_f32_16x16x32_bf16 v[36:39], v[112:115], v[158:161], v[36:39]
	v_mfma_f32_16x16x32_bf16 v[32:35], v[120:123], v[158:161], v[32:35]
	v_mfma_f32_16x16x32_bf16 v[28:31], v[112:115], v[166:169], v[28:31]
	v_mfma_f32_16x16x32_bf16 v[24:27], v[120:123], v[166:169], v[24:27]
	s_setprio 0
	s_setprio 1
	v_mfma_f32_16x16x32_bf16 v[20:23], v[124:127], v[140:143], v[20:23]
	v_mfma_f32_16x16x32_bf16 v[16:19], v[132:135], v[140:143], v[16:19]
	v_mfma_f32_16x16x32_bf16 v[12:15], v[124:127], v[148:151], v[12:15]
	v_mfma_f32_16x16x32_bf16 v[8:11], v[132:135], v[148:151], v[8:11]
	v_mfma_f32_16x16x32_bf16 v[4:7], v[124:127], v[162:165], v[4:7]
	v_mfma_f32_16x16x32_bf16 v[0:3], v[132:135], v[162:165], v[0:3]
	v_mfma_f32_16x16x32_bf16 v[20:23], v[128:131], v[144:147], v[20:23]
	v_mfma_f32_16x16x32_bf16 v[16:19], v[136:139], v[144:147], v[16:19]
	v_mfma_f32_16x16x32_bf16 v[12:15], v[128:131], v[158:161], v[12:15]
	v_mfma_f32_16x16x32_bf16 v[8:11], v[136:139], v[158:161], v[8:11]
	v_mfma_f32_16x16x32_bf16 v[4:7], v[128:131], v[166:169], v[4:7]
	v_mfma_f32_16x16x32_bf16 v[0:3], v[136:139], v[166:169], v[0:3]
	s_setprio 0
	s_barrier
	s_add_i32 s68, s68, 2
	s_add_u32 s90, s90, 0x100
	s_addc_u32 s91, s91, 0
	s_add_u32 s47, s47, 0x100
	s_addc_u32 s51, s51, 0
	s_cmp_lt_u32 s68, 14

.LBB0_468:
	s_bitcmp1_b32 s1, 0
	s_cselect_b32 s2, 0x4800, 0
	s_add_i32 s2, s2, 0
	s_mov_b32 s1, 0
	v_add_u32_e32 v211, s2, v177
	v_add3_u32 v212, s2, v179, v181
	v_mad_u32_u24 v242, v204, s87, v211
	v_mov_b32_e32 v243, v212
	v_mov_b32_e32 v232, v210
	v_mov_b32_e32 v233, v213
	ds_read_b128 v[148:151], v242
	ds_read_b128 v[144:147], v242 offset:16
	ds_read_b128 v[136:139], v242 offset:32
	ds_read_b128 v[140:143], v242 offset:48
	ds_read_b128 v[132:135], v243 offset:9216
	ds_read_b128 v[128:131], v243 offset:9248
	ds_read_b128 v[124:127], v243 offset:13824
	ds_read_b128 v[120:123], v243 offset:13856
	s_waitcnt lgkmcnt(4)
	v_mfma_f32_32x32x16_bf16 v[64:79], v[148:151], v[96:99], 0
	v_mfma_f32_32x32x16_bf16 v[64:79], v[144:147], v[112:115], v[64:79]
	v_mfma_f32_32x32x16_bf16 v[64:79], v[136:139], v[100:103], v[64:79]
	v_mfma_f32_32x32x16_bf16 v[64:79], v[140:143], v[116:119], v[64:79]
	s_nop 11
	v_max_f32_e32 v234, v65, v65
	v_max_f32_e32 v235, v64, v64
	v_max_f32_e32 v234, v235, v234
	v_max3_f32 v234, v234, v66, v67
	v_max3_f32 v234, v234, v68, v69
	v_max3_f32 v234, v234, v70, v71
	v_max3_f32 v234, v234, v72, v73
	v_max3_f32 v234, v234, v74, v75
	v_max3_f32 v234, v234, v76, v77
	v_max3_f32 v234, v234, v78, v79
	v_mov_b32_e32 v235, v234
	s_nop 1
	v_permlane32_swap_b32_e32 v234, v235
	v_max_f32_e32 v235, v235, v235
	v_max_f32_e32 v234, v234, v234
	v_max_f32_e32 v234, v234, v235
	v_mul_f32_e32 v234, 0x3e38aa3b, v234
	v_add_f32_e32 v235, 0x41000000, v232
	v_cmp_gt_f32_e32 vcc, v234, v235
	s_nop 1
	v_cndmask_b32_e32 v238, v232, v234, vcc
	v_fma_f32 v64, v64, s77, -v238
	v_exp_f32_e32 v64, v64
	v_fma_f32 v65, v65, s77, -v238
	v_exp_f32_e32 v65, v65
	v_add_f32_e32 v236, 0, v64
	v_fma_f32 v66, v66, s77, -v238
	v_exp_f32_e32 v66, v66
	v_add_f32_e32 v236, v65, v236
	v_fma_f32 v67, v67, s77, -v238
	v_exp_f32_e32 v67, v67
	v_add_f32_e32 v236, v66, v236
	v_fma_f32 v68, v68, s77, -v238
	v_exp_f32_e32 v68, v68
	v_add_f32_e32 v236, v67, v236
	v_fma_f32 v69, v69, s77, -v238
	v_exp_f32_e32 v69, v69
	v_add_f32_e32 v236, v68, v236
	v_fma_f32 v70, v70, s77, -v238
	v_exp_f32_e32 v70, v70
	v_add_f32_e32 v236, v69, v236
	v_fma_f32 v71, v71, s77, -v238
	v_exp_f32_e32 v71, v71
	v_add_f32_e32 v236, v70, v236
	v_mfma_f32_32x32x16_bf16 v[216:231], v[148:151], v[104:107], 0
	v_fma_f32 v72, v72, s77, -v238
	v_exp_f32_e32 v72, v72
	v_add_f32_e32 v236, v71, v236
	v_fma_f32 v73, v73, s77, -v238
	v_exp_f32_e32 v73, v73
	v_add_f32_e32 v236, v72, v236
	v_fma_f32 v74, v74, s77, -v238
	v_exp_f32_e32 v74, v74
	v_mfma_f32_32x32x16_bf16 v[216:231], v[144:147], v[88:91], v[216:231]
	v_add_f32_e32 v236, v73, v236
	v_fma_f32 v75, v75, s77, -v238
	v_exp_f32_e32 v75, v75
	v_add_f32_e32 v236, v74, v236
	v_fma_f32 v76, v76, s77, -v238
	v_exp_f32_e32 v76, v76
	v_add_f32_e32 v236, v75, v236
	v_fma_f32 v77, v77, s77, -v238
	v_mfma_f32_32x32x16_bf16 v[216:231], v[136:139], v[108:111], v[216:231]
	v_exp_f32_e32 v77, v77
	v_add_f32_e32 v236, v76, v236
	v_fma_f32 v78, v78, s77, -v238
	v_exp_f32_e32 v78, v78
	v_add_f32_e32 v236, v77, v236
	v_fma_f32 v79, v79, s77, -v238
	v_exp_f32_e32 v79, v79
	v_add_f32_e32 v236, v78, v236
	v_mfma_f32_32x32x16_bf16 v[216:231], v[140:143], v[92:95], v[216:231]
	v_cmp_neq_f32_e32 vcc, v238, v232
	v_add_f32_e32 v236, v79, v236
	ds_read_b128 v[148:151], v242 offset:4608
	ds_read_b128 v[144:147], v242 offset:4624
	ds_read_b128 v[136:139], v242 offset:4640
	ds_read_b128 v[140:143], v242 offset:4656
	v_mov_b32_e32 v237, v236
	s_nop 1
	v_permlane32_swap_b32_e32 v236, v237
	s_cbranch_vccz .Lat_k0
	v_sub_f32_e32 v240, v232, v238
	v_exp_f32_e32 v240, v240
	s_nop 0
	v_mul_f32_e32 v207, v207, v240
	v_pk_mul_f32 v[32:33], v[32:33], v[240:241] op_sel_hi:[1,0]
	v_pk_mul_f32 v[34:35], v[34:35], v[240:241] op_sel_hi:[1,0]
	v_pk_mul_f32 v[36:37], v[36:37], v[240:241] op_sel_hi:[1,0]
	v_pk_mul_f32 v[38:39], v[38:39], v[240:241] op_sel_hi:[1,0]
	v_pk_mul_f32 v[40:41], v[40:41], v[240:241] op_sel_hi:[1,0]
	v_pk_mul_f32 v[42:43], v[42:43], v[240:241] op_sel_hi:[1,0]
	v_pk_mul_f32 v[44:45], v[44:45], v[240:241] op_sel_hi:[1,0]
	v_pk_mul_f32 v[46:47], v[46:47], v[240:241] op_sel_hi:[1,0]
	v_pk_mul_f32 v[48:49], v[48:49], v[240:241] op_sel_hi:[1,0]
	v_pk_mul_f32 v[50:51], v[50:51], v[240:241] op_sel_hi:[1,0]
	v_pk_mul_f32 v[52:53], v[52:53], v[240:241] op_sel_hi:[1,0]
	v_pk_mul_f32 v[54:55], v[54:55], v[240:241] op_sel_hi:[1,0]
	v_pk_mul_f32 v[56:57], v[56:57], v[240:241] op_sel_hi:[1,0]
	v_pk_mul_f32 v[58:59], v[58:59], v[240:241] op_sel_hi:[1,0]
	v_pk_mul_f32 v[60:61], v[60:61], v[240:241] op_sel_hi:[1,0]
	v_pk_mul_f32 v[62:63], v[62:63], v[240:241] op_sel_hi:[1,0]
.Lat_k0:
	v_cvt_pk_bf16_f32 v64, v64, v65
	v_cvt_pk_bf16_f32 v65, v66, v67
	v_cvt_pk_bf16_f32 v66, v68, v69
	v_cvt_pk_bf16_f32 v67, v70, v71
	v_cvt_pk_bf16_f32 v68, v72, v73
	v_cvt_pk_bf16_f32 v69, v74, v75
	v_cvt_pk_bf16_f32 v70, v76, v77
	v_cvt_pk_bf16_f32 v71, v78, v79
	v_add_f32_e32 v234, v236, v237
	v_add_f32_e32 v207, v234, v207
	v_mov_b32_e32 v232, v238
	v_max_f32_e32 v234, v217, v217
	v_max_f32_e32 v235, v216, v216
	v_max_f32_e32 v234, v235, v234
	v_max3_f32 v234, v234, v218, v219
	s_waitcnt lgkmcnt(4)
	v_mfma_f32_32x32x16_bf16 v[48:63], v[132:135], v[64:67], v[48:63]
	v_max3_f32 v234, v234, v220, v221
	v_max3_f32 v234, v234, v222, v223
	v_max3_f32 v234, v234, v224, v225
	v_max3_f32 v234, v234, v226, v227
	v_max3_f32 v234, v234, v228, v229
	v_max3_f32 v234, v234, v230, v231
	v_mov_b32_e32 v235, v234
	s_nop 1
	v_permlane32_swap_b32_e32 v234, v235
	v_max_f32_e32 v235, v235, v235
	v_mfma_f32_32x32x16_bf16 v[32:47], v[124:127], v[64:67], v[32:47]
	v_max_f32_e32 v234, v234, v234
	v_max_f32_e32 v234, v234, v235
	v_mul_f32_e32 v234, 0x3e38aa3b, v234
	v_add_f32_e32 v235, 0x41000000, v233
	v_cmp_gt_f32_e32 vcc, v234, v235
	s_nop 1
	v_cndmask_b32_e32 v238, v233, v234, vcc
	v_fma_f32 v216, v216, s77, -v238
	v_exp_f32_e32 v216, v216
	v_fma_f32 v217, v217, s77, -v238
	v_mfma_f32_32x32x16_bf16 v[48:63], v[128:131], v[68:71], v[48:63]
	v_exp_f32_e32 v217, v217
	v_add_f32_e32 v236, 0, v216
	v_fma_f32 v218, v218, s77, -v238
	v_exp_f32_e32 v218, v218
	v_add_f32_e32 v236, v217, v236
	v_fma_f32 v219, v219, s77, -v238
	v_exp_f32_e32 v219, v219
	v_add_f32_e32 v236, v218, v236
	v_fma_f32 v220, v220, s77, -v238
	v_exp_f32_e32 v220, v220
	v_mfma_f32_32x32x16_bf16 v[32:47], v[120:123], v[68:71], v[32:47]
	v_add_f32_e32 v236, v219, v236
	v_fma_f32 v221, v221, s77, -v238
	v_exp_f32_e32 v221, v221
	v_add_f32_e32 v236, v220, v236
	v_fma_f32 v222, v222, s77, -v238
	v_exp_f32_e32 v222, v222
	v_add_f32_e32 v236, v221, v236
	v_fma_f32 v223, v223, s77, -v238
	v_exp_f32_e32 v223, v223
	v_add_f32_e32 v236, v222, v236
	s_waitcnt lgkmcnt(0)
	v_mfma_f32_32x32x16_bf16 v[64:79], v[148:151], v[96:99], 0
	v_fma_f32 v224, v224, s77, -v238
	v_exp_f32_e32 v224, v224
	v_add_f32_e32 v236, v223, v236
	v_fma_f32 v225, v225, s77, -v238
	v_exp_f32_e32 v225, v225
	v_add_f32_e32 v236, v224, v236
	v_fma_f32 v226, v226, s77, -v238
	v_exp_f32_e32 v226, v226
	v_mfma_f32_32x32x16_bf16 v[64:79], v[144:147], v[112:115], v[64:79]
	v_add_f32_e32 v236, v225, v236
	v_fma_f32 v227, v227, s77, -v238
	v_exp_f32_e32 v227, v227
	v_add_f32_e32 v236, v226, v236
	v_fma_f32 v228, v228, s77, -v238
	v_exp_f32_e32 v228, v228
	v_add_f32_e32 v236, v227, v236
	v_fma_f32 v229, v229, s77, -v238
	v_mfma_f32_32x32x16_bf16 v[64:79], v[136:139], v[100:103], v[64:79]
	v_exp_f32_e32 v229, v229
	v_add_f32_e32 v236, v228, v236
	v_fma_f32 v230, v230, s77, -v238
	v_exp_f32_e32 v230, v230
	v_add_f32_e32 v236, v229, v236
	v_fma_f32 v231, v231, s77, -v238
	v_exp_f32_e32 v231, v231
	v_add_f32_e32 v236, v230, v236
	v_mfma_f32_32x32x16_bf16 v[64:79], v[140:143], v[116:119], v[64:79]
	v_cmp_neq_f32_e32 vcc, v238, v233
	v_add_f32_e32 v236, v231, v236
	v_mov_b32_e32 v237, v236
	s_nop 1
	v_permlane32_swap_b32_e32 v236, v237
	s_cbranch_vccz .Lat_k1
	v_sub_f32_e32 v240, v233, v238
	v_exp_f32_e32 v240, v240
	s_nop 0
	v_mul_f32_e32 v185, v185, v240
	v_pk_mul_f32 v[0:1], v[0:1], v[240:241] op_sel_hi:[1,0]
	v_pk_mul_f32 v[2:3], v[2:3], v[240:241] op_sel_hi:[1,0]
	v_pk_mul_f32 v[4:5], v[4:5], v[240:241] op_sel_hi:[1,0]
	v_pk_mul_f32 v[6:7], v[6:7], v[240:241] op_sel_hi:[1,0]
	v_pk_mul_f32 v[8:9], v[8:9], v[240:241] op_sel_hi:[1,0]
	v_pk_mul_f32 v[10:11], v[10:11], v[240:241] op_sel_hi:[1,0]
	v_pk_mul_f32 v[12:13], v[12:13], v[240:241] op_sel_hi:[1,0]
	v_pk_mul_f32 v[14:15], v[14:15], v[240:241] op_sel_hi:[1,0]
	v_pk_mul_f32 v[16:17], v[16:17], v[240:241] op_sel_hi:[1,0]
	v_pk_mul_f32 v[18:19], v[18:19], v[240:241] op_sel_hi:[1,0]
	v_pk_mul_f32 v[20:21], v[20:21], v[240:241] op_sel_hi:[1,0]
	v_pk_mul_f32 v[22:23], v[22:23], v[240:241] op_sel_hi:[1,0]
	v_pk_mul_f32 v[24:25], v[24:25], v[240:241] op_sel_hi:[1,0]
	v_pk_mul_f32 v[26:27], v[26:27], v[240:241] op_sel_hi:[1,0]
	v_pk_mul_f32 v[28:29], v[28:29], v[240:241] op_sel_hi:[1,0]
	v_pk_mul_f32 v[30:31], v[30:31], v[240:241] op_sel_hi:[1,0]
.Lat_k1:
	v_cvt_pk_bf16_f32 v216, v216, v217
	v_cvt_pk_bf16_f32 v217, v218, v219
	v_cvt_pk_bf16_f32 v218, v220, v221
	v_cvt_pk_bf16_f32 v219, v222, v223
	v_cvt_pk_bf16_f32 v220, v224, v225
	v_cvt_pk_bf16_f32 v221, v226, v227
	v_cvt_pk_bf16_f32 v222, v228, v229
	v_cvt_pk_bf16_f32 v223, v230, v231
	v_add_f32_e32 v234, v236, v237
	v_add_f32_e32 v185, v234, v185
	v_mov_b32_e32 v233, v238
	v_max_f32_e32 v234, v65, v65
	v_max_f32_e32 v235, v64, v64
	v_max_f32_e32 v234, v235, v234
	v_max3_f32 v234, v234, v66, v67
	v_mfma_f32_32x32x16_bf16 v[16:31], v[132:135], v[216:219], v[16:31]
	v_max3_f32 v234, v234, v68, v69
	v_max3_f32 v234, v234, v70, v71
	v_max3_f32 v234, v234, v72, v73
	v_max3_f32 v234, v234, v74, v75
	v_max3_f32 v234, v234, v76, v77
	v_max3_f32 v234, v234, v78, v79
	v_mov_b32_e32 v235, v234
	s_nop 1
	v_permlane32_swap_b32_e32 v234, v235
	v_max_f32_e32 v235, v235, v235
	v_mfma_f32_32x32x16_bf16 v[0:15], v[124:127], v[216:219], v[0:15]
	v_max_f32_e32 v234, v234, v234
	v_max_f32_e32 v234, v234, v235
	v_mul_f32_e32 v234, 0x3e38aa3b, v234
	v_add_f32_e32 v235, 0x41000000, v232
	v_cmp_gt_f32_e32 vcc, v234, v235
	s_nop 1
	v_cndmask_b32_e32 v238, v232, v234, vcc
	v_fma_f32 v64, v64, s77, -v238
	v_exp_f32_e32 v64, v64
	v_fma_f32 v65, v65, s77, -v238
	v_mfma_f32_32x32x16_bf16 v[16:31], v[128:131], v[220:223], v[16:31]
	v_exp_f32_e32 v65, v65
	v_add_f32_e32 v236, 0, v64
	v_fma_f32 v66, v66, s77, -v238
	v_exp_f32_e32 v66, v66
	v_add_f32_e32 v236, v65, v236
	v_fma_f32 v67, v67, s77, -v238
	v_exp_f32_e32 v67, v67
	v_add_f32_e32 v236, v66, v236
	v_fma_f32 v68, v68, s77, -v238
	v_exp_f32_e32 v68, v68
	v_mfma_f32_32x32x16_bf16 v[0:15], v[120:123], v[220:223], v[0:15]
	v_add_f32_e32 v236, v67, v236
	v_fma_f32 v69, v69, s77, -v238
	ds_read_b128 v[132:135], v243 offset:9280
	ds_read_b128 v[128:131], v243 offset:9312
	ds_read_b128 v[124:127], v243 offset:13888
	ds_read_b128 v[120:123], v243 offset:13920
	v_exp_f32_e32 v69, v69
	v_add_f32_e32 v236, v68, v236
	v_fma_f32 v70, v70, s77, -v238
	v_exp_f32_e32 v70, v70
	v_add_f32_e32 v236, v69, v236
	v_fma_f32 v71, v71, s77, -v238
	v_exp_f32_e32 v71, v71
	v_add_f32_e32 v236, v70, v236
	v_mfma_f32_32x32x16_bf16 v[216:231], v[148:151], v[104:107], 0
	v_fma_f32 v72, v72, s77, -v238
	v_exp_f32_e32 v72, v72
	v_add_f32_e32 v236, v71, v236
	v_fma_f32 v73, v73, s77, -v238
	v_exp_f32_e32 v73, v73
	v_add_f32_e32 v236, v72, v236
	v_fma_f32 v74, v74, s77, -v238
	v_exp_f32_e32 v74, v74
	v_mfma_f32_32x32x16_bf16 v[216:231], v[144:147], v[88:91], v[216:231]
	v_add_f32_e32 v236, v73, v236
	v_fma_f32 v75, v75, s77, -v238
	v_exp_f32_e32 v75, v75
	v_add_f32_e32 v236, v74, v236
	v_fma_f32 v76, v76, s77, -v238
	v_exp_f32_e32 v76, v76
	v_add_f32_e32 v236, v75, v236
	v_fma_f32 v77, v77, s77, -v238
	v_mfma_f32_32x32x16_bf16 v[216:231], v[136:139], v[108:111], v[216:231]
	v_exp_f32_e32 v77, v77
	v_add_f32_e32 v236, v76, v236
	v_fma_f32 v78, v78, s77, -v238
	v_exp_f32_e32 v78, v78
	v_add_f32_e32 v236, v77, v236
	v_fma_f32 v79, v79, s77, -v238
	v_exp_f32_e32 v79, v79
	v_add_f32_e32 v236, v78, v236
	v_mfma_f32_32x32x16_bf16 v[216:231], v[140:143], v[92:95], v[216:231]
	v_cmp_neq_f32_e32 vcc, v238, v232
	v_add_f32_e32 v236, v79, v236
	v_mov_b32_e32 v237, v236
	s_nop 1
	v_permlane32_swap_b32_e32 v236, v237
	s_cbranch_vccz .Lat_k2
	v_sub_f32_e32 v240, v232, v238
	v_exp_f32_e32 v240, v240
	s_nop 0
	v_mul_f32_e32 v207, v207, v240
	v_pk_mul_f32 v[32:33], v[32:33], v[240:241] op_sel_hi:[1,0]
	v_pk_mul_f32 v[34:35], v[34:35], v[240:241] op_sel_hi:[1,0]
	v_pk_mul_f32 v[36:37], v[36:37], v[240:241] op_sel_hi:[1,0]
	v_pk_mul_f32 v[38:39], v[38:39], v[240:241] op_sel_hi:[1,0]
	v_pk_mul_f32 v[40:41], v[40:41], v[240:241] op_sel_hi:[1,0]
	v_pk_mul_f32 v[42:43], v[42:43], v[240:241] op_sel_hi:[1,0]
	v_pk_mul_f32 v[44:45], v[44:45], v[240:241] op_sel_hi:[1,0]
	v_pk_mul_f32 v[46:47], v[46:47], v[240:241] op_sel_hi:[1,0]
	v_pk_mul_f32 v[48:49], v[48:49], v[240:241] op_sel_hi:[1,0]
	v_pk_mul_f32 v[50:51], v[50:51], v[240:241] op_sel_hi:[1,0]
	v_pk_mul_f32 v[52:53], v[52:53], v[240:241] op_sel_hi:[1,0]
	v_pk_mul_f32 v[54:55], v[54:55], v[240:241] op_sel_hi:[1,0]
	v_pk_mul_f32 v[56:57], v[56:57], v[240:241] op_sel_hi:[1,0]
	v_pk_mul_f32 v[58:59], v[58:59], v[240:241] op_sel_hi:[1,0]
	v_pk_mul_f32 v[60:61], v[60:61], v[240:241] op_sel_hi:[1,0]
	v_pk_mul_f32 v[62:63], v[62:63], v[240:241] op_sel_hi:[1,0]
.Lat_k2:
	v_cvt_pk_bf16_f32 v64, v64, v65
	v_cvt_pk_bf16_f32 v65, v66, v67
	v_cvt_pk_bf16_f32 v66, v68, v69
	v_cvt_pk_bf16_f32 v67, v70, v71
	v_cvt_pk_bf16_f32 v68, v72, v73
	v_cvt_pk_bf16_f32 v69, v74, v75
	v_cvt_pk_bf16_f32 v70, v76, v77
	v_cvt_pk_bf16_f32 v71, v78, v79
	v_add_f32_e32 v234, v236, v237
	v_add_f32_e32 v207, v234, v207
	v_mov_b32_e32 v232, v238
	v_max_f32_e32 v234, v217, v217
	v_max_f32_e32 v235, v216, v216
	v_max_f32_e32 v234, v235, v234
	v_max3_f32 v234, v234, v218, v219
	s_waitcnt lgkmcnt(0)
	v_mfma_f32_32x32x16_bf16 v[48:63], v[132:135], v[64:67], v[48:63]
	v_max3_f32 v234, v234, v220, v221
	v_max3_f32 v234, v234, v222, v223
	v_max3_f32 v234, v234, v224, v225
	v_max3_f32 v234, v234, v226, v227
	v_max3_f32 v234, v234, v228, v229
	v_max3_f32 v234, v234, v230, v231
	v_mov_b32_e32 v235, v234
	s_nop 1
	v_permlane32_swap_b32_e32 v234, v235
	v_max_f32_e32 v235, v235, v235
	v_mfma_f32_32x32x16_bf16 v[32:47], v[124:127], v[64:67], v[32:47]
	v_max_f32_e32 v234, v234, v234
	v_max_f32_e32 v234, v234, v235
	v_mul_f32_e32 v234, 0x3e38aa3b, v234
	v_add_f32_e32 v235, 0x41000000, v233
	v_cmp_gt_f32_e32 vcc, v234, v235
	s_nop 1
	v_cndmask_b32_e32 v238, v233, v234, vcc
	v_fma_f32 v216, v216, s77, -v238
	v_exp_f32_e32 v216, v216
	v_fma_f32 v217, v217, s77, -v238
	v_mfma_f32_32x32x16_bf16 v[48:63], v[128:131], v[68:71], v[48:63]
	v_exp_f32_e32 v217, v217
	v_add_f32_e32 v236, 0, v216
	v_fma_f32 v218, v218, s77, -v238
	v_exp_f32_e32 v218, v218
	v_add_f32_e32 v236, v217, v236
	v_fma_f32 v219, v219, s77, -v238
	v_exp_f32_e32 v219, v219
	v_add_f32_e32 v236, v218, v236
	v_fma_f32 v220, v220, s77, -v238
	v_exp_f32_e32 v220, v220
	v_mfma_f32_32x32x16_bf16 v[32:47], v[120:123], v[68:71], v[32:47]
	v_add_f32_e32 v236, v219, v236
	v_fma_f32 v221, v221, s77, -v238
	v_exp_f32_e32 v221, v221
	v_add_f32_e32 v236, v220, v236
	v_fma_f32 v222, v222, s77, -v238
	v_exp_f32_e32 v222, v222
	v_add_f32_e32 v236, v221, v236
	v_fma_f32 v223, v223, s77, -v238
	v_exp_f32_e32 v223, v223
	v_add_f32_e32 v236, v222, v236
	v_fma_f32 v224, v224, s77, -v238
	v_exp_f32_e32 v224, v224
	v_add_f32_e32 v236, v223, v236
	v_fma_f32 v225, v225, s77, -v238
	v_exp_f32_e32 v225, v225
	v_add_f32_e32 v236, v224, v236
	v_fma_f32 v226, v226, s77, -v238
	v_exp_f32_e32 v226, v226
	v_add_f32_e32 v236, v225, v236
	v_fma_f32 v227, v227, s77, -v238
	v_exp_f32_e32 v227, v227
	v_add_f32_e32 v236, v226, v236
	v_fma_f32 v228, v228, s77, -v238
	v_exp_f32_e32 v228, v228
	v_add_f32_e32 v236, v227, v236
	v_fma_f32 v229, v229, s77, -v238
	v_exp_f32_e32 v229, v229
	v_add_f32_e32 v236, v228, v236
	v_fma_f32 v230, v230, s77, -v238
	v_exp_f32_e32 v230, v230
	v_add_f32_e32 v236, v229, v236
	v_fma_f32 v231, v231, s77, -v238
	v_exp_f32_e32 v231, v231
	v_add_f32_e32 v236, v230, v236
	v_cmp_neq_f32_e32 vcc, v238, v233
	v_add_f32_e32 v236, v231, v236
	v_mov_b32_e32 v237, v236
	s_nop 1
	v_permlane32_swap_b32_e32 v236, v237
	s_cbranch_vccz .Lat_k3
	v_sub_f32_e32 v240, v233, v238
	v_exp_f32_e32 v240, v240
	s_nop 0
	v_mul_f32_e32 v185, v185, v240
	v_pk_mul_f32 v[0:1], v[0:1], v[240:241] op_sel_hi:[1,0]
	v_pk_mul_f32 v[2:3], v[2:3], v[240:241] op_sel_hi:[1,0]
	v_pk_mul_f32 v[4:5], v[4:5], v[240:241] op_sel_hi:[1,0]
	v_pk_mul_f32 v[6:7], v[6:7], v[240:241] op_sel_hi:[1,0]
	v_pk_mul_f32 v[8:9], v[8:9], v[240:241] op_sel_hi:[1,0]
	v_pk_mul_f32 v[10:11], v[10:11], v[240:241] op_sel_hi:[1,0]
	v_pk_mul_f32 v[12:13], v[12:13], v[240:241] op_sel_hi:[1,0]
	v_pk_mul_f32 v[14:15], v[14:15], v[240:241] op_sel_hi:[1,0]
	v_pk_mul_f32 v[16:17], v[16:17], v[240:241] op_sel_hi:[1,0]
	v_pk_mul_f32 v[18:19], v[18:19], v[240:241] op_sel_hi:[1,0]
	v_pk_mul_f32 v[20:21], v[20:21], v[240:241] op_sel_hi:[1,0]
	v_pk_mul_f32 v[22:23], v[22:23], v[240:241] op_sel_hi:[1,0]
	v_pk_mul_f32 v[24:25], v[24:25], v[240:241] op_sel_hi:[1,0]
	v_pk_mul_f32 v[26:27], v[26:27], v[240:241] op_sel_hi:[1,0]
	v_pk_mul_f32 v[28:29], v[28:29], v[240:241] op_sel_hi:[1,0]
	v_pk_mul_f32 v[30:31], v[30:31], v[240:241] op_sel_hi:[1,0]
.Lat_k3:
	v_cvt_pk_bf16_f32 v216, v216, v217
	v_cvt_pk_bf16_f32 v217, v218, v219
	v_cvt_pk_bf16_f32 v218, v220, v221
	v_cvt_pk_bf16_f32 v219, v222, v223
	v_cvt_pk_bf16_f32 v220, v224, v225
	v_cvt_pk_bf16_f32 v221, v226, v227
	v_cvt_pk_bf16_f32 v222, v228, v229
	v_cvt_pk_bf16_f32 v223, v230, v231
	v_add_f32_e32 v234, v236, v237
	v_add_f32_e32 v185, v234, v185
	v_mov_b32_e32 v233, v238
	v_mfma_f32_32x32x16_bf16 v[16:31], v[132:135], v[216:219], v[16:31]
	v_mfma_f32_32x32x16_bf16 v[0:15], v[124:127], v[216:219], v[0:15]
	v_mfma_f32_32x32x16_bf16 v[16:31], v[128:131], v[220:223], v[16:31]
	v_mfma_f32_32x32x16_bf16 v[0:15], v[120:123], v[220:223], v[0:15]
	v_mov_b32_e32 v193, v232
	v_mov_b32_e32 v210, v233

.LBB0_517:
	s_or_b64 exec, exec, s[42:43]
	v_readlane_b32 s18, v255, 17
	s_lshl_b32 s28, s18, 1
	s_add_u32 s50, s58, 0xa10000
	v_readlane_b32 s16, v254, 30
	s_addc_u32 s51, s59, 0
	s_add_i32 s29, s16, s2
	v_lshl_add_u64 v[10:11], v[0:1], 0, s[48:49]
	s_mov_b32 m0, s29
	s_waitcnt vmcnt(2)
	s_barrier
	global_load_lds_dwordx4 v[10:11], off
	v_lshl_add_u64 v[10:11], v[0:1], 0, s[14:15]
	s_add_i32 m0, s29, 0x2000
	s_add_i32 s34, s85, 0x8000
	global_load_lds_dwordx4 v[10:11], off
	v_lshl_add_u64 v[10:11], v[2:3], 0, s[48:49]
	s_mov_b32 m0, s34
	s_add_i32 s35, s85, 0xa000
	v_readlane_b32 s17, v254, 31
	global_load_lds_dwordx4 v[10:11], off
	v_lshl_add_u64 v[2:3], v[2:3], 0, s[14:15]
	s_mov_b32 m0, s35
	s_add_i32 s2, s17, s2
	global_load_lds_dwordx4 v[2:3], off
	v_lshl_add_u64 v[2:3], v[0:1], 0, s[56:57]
	s_mov_b32 m0, s2
	v_lshl_add_u64 v[0:1], v[0:1], 0, s[62:63]
	global_load_lds_dwordx4 v[2:3], off
	s_add_i32 m0, s2, 0x2000
	v_lshlrev_b32_e32 v2, 2, v4
	global_load_lds_dwordx4 v[0:1], off
	v_and_b32_e32 v0, 15, v4
	v_and_b32_e32 v1, 48, v4
	v_lshlrev_b32_e32 v0, 6, v0
	v_and_b32_e32 v2, 32, v2
	v_bitop3_b32 v0, v0, v2, v1 bitop3:0x36
	s_add_i32 s2, 0, 0x10000
	v_add_u32_e32 v3, s2, v0
	s_add_i32 s2, 0, 0x14000
	v_add_u32_e32 v10, s2, v0
	s_movk_i32 s2, 0x100
	v_cmp_gt_u32_e64 s[42:43], s2, v9
	v_lshlrev_b32_e32 v4, 6, v4
	s_movk_i32 s2, 0x3c0
	v_and_or_b32 v1, v4, s2, v1
	s_max_u32 s2, s28, 1
	s_lshl_b32 s2, s2, 10
	v_mul_i32_i24_e32 v11, 48, v8
	s_addk_i32 s2, 0xfc00
	v_lshlrev_b32_e32 v11, 7, v11
	s_add_u32 s52, s58, 0x910000
	v_add_u32_e32 v12, s16, v0
	v_add_u32_e32 v13, s17, v0
	v_xad_u32 v1, v1, v2, 0
	v_add_u32_e32 v2, 0x800, v11
	v_add_u32_e32 v4, 0x1000, v11
	s_addc_u32 s53, s59, 0
	s_lshl_b64 s[66:67], s[2:3], 2
	v_readlane_b32 s16, v255, 9
	v_lshlrev_b32_e32 v11, 14, v5
	v_readlane_b32 s17, v255, 10
	s_add_u32 s54, s16, s66
	v_and_b32_e32 v11, 0xffff8000, v11
	s_waitcnt vmcnt(6)
	v_lshlrev_b32_e32 v9, 6, v9
	s_addc_u32 s55, s17, s67
	v_readlane_b32 s16, v255, 11
	v_lshl_add_u32 v6, v6, 11, v11
	v_and_b32_e32 v5, 1, v5
	v_and_b32_e32 v9, 0x3000, v9
	v_add_u32_e32 v0, 0, v0
	v_mul_i32_i24_e32 v8, 0x1800, v8
	v_readlane_b32 s17, v255, 12
	s_add_u32 s66, s16, s66
	v_lshl_or_b32 v5, v5, 6, v6
	s_mul_i32 s28, s18, 9
	s_addc_u32 s67, s17, s67
	v_lshl_add_u32 v114, v7, 1, v5
	v_mov_b32_e32 v115, v153
	v_add_u32_e32 v136, v3, v9
	v_add_u32_e32 v137, v10, v9
	v_add_u32_e32 v138, v0, v8
	v_add_u32_e32 v139, v1, v2
	v_add_u32_e32 v140, v1, v4
	v_add_u32_e32 v141, v12, v9
	v_add_u32_e32 v142, v13, v9
	s_mov_b64 s[72:73], s[90:91]
	s_mov_b64 s[88:89], s[46:47]
	s_barrier
	s_branch .LBB0_520
.Ltramp1:
	s_branch .LBB0_1255
.LBB0_518:
	s_or_b64 exec, exec, s[44:45]
	s_mov_b64 s[44:45], 0

.LBB0_522:
	s_add_u32 s46, s46, 0x30080
	s_addc_u32 s47, s47, 0
	s_add_u32 s2, s90, 0x100
	s_addc_u32 s29, s91, 0
	s_mov_b32 s45, -2
	ds_read_b128 v[96:99], v136
	ds_read_b128 v[100:103], v136 offset:1024
	ds_read_b128 v[104:107], v136 offset:2048
	ds_read_b128 v[108:111], v136 offset:3072
	ds_read_b128 v[116:119], v137
	ds_read_b128 v[120:123], v137 offset:1024
	ds_read_b128 v[124:127], v137 offset:2048
	ds_read_b128 v[128:131], v137 offset:3072
	s_add_u32 s69, s46, 0xfffd0080
	s_addc_u32 s71, s47, -1
	s_cmp_eq_u32 s45, 12
	s_cselect_b32 s75, s89, s71
	s_cselect_b32 s74, s88, s69
	s_cselect_b32 s91, s73, s29
	s_cselect_b32 s90, s72, s2
	v_lshl_add_u64 v[170:171], s[46:47], 0, v[114:115]
	s_add_i32 m0, s85, 0xc000
	ds_read_b128 v[132:135], v138
	ds_read_b128 v[144:147], v138 offset:1024
	ds_read_b128 v[148:151], v139
	ds_read_b128 v[158:161], v139 offset:1024
	ds_read_b128 v[162:165], v140
	ds_read_b128 v[166:169], v140 offset:1024
	global_load_lds_dwordx4 v[170:171], off
	v_lshl_add_u64 v[170:171], v[170:171], 0, s[8:9]
	s_add_i32 m0, s85, 0xe000
	s_nop 0
	global_load_lds_dwordx4 v[170:171], off
	s_waitcnt vmcnt(8)
	s_waitcnt lgkmcnt(0)
	s_barrier
	s_setprio 1
	s_waitcnt lgkmcnt(0)
	v_mfma_f32_16x16x32_bf16 v[92:95], v[96:99], v[132:135], 0
	v_mfma_f32_16x16x32_bf16 v[88:91], v[104:107], v[132:135], 0
	v_mfma_f32_16x16x32_bf16 v[76:79], v[96:99], v[148:151], 0
	v_mfma_f32_16x16x32_bf16 v[72:75], v[104:107], v[148:151], 0
	v_mfma_f32_16x16x32_bf16 v[60:63], v[96:99], v[162:165], 0
	v_mfma_f32_16x16x32_bf16 v[56:59], v[104:107], v[162:165], 0
	v_mfma_f32_16x16x32_bf16 v[92:95], v[100:103], v[144:147], v[92:95]
	v_mfma_f32_16x16x32_bf16 v[88:91], v[108:111], v[144:147], v[88:91]
	v_mfma_f32_16x16x32_bf16 v[76:79], v[100:103], v[158:161], v[76:79]
	v_mfma_f32_16x16x32_bf16 v[72:75], v[108:111], v[158:161], v[72:75]
	v_mfma_f32_16x16x32_bf16 v[60:63], v[100:103], v[166:169], v[60:63]
	v_mfma_f32_16x16x32_bf16 v[56:59], v[108:111], v[166:169], v[56:59]
	s_setprio 0
	s_setprio 1
	v_mfma_f32_16x16x32_bf16 v[84:87], v[116:119], v[132:135], 0
	v_mfma_f32_16x16x32_bf16 v[80:83], v[124:127], v[132:135], 0
	v_mfma_f32_16x16x32_bf16 v[68:71], v[116:119], v[148:151], 0
	v_mfma_f32_16x16x32_bf16 v[64:67], v[124:127], v[148:151], 0
	v_mfma_f32_16x16x32_bf16 v[52:55], v[116:119], v[162:165], 0
	v_mfma_f32_16x16x32_bf16 v[48:51], v[124:127], v[162:165], 0
	v_mfma_f32_16x16x32_bf16 v[84:87], v[120:123], v[144:147], v[84:87]
	v_mfma_f32_16x16x32_bf16 v[80:83], v[128:131], v[144:147], v[80:83]
	v_mfma_f32_16x16x32_bf16 v[68:71], v[120:123], v[158:161], v[68:71]
	v_mfma_f32_16x16x32_bf16 v[64:67], v[128:131], v[158:161], v[64:67]
	v_mfma_f32_16x16x32_bf16 v[52:55], v[120:123], v[166:169], v[52:55]
	v_mfma_f32_16x16x32_bf16 v[48:51], v[128:131], v[166:169], v[48:51]
	s_setprio 0
	s_barrier
	s_mov_b32 m0, s95
	v_lshl_add_u64 v[170:171], s[90:91], 0, v[112:113]
	ds_read_b128 v[132:135], v138 offset:16384
	ds_read_b128 v[144:147], v138 offset:17408
	ds_read_b128 v[148:151], v139 offset:16384
	ds_read_b128 v[158:161], v139 offset:17408
	ds_read_b128 v[162:165], v140 offset:16384
	ds_read_b128 v[166:169], v140 offset:17408
	global_load_lds_dwordx4 v[170:171], off
	v_lshl_add_u64 v[172:173], v[170:171], 0, s[8:9]
	s_mov_b32 m0, s36
	s_nop 0
	global_load_lds_dwordx4 v[172:173], off
	v_lshl_add_u64 v[172:173], v[170:171], 0, s[10:11]
	s_mov_b32 m0, s37
	s_nop 0
	global_load_lds_dwordx4 v[172:173], off
	v_lshl_add_u64 v[172:173], v[170:171], 0, s[12:13]
	s_mov_b32 m0, s38
	s_nop 0
	global_load_lds_dwordx4 v[172:173], off
	v_lshl_add_u64 v[172:173], s[74:75], 0, v[112:113]
	s_mov_b32 m0, s85
	v_lshl_add_u64 v[174:175], v[172:173], 0, s[8:9]
	global_load_lds_dwordx4 v[172:173], off
	s_mov_b32 m0, s39
	s_nop 0
	global_load_lds_dwordx4 v[174:175], off
	s_waitcnt vmcnt(8)
	s_waitcnt lgkmcnt(0)
	s_barrier
	s_setprio 1
	s_waitcnt lgkmcnt(0)
	v_mfma_f32_16x16x32_bf16 v[44:47], v[96:99], v[132:135], 0
	v_mfma_f32_16x16x32_bf16 v[40:43], v[104:107], v[132:135], 0
	v_mfma_f32_16x16x32_bf16 v[28:31], v[96:99], v[148:151], 0
	v_mfma_f32_16x16x32_bf16 v[24:27], v[104:107], v[148:151], 0
	v_mfma_f32_16x16x32_bf16 v[12:15], v[96:99], v[162:165], 0
	v_mfma_f32_16x16x32_bf16 v[8:11], v[104:107], v[162:165], 0
	v_mfma_f32_16x16x32_bf16 v[44:47], v[100:103], v[144:147], v[44:47]
	v_mfma_f32_16x16x32_bf16 v[40:43], v[108:111], v[144:147], v[40:43]
	v_mfma_f32_16x16x32_bf16 v[28:31], v[100:103], v[158:161], v[28:31]
	v_mfma_f32_16x16x32_bf16 v[24:27], v[108:111], v[158:161], v[24:27]
	v_mfma_f32_16x16x32_bf16 v[12:15], v[100:103], v[166:169], v[12:15]
	v_mfma_f32_16x16x32_bf16 v[8:11], v[108:111], v[166:169], v[8:11]
	s_setprio 0
	s_setprio 1
	v_mfma_f32_16x16x32_bf16 v[36:39], v[116:119], v[132:135], 0
	v_mfma_f32_16x16x32_bf16 v[32:35], v[124:127], v[132:135], 0
	v_mfma_f32_16x16x32_bf16 v[20:23], v[116:119], v[148:151], 0
	v_mfma_f32_16x16x32_bf16 v[16:19], v[124:127], v[148:151], 0
	v_mfma_f32_16x16x32_bf16 v[4:7], v[116:119], v[162:165], 0
	v_mfma_f32_16x16x32_bf16 v[0:3], v[124:127], v[162:165], 0
	v_mfma_f32_16x16x32_bf16 v[36:39], v[120:123], v[144:147], v[36:39]
	v_mfma_f32_16x16x32_bf16 v[32:35], v[128:131], v[144:147], v[32:35]
	v_mfma_f32_16x16x32_bf16 v[20:23], v[120:123], v[158:161], v[20:23]
	v_mfma_f32_16x16x32_bf16 v[16:19], v[128:131], v[158:161], v[16:19]
	v_mfma_f32_16x16x32_bf16 v[4:7], v[120:123], v[166:169], v[4:7]
	v_mfma_f32_16x16x32_bf16 v[0:3], v[128:131], v[166:169], v[0:3]
	s_setprio 0
	s_barrier
	ds_read_b128 v[96:99], v141
	ds_read_b128 v[100:103], v141 offset:1024
	ds_read_b128 v[104:107], v141 offset:2048
	ds_read_b128 v[108:111], v141 offset:3072
	ds_read_b128 v[116:119], v142
	ds_read_b128 v[120:123], v142 offset:1024
	ds_read_b128 v[124:127], v142 offset:2048
	ds_read_b128 v[128:131], v142 offset:3072
	s_mov_b32 m0, s0
	v_lshl_add_u64 v[174:175], v[172:173], 0, s[96:97]
	ds_read_b128 v[132:135], v138 offset:32768
	ds_read_b128 v[144:147], v138 offset:33792
	ds_read_b128 v[148:151], v139 offset:32768
	ds_read_b128 v[158:161], v139 offset:33792
	ds_read_b128 v[162:165], v140 offset:32768
	ds_read_b128 v[166:169], v140 offset:33792
	global_load_lds_dwordx4 v[174:175], off
	v_lshl_add_u64 v[174:175], v[172:173], 0, s[60:61]
	s_mov_b32 m0, s1
	s_nop 0
	global_load_lds_dwordx4 v[174:175], off
	s_waitcnt vmcnt(8)
	s_waitcnt lgkmcnt(0)
	s_barrier
	s_setprio 1
	s_waitcnt lgkmcnt(0)
	v_mfma_f32_16x16x32_bf16 v[92:95], v[96:99], v[132:135], v[92:95]
	v_mfma_f32_16x16x32_bf16 v[88:91], v[104:107], v[132:135], v[88:91]
	v_mfma_f32_16x16x32_bf16 v[76:79], v[96:99], v[148:151], v[76:79]
	v_mfma_f32_16x16x32_bf16 v[72:75], v[104:107], v[148:151], v[72:75]
	v_mfma_f32_16x16x32_bf16 v[60:63], v[96:99], v[162:165], v[60:63]
	v_mfma_f32_16x16x32_bf16 v[56:59], v[104:107], v[162:165], v[56:59]
	v_mfma_f32_16x16x32_bf16 v[92:95], v[100:103], v[144:147], v[92:95]
	v_mfma_f32_16x16x32_bf16 v[88:91], v[108:111], v[144:147], v[88:91]
	v_mfma_f32_16x16x32_bf16 v[76:79], v[100:103], v[158:161], v[76:79]
	v_mfma_f32_16x16x32_bf16 v[72:75], v[108:111], v[158:161], v[72:75]
	v_mfma_f32_16x16x32_bf16 v[60:63], v[100:103], v[166:169], v[60:63]
	v_mfma_f32_16x16x32_bf16 v[56:59], v[108:111], v[166:169], v[56:59]
	s_setprio 0
	s_setprio 1
	v_mfma_f32_16x16x32_bf16 v[84:87], v[116:119], v[132:135], v[84:87]
	v_mfma_f32_16x16x32_bf16 v[80:83], v[124:127], v[132:135], v[80:83]
	v_mfma_f32_16x16x32_bf16 v[68:71], v[116:119], v[148:151], v[68:71]
	v_mfma_f32_16x16x32_bf16 v[64:67], v[124:127], v[148:151], v[64:67]
	v_mfma_f32_16x16x32_bf16 v[52:55], v[116:119], v[162:165], v[52:55]
	v_mfma_f32_16x16x32_bf16 v[48:51], v[124:127], v[162:165], v[48:51]
	v_mfma_f32_16x16x32_bf16 v[84:87], v[120:123], v[144:147], v[84:87]
	v_mfma_f32_16x16x32_bf16 v[80:83], v[128:131], v[144:147], v[80:83]
	v_mfma_f32_16x16x32_bf16 v[68:71], v[120:123], v[158:161], v[68:71]
	v_mfma_f32_16x16x32_bf16 v[64:67], v[128:131], v[158:161], v[64:67]
	v_mfma_f32_16x16x32_bf16 v[52:55], v[120:123], v[166:169], v[52:55]
	v_mfma_f32_16x16x32_bf16 v[48:51], v[128:131], v[166:169], v[48:51]
	s_setprio 0
	s_barrier
	v_lshl_add_u64 v[174:175], v[170:171], 0, s[48:49]
	s_add_i32 m0, s85, 0x18000
	ds_read_b128 v[132:135], v138 offset:49152
	ds_read_b128 v[144:147], v138 offset:50176
	ds_read_b128 v[148:151], v139 offset:49152
	ds_read_b128 v[158:161], v139 offset:50176
	ds_read_b128 v[162:165], v140 offset:49152
	ds_read_b128 v[166:169], v140 offset:50176
	global_load_lds_dwordx4 v[174:175], off
	v_lshl_add_u64 v[174:175], v[170:171], 0, s[14:15]
	s_add_i32 m0, s85, 0x1a000
	s_nop 0
	global_load_lds_dwordx4 v[174:175], off
	v_lshl_add_u64 v[174:175], v[170:171], 0, s[56:57]
	s_add_i32 m0, s85, 0x1c000
	v_lshl_add_u64 v[170:171], v[170:171], 0, s[62:63]
	global_load_lds_dwordx4 v[174:175], off
	s_add_i32 m0, s85, 0x1e000
	s_nop 0
	global_load_lds_dwordx4 v[170:171], off
	v_lshl_add_u64 v[170:171], v[172:173], 0, s[48:49]
	s_mov_b32 m0, s34
	s_nop 0
	global_load_lds_dwordx4 v[170:171], off
	v_lshl_add_u64 v[170:171], v[172:173], 0, s[14:15]
	s_mov_b32 m0, s35
	s_nop 0
	global_load_lds_dwordx4 v[170:171], off
	s_waitcnt vmcnt(8)
	s_waitcnt lgkmcnt(0)
	s_barrier
	s_setprio 1
	s_waitcnt lgkmcnt(0)
	v_mfma_f32_16x16x32_bf16 v[44:47], v[96:99], v[132:135], v[44:47]
	v_mfma_f32_16x16x32_bf16 v[40:43], v[104:107], v[132:135], v[40:43]
	v_mfma_f32_16x16x32_bf16 v[28:31], v[96:99], v[148:151], v[28:31]
	v_mfma_f32_16x16x32_bf16 v[24:27], v[104:107], v[148:151], v[24:27]
	v_mfma_f32_16x16x32_bf16 v[12:15], v[96:99], v[162:165], v[12:15]
	v_mfma_f32_16x16x32_bf16 v[8:11], v[104:107], v[162:165], v[8:11]
	v_mfma_f32_16x16x32_bf16 v[44:47], v[100:103], v[144:147], v[44:47]
	v_mfma_f32_16x16x32_bf16 v[40:43], v[108:111], v[144:147], v[40:43]
	v_mfma_f32_16x16x32_bf16 v[28:31], v[100:103], v[158:161], v[28:31]
	v_mfma_f32_16x16x32_bf16 v[24:27], v[108:111], v[158:161], v[24:27]
	v_mfma_f32_16x16x32_bf16 v[12:15], v[100:103], v[166:169], v[12:15]
	v_mfma_f32_16x16x32_bf16 v[8:11], v[108:111], v[166:169], v[8:11]
	s_setprio 0
	s_setprio 1
	v_mfma_f32_16x16x32_bf16 v[36:39], v[116:119], v[132:135], v[36:39]
	v_mfma_f32_16x16x32_bf16 v[32:35], v[124:127], v[132:135], v[32:35]
	v_mfma_f32_16x16x32_bf16 v[20:23], v[116:119], v[148:151], v[20:23]
	v_mfma_f32_16x16x32_bf16 v[16:19], v[124:127], v[148:151], v[16:19]
	v_mfma_f32_16x16x32_bf16 v[4:7], v[116:119], v[162:165], v[4:7]
	v_mfma_f32_16x16x32_bf16 v[0:3], v[124:127], v[162:165], v[0:3]
	v_mfma_f32_16x16x32_bf16 v[36:39], v[120:123], v[144:147], v[36:39]
	v_mfma_f32_16x16x32_bf16 v[32:35], v[128:131], v[144:147], v[32:35]
	v_mfma_f32_16x16x32_bf16 v[20:23], v[120:123], v[158:161], v[20:23]
	v_mfma_f32_16x16x32_bf16 v[16:19], v[128:131], v[158:161], v[16:19]
	v_mfma_f32_16x16x32_bf16 v[4:7], v[120:123], v[166:169], v[4:7]
	v_mfma_f32_16x16x32_bf16 v[0:3], v[128:131], v[166:169], v[0:3]
	s_setprio 0
	s_barrier
	s_add_i32 s45, s45, 2
	s_add_u32 s46, s46, 0x100
	s_addc_u32 s47, s47, 0
	s_add_u32 s2, s2, 0x100
	s_addc_u32 s29, s29, 0
	s_cmp_lt_u32 s45, 14

.LBB0_705:
	s_add_u32 s46, s46, 0x40080
	s_addc_u32 s47, s47, 0
	s_add_u32 s1, s92, 0x100
	s_addc_u32 s28, s93, 0
	s_mov_b32 s29, -2
	ds_read_b128 v[132:135], v156
	ds_read_b128 v[136:139], v156 offset:1024
	ds_read_b128 v[140:143], v156 offset:2048
	ds_read_b128 v[144:147], v156 offset:3072
	ds_read_b128 v[148:151], v190
	ds_read_b128 v[158:161], v190 offset:1024
	ds_read_b128 v[162:165], v190 offset:2048
	ds_read_b128 v[166:169], v190 offset:3072
	s_add_u32 s34, s46, 0xfffc0080
	s_addc_u32 s35, s47, -1
	s_cmp_eq_u32 s29, 12
	s_cselect_b32 s35, s51, s35
	s_cselect_b32 s34, s50, s34
	s_cselect_b32 s37, s43, s28
	s_cselect_b32 s36, s42, s1
	v_lshl_add_u64 v[218:219], s[46:47], 0, v[130:131]
	s_add_i32 m0, s91, 0xc000
	ds_read_b128 v[170:173], v191
	ds_read_b128 v[174:177], v191 offset:1024
	ds_read_b128 v[178:181], v201
	ds_read_b128 v[182:185], v201 offset:1024
	ds_read_b128 v[186:189], v202
	ds_read_b128 v[206:209], v202 offset:1024
	ds_read_b128 v[210:213], v203
	ds_read_b128 v[214:217], v203 offset:1024
	global_load_lds_dwordx4 v[218:219], off
	v_lshl_add_u64 v[218:219], v[218:219], 0, s[8:9]
	s_add_i32 m0, s91, 0xe000
	s_nop 0
	global_load_lds_dwordx4 v[218:219], off
	s_waitcnt vmcnt(8)
	s_waitcnt lgkmcnt(0)
	s_barrier
	s_setprio 1
	s_waitcnt lgkmcnt(0)
	v_mfma_f32_16x16x32_bf16 v[124:127], v[132:135], v[170:173], 0
	v_mfma_f32_16x16x32_bf16 v[120:123], v[140:143], v[170:173], 0
	v_mfma_f32_16x16x32_bf16 v[116:119], v[132:135], v[178:181], 0
	v_mfma_f32_16x16x32_bf16 v[112:115], v[140:143], v[178:181], 0
	v_mfma_f32_16x16x32_bf16 v[108:111], v[132:135], v[186:189], 0
	v_mfma_f32_16x16x32_bf16 v[104:107], v[140:143], v[186:189], 0
	v_mfma_f32_16x16x32_bf16 v[100:103], v[132:135], v[210:213], 0
	v_mfma_f32_16x16x32_bf16 v[96:99], v[140:143], v[210:213], 0
	v_mfma_f32_16x16x32_bf16 v[124:127], v[136:139], v[174:177], v[124:127]
	v_mfma_f32_16x16x32_bf16 v[120:123], v[144:147], v[174:177], v[120:123]
	v_mfma_f32_16x16x32_bf16 v[116:119], v[136:139], v[182:185], v[116:119]
	v_mfma_f32_16x16x32_bf16 v[112:115], v[144:147], v[182:185], v[112:115]
	v_mfma_f32_16x16x32_bf16 v[108:111], v[136:139], v[206:209], v[108:111]
	v_mfma_f32_16x16x32_bf16 v[104:107], v[144:147], v[206:209], v[104:107]
	v_mfma_f32_16x16x32_bf16 v[100:103], v[136:139], v[214:217], v[100:103]
	v_mfma_f32_16x16x32_bf16 v[96:99], v[144:147], v[214:217], v[96:99]
	s_setprio 0
	s_setprio 1
	v_mfma_f32_16x16x32_bf16 v[92:95], v[148:151], v[170:173], 0
	v_mfma_f32_16x16x32_bf16 v[88:91], v[162:165], v[170:173], 0
	v_mfma_f32_16x16x32_bf16 v[84:87], v[148:151], v[178:181], 0
	v_mfma_f32_16x16x32_bf16 v[80:83], v[162:165], v[178:181], 0
	v_mfma_f32_16x16x32_bf16 v[76:79], v[148:151], v[186:189], 0
	v_mfma_f32_16x16x32_bf16 v[72:75], v[162:165], v[186:189], 0
	v_mfma_f32_16x16x32_bf16 v[68:71], v[148:151], v[210:213], 0
	v_mfma_f32_16x16x32_bf16 v[64:67], v[162:165], v[210:213], 0
	v_mfma_f32_16x16x32_bf16 v[92:95], v[158:161], v[174:177], v[92:95]
	v_mfma_f32_16x16x32_bf16 v[88:91], v[166:169], v[174:177], v[88:91]
	v_mfma_f32_16x16x32_bf16 v[84:87], v[158:161], v[182:185], v[84:87]
	v_mfma_f32_16x16x32_bf16 v[80:83], v[166:169], v[182:185], v[80:83]
	v_mfma_f32_16x16x32_bf16 v[76:79], v[158:161], v[206:209], v[76:79]
	v_mfma_f32_16x16x32_bf16 v[72:75], v[166:169], v[206:209], v[72:75]
	v_mfma_f32_16x16x32_bf16 v[68:71], v[158:161], v[214:217], v[68:71]
	v_mfma_f32_16x16x32_bf16 v[64:67], v[166:169], v[214:217], v[64:67]
	s_setprio 0
	s_barrier
	s_mov_b32 m0, s95
	v_lshl_add_u64 v[218:219], s[36:37], 0, v[128:129]
	ds_read_b128 v[170:173], v191 offset:16384
	ds_read_b128 v[174:177], v191 offset:17408
	ds_read_b128 v[178:181], v201 offset:16384
	ds_read_b128 v[182:185], v201 offset:17408
	ds_read_b128 v[186:189], v202 offset:16384
	ds_read_b128 v[206:209], v202 offset:17408
	ds_read_b128 v[210:213], v203 offset:16384
	ds_read_b128 v[214:217], v203 offset:17408
	global_load_lds_dwordx4 v[218:219], off
	v_lshl_add_u64 v[220:221], v[218:219], 0, s[8:9]
	s_mov_b32 m0, s70
	s_nop 0
	global_load_lds_dwordx4 v[220:221], off
	v_lshl_add_u64 v[220:221], v[218:219], 0, s[10:11]
	s_mov_b32 m0, s71
	s_nop 0
	global_load_lds_dwordx4 v[220:221], off
	v_lshl_add_u64 v[220:221], v[218:219], 0, s[12:13]
	s_mov_b32 m0, s7
	s_nop 0
	global_load_lds_dwordx4 v[220:221], off
	v_lshl_add_u64 v[220:221], s[34:35], 0, v[128:129]
	s_mov_b32 m0, s91
	v_lshl_add_u64 v[222:223], v[220:221], 0, s[8:9]
	global_load_lds_dwordx4 v[220:221], off
	s_mov_b32 m0, s75
	s_nop 0
	global_load_lds_dwordx4 v[222:223], off
	s_waitcnt vmcnt(8)
	s_waitcnt lgkmcnt(0)
	s_barrier
	s_setprio 1
	s_waitcnt lgkmcnt(0)
	v_mfma_f32_16x16x32_bf16 v[60:63], v[132:135], v[170:173], 0
	v_mfma_f32_16x16x32_bf16 v[56:59], v[140:143], v[170:173], 0
	v_mfma_f32_16x16x32_bf16 v[52:55], v[132:135], v[178:181], 0
	v_mfma_f32_16x16x32_bf16 v[48:51], v[140:143], v[178:181], 0
	v_mfma_f32_16x16x32_bf16 v[44:47], v[132:135], v[186:189], 0
	v_mfma_f32_16x16x32_bf16 v[40:43], v[140:143], v[186:189], 0
	v_mfma_f32_16x16x32_bf16 v[36:39], v[132:135], v[210:213], 0
	v_mfma_f32_16x16x32_bf16 v[32:35], v[140:143], v[210:213], 0
	v_mfma_f32_16x16x32_bf16 v[60:63], v[136:139], v[174:177], v[60:63]
	v_mfma_f32_16x16x32_bf16 v[56:59], v[144:147], v[174:177], v[56:59]
	v_mfma_f32_16x16x32_bf16 v[52:55], v[136:139], v[182:185], v[52:55]
	v_mfma_f32_16x16x32_bf16 v[48:51], v[144:147], v[182:185], v[48:51]
	v_mfma_f32_16x16x32_bf16 v[44:47], v[136:139], v[206:209], v[44:47]
	v_mfma_f32_16x16x32_bf16 v[40:43], v[144:147], v[206:209], v[40:43]
	v_mfma_f32_16x16x32_bf16 v[36:39], v[136:139], v[214:217], v[36:39]
	v_mfma_f32_16x16x32_bf16 v[32:35], v[144:147], v[214:217], v[32:35]
	s_setprio 0
	s_setprio 1
	v_mfma_f32_16x16x32_bf16 v[28:31], v[148:151], v[170:173], 0
	v_mfma_f32_16x16x32_bf16 v[24:27], v[162:165], v[170:173], 0
	v_mfma_f32_16x16x32_bf16 v[20:23], v[148:151], v[178:181], 0
	v_mfma_f32_16x16x32_bf16 v[16:19], v[162:165], v[178:181], 0
	v_mfma_f32_16x16x32_bf16 v[12:15], v[148:151], v[186:189], 0
	v_mfma_f32_16x16x32_bf16 v[8:11], v[162:165], v[186:189], 0
	v_mfma_f32_16x16x32_bf16 v[4:7], v[148:151], v[210:213], 0
	v_mfma_f32_16x16x32_bf16 v[0:3], v[162:165], v[210:213], 0
	v_mfma_f32_16x16x32_bf16 v[28:31], v[158:161], v[174:177], v[28:31]
	v_mfma_f32_16x16x32_bf16 v[24:27], v[166:169], v[174:177], v[24:27]
	v_mfma_f32_16x16x32_bf16 v[20:23], v[158:161], v[182:185], v[20:23]
	v_mfma_f32_16x16x32_bf16 v[16:19], v[166:169], v[182:185], v[16:19]
	v_mfma_f32_16x16x32_bf16 v[12:15], v[158:161], v[206:209], v[12:15]
	v_mfma_f32_16x16x32_bf16 v[8:11], v[166:169], v[206:209], v[8:11]
	v_mfma_f32_16x16x32_bf16 v[4:7], v[158:161], v[214:217], v[4:7]
	v_mfma_f32_16x16x32_bf16 v[0:3], v[166:169], v[214:217], v[0:3]
	s_setprio 0
	s_barrier
	ds_read_b128 v[132:135], v204
	ds_read_b128 v[136:139], v204 offset:1024
	ds_read_b128 v[140:143], v204 offset:2048
	ds_read_b128 v[144:147], v204 offset:3072
	ds_read_b128 v[148:151], v205
	ds_read_b128 v[158:161], v205 offset:1024
	ds_read_b128 v[162:165], v205 offset:2048
	ds_read_b128 v[166:169], v205 offset:3072
	s_mov_b32 m0, s76
	v_lshl_add_u64 v[222:223], v[220:221], 0, s[10:11]
	ds_read_b128 v[170:173], v191 offset:32768
	ds_read_b128 v[174:177], v191 offset:33792
	ds_read_b128 v[178:181], v201 offset:32768
	ds_read_b128 v[182:185], v201 offset:33792
	ds_read_b128 v[186:189], v202 offset:32768
	ds_read_b128 v[206:209], v202 offset:33792
	ds_read_b128 v[210:213], v203 offset:32768
	ds_read_b128 v[214:217], v203 offset:33792
	global_load_lds_dwordx4 v[222:223], off
	v_lshl_add_u64 v[222:223], v[220:221], 0, s[12:13]
	s_mov_b32 m0, s78
	s_nop 0
	global_load_lds_dwordx4 v[222:223], off
	s_waitcnt vmcnt(8)
	s_waitcnt lgkmcnt(0)
	s_barrier
	s_setprio 1
	s_waitcnt lgkmcnt(0)
	v_mfma_f32_16x16x32_bf16 v[124:127], v[132:135], v[170:173], v[124:127]
	v_mfma_f32_16x16x32_bf16 v[120:123], v[140:143], v[170:173], v[120:123]
	v_mfma_f32_16x16x32_bf16 v[116:119], v[132:135], v[178:181], v[116:119]
	v_mfma_f32_16x16x32_bf16 v[112:115], v[140:143], v[178:181], v[112:115]
	v_mfma_f32_16x16x32_bf16 v[108:111], v[132:135], v[186:189], v[108:111]
	v_mfma_f32_16x16x32_bf16 v[104:107], v[140:143], v[186:189], v[104:107]
	v_mfma_f32_16x16x32_bf16 v[100:103], v[132:135], v[210:213], v[100:103]
	v_mfma_f32_16x16x32_bf16 v[96:99], v[140:143], v[210:213], v[96:99]
	v_mfma_f32_16x16x32_bf16 v[124:127], v[136:139], v[174:177], v[124:127]
	v_mfma_f32_16x16x32_bf16 v[120:123], v[144:147], v[174:177], v[120:123]
	v_mfma_f32_16x16x32_bf16 v[116:119], v[136:139], v[182:185], v[116:119]
	v_mfma_f32_16x16x32_bf16 v[112:115], v[144:147], v[182:185], v[112:115]
	v_mfma_f32_16x16x32_bf16 v[108:111], v[136:139], v[206:209], v[108:111]
	v_mfma_f32_16x16x32_bf16 v[104:107], v[144:147], v[206:209], v[104:107]
	v_mfma_f32_16x16x32_bf16 v[100:103], v[136:139], v[214:217], v[100:103]
	v_mfma_f32_16x16x32_bf16 v[96:99], v[144:147], v[214:217], v[96:99]
	s_setprio 0
	s_setprio 1
	v_mfma_f32_16x16x32_bf16 v[92:95], v[148:151], v[170:173], v[92:95]
	v_mfma_f32_16x16x32_bf16 v[88:91], v[162:165], v[170:173], v[88:91]
	v_mfma_f32_16x16x32_bf16 v[84:87], v[148:151], v[178:181], v[84:87]
	v_mfma_f32_16x16x32_bf16 v[80:83], v[162:165], v[178:181], v[80:83]
	v_mfma_f32_16x16x32_bf16 v[76:79], v[148:151], v[186:189], v[76:79]
	v_mfma_f32_16x16x32_bf16 v[72:75], v[162:165], v[186:189], v[72:75]
	v_mfma_f32_16x16x32_bf16 v[68:71], v[148:151], v[210:213], v[68:71]
	v_mfma_f32_16x16x32_bf16 v[64:67], v[162:165], v[210:213], v[64:67]
	v_mfma_f32_16x16x32_bf16 v[92:95], v[158:161], v[174:177], v[92:95]
	v_mfma_f32_16x16x32_bf16 v[88:91], v[166:169], v[174:177], v[88:91]
	v_mfma_f32_16x16x32_bf16 v[84:87], v[158:161], v[182:185], v[84:87]
	v_mfma_f32_16x16x32_bf16 v[80:83], v[166:169], v[182:185], v[80:83]
	v_mfma_f32_16x16x32_bf16 v[76:79], v[158:161], v[206:209], v[76:79]
	v_mfma_f32_16x16x32_bf16 v[72:75], v[166:169], v[206:209], v[72:75]
	v_mfma_f32_16x16x32_bf16 v[68:71], v[158:161], v[214:217], v[68:71]
	v_mfma_f32_16x16x32_bf16 v[64:67], v[166:169], v[214:217], v[64:67]
	s_setprio 0
	s_barrier
	v_lshl_add_u64 v[222:223], v[218:219], 0, s[48:49]
	s_add_i32 m0, s91, 0x18000
	ds_read_b128 v[170:173], v191 offset:49152
	ds_read_b128 v[174:177], v191 offset:50176
	ds_read_b128 v[178:181], v201 offset:49152
	ds_read_b128 v[182:185], v201 offset:50176
	ds_read_b128 v[186:189], v202 offset:49152
	ds_read_b128 v[206:209], v202 offset:50176
	ds_read_b128 v[210:213], v203 offset:49152
	ds_read_b128 v[214:217], v203 offset:50176
	global_load_lds_dwordx4 v[222:223], off
	v_lshl_add_u64 v[222:223], v[218:219], 0, s[14:15]
	s_add_i32 m0, s91, 0x1a000
	s_nop 0
	global_load_lds_dwordx4 v[222:223], off
	v_lshl_add_u64 v[222:223], v[218:219], 0, s[56:57]
	s_add_i32 m0, s91, 0x1c000
	v_lshl_add_u64 v[218:219], v[218:219], 0, s[62:63]
	global_load_lds_dwordx4 v[222:223], off
	s_add_i32 m0, s91, 0x1e000
	s_nop 0
	global_load_lds_dwordx4 v[218:219], off
	v_lshl_add_u64 v[218:219], v[220:221], 0, s[48:49]
	s_mov_b32 m0, s33
	s_nop 0
	global_load_lds_dwordx4 v[218:219], off
	v_lshl_add_u64 v[218:219], v[220:221], 0, s[14:15]
	s_mov_b32 m0, s85
	s_nop 0
	global_load_lds_dwordx4 v[218:219], off
	s_waitcnt vmcnt(8)
	s_waitcnt lgkmcnt(0)
	s_barrier
	s_setprio 1
	s_waitcnt lgkmcnt(0)
	v_mfma_f32_16x16x32_bf16 v[60:63], v[132:135], v[170:173], v[60:63]
	v_mfma_f32_16x16x32_bf16 v[56:59], v[140:143], v[170:173], v[56:59]
	v_mfma_f32_16x16x32_bf16 v[52:55], v[132:135], v[178:181], v[52:55]
	v_mfma_f32_16x16x32_bf16 v[48:51], v[140:143], v[178:181], v[48:51]
	v_mfma_f32_16x16x32_bf16 v[44:47], v[132:135], v[186:189], v[44:47]
	v_mfma_f32_16x16x32_bf16 v[40:43], v[140:143], v[186:189], v[40:43]
	v_mfma_f32_16x16x32_bf16 v[36:39], v[132:135], v[210:213], v[36:39]
	v_mfma_f32_16x16x32_bf16 v[32:35], v[140:143], v[210:213], v[32:35]
	v_mfma_f32_16x16x32_bf16 v[60:63], v[136:139], v[174:177], v[60:63]
	v_mfma_f32_16x16x32_bf16 v[56:59], v[144:147], v[174:177], v[56:59]
	v_mfma_f32_16x16x32_bf16 v[52:55], v[136:139], v[182:185], v[52:55]
	v_mfma_f32_16x16x32_bf16 v[48:51], v[144:147], v[182:185], v[48:51]
	v_mfma_f32_16x16x32_bf16 v[44:47], v[136:139], v[206:209], v[44:47]
	v_mfma_f32_16x16x32_bf16 v[40:43], v[144:147], v[206:209], v[40:43]
	v_mfma_f32_16x16x32_bf16 v[36:39], v[136:139], v[214:217], v[36:39]
	v_mfma_f32_16x16x32_bf16 v[32:35], v[144:147], v[214:217], v[32:35]
	s_setprio 0
	s_setprio 1
	v_mfma_f32_16x16x32_bf16 v[28:31], v[148:151], v[170:173], v[28:31]
	v_mfma_f32_16x16x32_bf16 v[24:27], v[162:165], v[170:173], v[24:27]
	v_mfma_f32_16x16x32_bf16 v[20:23], v[148:151], v[178:181], v[20:23]
	v_mfma_f32_16x16x32_bf16 v[16:19], v[162:165], v[178:181], v[16:19]
	v_mfma_f32_16x16x32_bf16 v[12:15], v[148:151], v[186:189], v[12:15]
	v_mfma_f32_16x16x32_bf16 v[8:11], v[162:165], v[186:189], v[8:11]
	v_mfma_f32_16x16x32_bf16 v[4:7], v[148:151], v[210:213], v[4:7]
	v_mfma_f32_16x16x32_bf16 v[0:3], v[162:165], v[210:213], v[0:3]
	v_mfma_f32_16x16x32_bf16 v[28:31], v[158:161], v[174:177], v[28:31]
	v_mfma_f32_16x16x32_bf16 v[24:27], v[166:169], v[174:177], v[24:27]
	v_mfma_f32_16x16x32_bf16 v[20:23], v[158:161], v[182:185], v[20:23]
	v_mfma_f32_16x16x32_bf16 v[16:19], v[166:169], v[182:185], v[16:19]
	v_mfma_f32_16x16x32_bf16 v[12:15], v[158:161], v[206:209], v[12:15]
	v_mfma_f32_16x16x32_bf16 v[8:11], v[166:169], v[206:209], v[8:11]
	v_mfma_f32_16x16x32_bf16 v[4:7], v[158:161], v[214:217], v[4:7]
	v_mfma_f32_16x16x32_bf16 v[0:3], v[166:169], v[214:217], v[0:3]
	s_setprio 0
	s_barrier
	s_add_i32 s29, s29, 2
	s_add_u32 s46, s46, 0x100
	s_addc_u32 s47, s47, 0
	s_add_u32 s1, s1, 0x100
	s_addc_u32 s28, s28, 0
	s_cmp_lt_u32 s29, 14

.LBB0_923:
	s_add_u32 s44, s44, 0x20080
	s_addc_u32 s45, s45, 0
	s_add_u32 s41, s46, 0x100
	s_addc_u32 s46, s47, 0
	s_mov_b32 s47, -2
	ds_read_b128 v[68:71], v100
	ds_read_b128 v[72:75], v100 offset:1024
	ds_read_b128 v[76:79], v100 offset:2048
	ds_read_b128 v[80:83], v100 offset:3072
	ds_read_b128 v[84:87], v101
	ds_read_b128 v[88:91], v101 offset:1024
	ds_read_b128 v[92:95], v101 offset:2048
	ds_read_b128 v[96:99], v101 offset:3072
	s_add_u32 s67, s44, 0xfffe0080
	s_addc_u32 s71, s45, -1
	s_cmp_eq_u32 s47, 12
	s_cselect_b32 s79, s93, s71
	s_cselect_b32 s78, s92, s67
	s_cselect_b32 vcc_hi, s95, s46
	s_cselect_b32 vcc_lo, s94, s41
	v_lshl_add_u64 v[122:123], s[44:45], 0, v[66:67]
	s_add_i32 m0, s1, 0xc000
	ds_read_b128 v[106:109], v102
	ds_read_b128 v[110:113], v102 offset:1024
	ds_read_b128 v[114:117], v103
	ds_read_b128 v[118:121], v103 offset:1024
	global_load_lds_dwordx4 v[122:123], off
	v_lshl_add_u64 v[122:123], v[122:123], 0, s[8:9]
	s_add_i32 m0, s1, 0xe000
	s_nop 0
	global_load_lds_dwordx4 v[122:123], off
	s_waitcnt vmcnt(8)
	s_waitcnt lgkmcnt(0)
	s_barrier
	s_setprio 1
	s_waitcnt lgkmcnt(0)
	v_mfma_f32_16x16x32_bf16 v[60:63], v[68:71], v[106:109], 0
	v_mfma_f32_16x16x32_bf16 v[56:59], v[76:79], v[106:109], 0
	v_mfma_f32_16x16x32_bf16 v[52:55], v[68:71], v[114:117], 0
	v_mfma_f32_16x16x32_bf16 v[48:51], v[76:79], v[114:117], 0
	v_mfma_f32_16x16x32_bf16 v[60:63], v[72:75], v[110:113], v[60:63]
	v_mfma_f32_16x16x32_bf16 v[56:59], v[80:83], v[110:113], v[56:59]
	v_mfma_f32_16x16x32_bf16 v[52:55], v[72:75], v[118:121], v[52:55]
	v_mfma_f32_16x16x32_bf16 v[48:51], v[80:83], v[118:121], v[48:51]
	s_setprio 0
	s_setprio 1
	v_mfma_f32_16x16x32_bf16 v[44:47], v[84:87], v[106:109], 0
	v_mfma_f32_16x16x32_bf16 v[40:43], v[92:95], v[106:109], 0
	v_mfma_f32_16x16x32_bf16 v[36:39], v[84:87], v[114:117], 0
	v_mfma_f32_16x16x32_bf16 v[32:35], v[92:95], v[114:117], 0
	v_mfma_f32_16x16x32_bf16 v[44:47], v[88:91], v[110:113], v[44:47]
	v_mfma_f32_16x16x32_bf16 v[40:43], v[96:99], v[110:113], v[40:43]
	v_mfma_f32_16x16x32_bf16 v[36:39], v[88:91], v[118:121], v[36:39]
	v_mfma_f32_16x16x32_bf16 v[32:35], v[96:99], v[118:121], v[32:35]
	s_setprio 0
	s_barrier
	s_mov_b32 m0, s7
	v_lshl_add_u64 v[122:123], vcc, 0, v[64:65]
	ds_read_b128 v[106:109], v102 offset:16384
	ds_read_b128 v[110:113], v102 offset:17408
	ds_read_b128 v[114:117], v103 offset:16384
	ds_read_b128 v[118:121], v103 offset:17408
	global_load_lds_dwordx4 v[122:123], off
	v_lshl_add_u64 v[124:125], v[122:123], 0, s[8:9]
	s_mov_b32 m0, s28
	s_nop 0
	global_load_lds_dwordx4 v[124:125], off
	v_lshl_add_u64 v[124:125], v[122:123], 0, s[10:11]
	s_mov_b32 m0, s29
	s_nop 0
	global_load_lds_dwordx4 v[124:125], off
	v_lshl_add_u64 v[124:125], v[122:123], 0, s[12:13]
	s_mov_b32 m0, s33
	s_nop 0
	global_load_lds_dwordx4 v[124:125], off
	v_lshl_add_u64 v[124:125], s[78:79], 0, v[64:65]
	s_mov_b32 m0, s1
	v_lshl_add_u64 v[126:127], v[124:125], 0, s[8:9]
	global_load_lds_dwordx4 v[124:125], off
	s_mov_b32 m0, s34
	s_nop 0
	global_load_lds_dwordx4 v[126:127], off
	s_waitcnt vmcnt(8)
	s_waitcnt lgkmcnt(0)
	s_barrier
	s_setprio 1
	s_waitcnt lgkmcnt(0)
	v_mfma_f32_16x16x32_bf16 v[28:31], v[68:71], v[106:109], 0
	v_mfma_f32_16x16x32_bf16 v[24:27], v[76:79], v[106:109], 0
	v_mfma_f32_16x16x32_bf16 v[20:23], v[68:71], v[114:117], 0
	v_mfma_f32_16x16x32_bf16 v[16:19], v[76:79], v[114:117], 0
	v_mfma_f32_16x16x32_bf16 v[28:31], v[72:75], v[110:113], v[28:31]
	v_mfma_f32_16x16x32_bf16 v[24:27], v[80:83], v[110:113], v[24:27]
	v_mfma_f32_16x16x32_bf16 v[20:23], v[72:75], v[118:121], v[20:23]
	v_mfma_f32_16x16x32_bf16 v[16:19], v[80:83], v[118:121], v[16:19]
	s_setprio 0
	s_setprio 1
	v_mfma_f32_16x16x32_bf16 v[12:15], v[84:87], v[106:109], 0
	v_mfma_f32_16x16x32_bf16 v[8:11], v[92:95], v[106:109], 0
	v_mfma_f32_16x16x32_bf16 v[4:7], v[84:87], v[114:117], 0
	v_mfma_f32_16x16x32_bf16 v[0:3], v[92:95], v[114:117], 0
	v_mfma_f32_16x16x32_bf16 v[12:15], v[88:91], v[110:113], v[12:15]
	v_mfma_f32_16x16x32_bf16 v[8:11], v[96:99], v[110:113], v[8:11]
	v_mfma_f32_16x16x32_bf16 v[4:7], v[88:91], v[118:121], v[4:7]
	v_mfma_f32_16x16x32_bf16 v[0:3], v[96:99], v[118:121], v[0:3]
	s_setprio 0
	s_barrier
	ds_read_b128 v[68:71], v104
	ds_read_b128 v[72:75], v104 offset:1024
	ds_read_b128 v[76:79], v104 offset:2048
	ds_read_b128 v[80:83], v104 offset:3072
	ds_read_b128 v[84:87], v105
	ds_read_b128 v[88:91], v105 offset:1024
	ds_read_b128 v[92:95], v105 offset:2048
	ds_read_b128 v[96:99], v105 offset:3072
	s_mov_b32 m0, s35
	ds_read_b128 v[106:109], v102 offset:32768
	ds_read_b128 v[110:113], v102 offset:33792
	ds_read_b128 v[114:117], v103 offset:32768
	ds_read_b128 v[118:121], v103 offset:33792
	global_load_lds_dwordx4 v[126:127], off
	v_lshl_add_u64 v[126:127], v[124:125], 0, s[10:11]
	s_mov_b32 m0, s36
	s_nop 0
	global_load_lds_dwordx4 v[126:127], off
	s_waitcnt vmcnt(8)
	s_waitcnt lgkmcnt(0)
	s_barrier
	s_setprio 1
	s_waitcnt lgkmcnt(0)
	v_mfma_f32_16x16x32_bf16 v[60:63], v[68:71], v[106:109], v[60:63]
	v_mfma_f32_16x16x32_bf16 v[56:59], v[76:79], v[106:109], v[56:59]
	v_mfma_f32_16x16x32_bf16 v[52:55], v[68:71], v[114:117], v[52:55]
	v_mfma_f32_16x16x32_bf16 v[48:51], v[76:79], v[114:117], v[48:51]
	v_mfma_f32_16x16x32_bf16 v[60:63], v[72:75], v[110:113], v[60:63]
	v_mfma_f32_16x16x32_bf16 v[56:59], v[80:83], v[110:113], v[56:59]
	v_mfma_f32_16x16x32_bf16 v[52:55], v[72:75], v[118:121], v[52:55]
	v_mfma_f32_16x16x32_bf16 v[48:51], v[80:83], v[118:121], v[48:51]
	s_setprio 0
	s_setprio 1
	v_mfma_f32_16x16x32_bf16 v[44:47], v[84:87], v[106:109], v[44:47]
	v_mfma_f32_16x16x32_bf16 v[40:43], v[92:95], v[106:109], v[40:43]
	v_mfma_f32_16x16x32_bf16 v[36:39], v[84:87], v[114:117], v[36:39]
	v_mfma_f32_16x16x32_bf16 v[32:35], v[92:95], v[114:117], v[32:35]
	v_mfma_f32_16x16x32_bf16 v[44:47], v[88:91], v[110:113], v[44:47]
	v_mfma_f32_16x16x32_bf16 v[40:43], v[96:99], v[110:113], v[40:43]
	v_mfma_f32_16x16x32_bf16 v[36:39], v[88:91], v[118:121], v[36:39]
	v_mfma_f32_16x16x32_bf16 v[32:35], v[96:99], v[118:121], v[32:35]
	s_setprio 0
	s_barrier
	v_lshl_add_u64 v[126:127], v[122:123], 0, s[48:49]
	s_add_i32 m0, s1, 0x18000
	ds_read_b128 v[106:109], v102 offset:49152
	ds_read_b128 v[110:113], v102 offset:50176
	ds_read_b128 v[114:117], v103 offset:49152
	ds_read_b128 v[118:121], v103 offset:50176
	global_load_lds_dwordx4 v[126:127], off
	v_lshl_add_u64 v[126:127], v[122:123], 0, s[14:15]
	s_add_i32 m0, s1, 0x1a000
	s_nop 0
	global_load_lds_dwordx4 v[126:127], off
	v_lshl_add_u64 v[126:127], v[122:123], 0, s[56:57]
	s_add_i32 m0, s1, 0x1c000
	v_lshl_add_u64 v[122:123], v[122:123], 0, s[62:63]
	global_load_lds_dwordx4 v[126:127], off
	s_add_i32 m0, s1, 0x1e000
	s_nop 0
	global_load_lds_dwordx4 v[122:123], off
	v_lshl_add_u64 v[122:123], v[124:125], 0, s[48:49]
	s_mov_b32 m0, s37
	s_nop 0
	global_load_lds_dwordx4 v[122:123], off
	v_lshl_add_u64 v[122:123], v[124:125], 0, s[14:15]
	s_mov_b32 m0, s38
	s_nop 0
	global_load_lds_dwordx4 v[122:123], off
	s_waitcnt vmcnt(8)
	s_waitcnt lgkmcnt(0)
	s_barrier
	s_setprio 1
	s_waitcnt lgkmcnt(0)
	v_mfma_f32_16x16x32_bf16 v[28:31], v[68:71], v[106:109], v[28:31]
	v_mfma_f32_16x16x32_bf16 v[24:27], v[76:79], v[106:109], v[24:27]
	v_mfma_f32_16x16x32_bf16 v[20:23], v[68:71], v[114:117], v[20:23]
	v_mfma_f32_16x16x32_bf16 v[16:19], v[76:79], v[114:117], v[16:19]
	v_mfma_f32_16x16x32_bf16 v[28:31], v[72:75], v[110:113], v[28:31]
	v_mfma_f32_16x16x32_bf16 v[24:27], v[80:83], v[110:113], v[24:27]
	v_mfma_f32_16x16x32_bf16 v[20:23], v[72:75], v[118:121], v[20:23]
	v_mfma_f32_16x16x32_bf16 v[16:19], v[80:83], v[118:121], v[16:19]
	s_setprio 0
	s_setprio 1
	v_mfma_f32_16x16x32_bf16 v[12:15], v[84:87], v[106:109], v[12:15]
	v_mfma_f32_16x16x32_bf16 v[8:11], v[92:95], v[106:109], v[8:11]
	v_mfma_f32_16x16x32_bf16 v[4:7], v[84:87], v[114:117], v[4:7]
	v_mfma_f32_16x16x32_bf16 v[0:3], v[92:95], v[114:117], v[0:3]
	v_mfma_f32_16x16x32_bf16 v[12:15], v[88:91], v[110:113], v[12:15]
	v_mfma_f32_16x16x32_bf16 v[8:11], v[96:99], v[110:113], v[8:11]
	v_mfma_f32_16x16x32_bf16 v[4:7], v[88:91], v[118:121], v[4:7]
	v_mfma_f32_16x16x32_bf16 v[0:3], v[96:99], v[118:121], v[0:3]
	s_setprio 0
	s_barrier
	s_add_i32 s47, s47, 2
	s_add_u32 s44, s44, 0x100
	s_addc_u32 s45, s45, 0
	s_add_u32 s41, s41, 0x100
	s_addc_u32 s46, s46, 0
	s_cmp_lt_u32 s47, 14

.LBB0_1047:
	s_add_u32 s46, s46, 0x40080
	s_addc_u32 s47, s47, 0
	s_add_u32 s1, s92, 0x100
	s_addc_u32 s28, s93, 0
	s_mov_b32 s29, -2
	ds_read_b128 v[132:135], v156
	ds_read_b128 v[136:139], v156 offset:1024
	ds_read_b128 v[140:143], v156 offset:2048
	ds_read_b128 v[144:147], v156 offset:3072
	ds_read_b128 v[148:151], v190
	ds_read_b128 v[158:161], v190 offset:1024
	ds_read_b128 v[162:165], v190 offset:2048
	ds_read_b128 v[166:169], v190 offset:3072
	s_add_u32 s34, s46, 0xfffc0080
	s_addc_u32 s35, s47, -1
	s_cmp_eq_u32 s29, 12
	s_cselect_b32 s35, s41, s35
	s_cselect_b32 s34, s40, s34
	s_cselect_b32 s37, s43, s28
	s_cselect_b32 s36, s42, s1
	v_lshl_add_u64 v[218:219], s[46:47], 0, v[130:131]
	s_add_i32 m0, s75, 0xc000
	ds_read_b128 v[170:173], v191
	ds_read_b128 v[174:177], v191 offset:1024
	ds_read_b128 v[178:181], v201
	ds_read_b128 v[182:185], v201 offset:1024
	ds_read_b128 v[186:189], v202
	ds_read_b128 v[206:209], v202 offset:1024
	ds_read_b128 v[210:213], v203
	ds_read_b128 v[214:217], v203 offset:1024
	global_load_lds_dwordx4 v[218:219], off
	v_lshl_add_u64 v[218:219], v[218:219], 0, s[8:9]
	s_add_i32 m0, s75, 0xe000
	s_nop 0
	global_load_lds_dwordx4 v[218:219], off
	s_waitcnt vmcnt(8)
	s_waitcnt lgkmcnt(0)
	s_barrier
	s_setprio 1
	s_waitcnt lgkmcnt(0)
	v_mfma_f32_16x16x32_bf16 v[124:127], v[132:135], v[170:173], 0
	v_mfma_f32_16x16x32_bf16 v[120:123], v[140:143], v[170:173], 0
	v_mfma_f32_16x16x32_bf16 v[116:119], v[132:135], v[178:181], 0
	v_mfma_f32_16x16x32_bf16 v[112:115], v[140:143], v[178:181], 0
	v_mfma_f32_16x16x32_bf16 v[108:111], v[132:135], v[186:189], 0
	v_mfma_f32_16x16x32_bf16 v[104:107], v[140:143], v[186:189], 0
	v_mfma_f32_16x16x32_bf16 v[100:103], v[132:135], v[210:213], 0
	v_mfma_f32_16x16x32_bf16 v[96:99], v[140:143], v[210:213], 0
	v_mfma_f32_16x16x32_bf16 v[124:127], v[136:139], v[174:177], v[124:127]
	v_mfma_f32_16x16x32_bf16 v[120:123], v[144:147], v[174:177], v[120:123]
	v_mfma_f32_16x16x32_bf16 v[116:119], v[136:139], v[182:185], v[116:119]
	v_mfma_f32_16x16x32_bf16 v[112:115], v[144:147], v[182:185], v[112:115]
	v_mfma_f32_16x16x32_bf16 v[108:111], v[136:139], v[206:209], v[108:111]
	v_mfma_f32_16x16x32_bf16 v[104:107], v[144:147], v[206:209], v[104:107]
	v_mfma_f32_16x16x32_bf16 v[100:103], v[136:139], v[214:217], v[100:103]
	v_mfma_f32_16x16x32_bf16 v[96:99], v[144:147], v[214:217], v[96:99]
	s_setprio 0
	s_setprio 1
	v_mfma_f32_16x16x32_bf16 v[92:95], v[148:151], v[170:173], 0
	v_mfma_f32_16x16x32_bf16 v[88:91], v[162:165], v[170:173], 0
	v_mfma_f32_16x16x32_bf16 v[84:87], v[148:151], v[178:181], 0
	v_mfma_f32_16x16x32_bf16 v[80:83], v[162:165], v[178:181], 0
	v_mfma_f32_16x16x32_bf16 v[76:79], v[148:151], v[186:189], 0
	v_mfma_f32_16x16x32_bf16 v[72:75], v[162:165], v[186:189], 0
	v_mfma_f32_16x16x32_bf16 v[68:71], v[148:151], v[210:213], 0
	v_mfma_f32_16x16x32_bf16 v[64:67], v[162:165], v[210:213], 0
	v_mfma_f32_16x16x32_bf16 v[92:95], v[158:161], v[174:177], v[92:95]
	v_mfma_f32_16x16x32_bf16 v[88:91], v[166:169], v[174:177], v[88:91]
	v_mfma_f32_16x16x32_bf16 v[84:87], v[158:161], v[182:185], v[84:87]
	v_mfma_f32_16x16x32_bf16 v[80:83], v[166:169], v[182:185], v[80:83]
	v_mfma_f32_16x16x32_bf16 v[76:79], v[158:161], v[206:209], v[76:79]
	v_mfma_f32_16x16x32_bf16 v[72:75], v[166:169], v[206:209], v[72:75]
	v_mfma_f32_16x16x32_bf16 v[68:71], v[158:161], v[214:217], v[68:71]
	v_mfma_f32_16x16x32_bf16 v[64:67], v[166:169], v[214:217], v[64:67]
	s_setprio 0
	s_barrier
	s_mov_b32 m0, s91
	v_lshl_add_u64 v[218:219], s[36:37], 0, v[128:129]
	ds_read_b128 v[170:173], v191 offset:16384
	ds_read_b128 v[174:177], v191 offset:17408
	ds_read_b128 v[178:181], v201 offset:16384
	ds_read_b128 v[182:185], v201 offset:17408
	ds_read_b128 v[186:189], v202 offset:16384
	ds_read_b128 v[206:209], v202 offset:17408
	ds_read_b128 v[210:213], v203 offset:16384
	ds_read_b128 v[214:217], v203 offset:17408
	global_load_lds_dwordx4 v[218:219], off
	v_lshl_add_u64 v[220:221], v[218:219], 0, s[8:9]
	s_mov_b32 m0, s94
	s_nop 0
	global_load_lds_dwordx4 v[220:221], off
	v_lshl_add_u64 v[220:221], v[218:219], 0, s[10:11]
	s_mov_b32 m0, s95
	s_nop 0
	global_load_lds_dwordx4 v[220:221], off
	v_lshl_add_u64 v[220:221], v[218:219], 0, s[12:13]
	s_mov_b32 m0, s7
	s_nop 0
	global_load_lds_dwordx4 v[220:221], off
	v_lshl_add_u64 v[220:221], s[34:35], 0, v[128:129]
	s_mov_b32 m0, s75
	v_lshl_add_u64 v[222:223], v[220:221], 0, s[8:9]
	global_load_lds_dwordx4 v[220:221], off
	s_mov_b32 m0, s76
	s_nop 0
	global_load_lds_dwordx4 v[222:223], off
	s_waitcnt vmcnt(8)
	s_waitcnt lgkmcnt(0)
	s_barrier
	s_setprio 1
	s_waitcnt lgkmcnt(0)
	v_mfma_f32_16x16x32_bf16 v[60:63], v[132:135], v[170:173], 0
	v_mfma_f32_16x16x32_bf16 v[56:59], v[140:143], v[170:173], 0
	v_mfma_f32_16x16x32_bf16 v[52:55], v[132:135], v[178:181], 0
	v_mfma_f32_16x16x32_bf16 v[48:51], v[140:143], v[178:181], 0
	v_mfma_f32_16x16x32_bf16 v[44:47], v[132:135], v[186:189], 0
	v_mfma_f32_16x16x32_bf16 v[40:43], v[140:143], v[186:189], 0
	v_mfma_f32_16x16x32_bf16 v[36:39], v[132:135], v[210:213], 0
	v_mfma_f32_16x16x32_bf16 v[32:35], v[140:143], v[210:213], 0
	v_mfma_f32_16x16x32_bf16 v[60:63], v[136:139], v[174:177], v[60:63]
	v_mfma_f32_16x16x32_bf16 v[56:59], v[144:147], v[174:177], v[56:59]
	v_mfma_f32_16x16x32_bf16 v[52:55], v[136:139], v[182:185], v[52:55]
	v_mfma_f32_16x16x32_bf16 v[48:51], v[144:147], v[182:185], v[48:51]
	v_mfma_f32_16x16x32_bf16 v[44:47], v[136:139], v[206:209], v[44:47]
	v_mfma_f32_16x16x32_bf16 v[40:43], v[144:147], v[206:209], v[40:43]
	v_mfma_f32_16x16x32_bf16 v[36:39], v[136:139], v[214:217], v[36:39]
	v_mfma_f32_16x16x32_bf16 v[32:35], v[144:147], v[214:217], v[32:35]
	s_setprio 0
	s_setprio 1
	v_mfma_f32_16x16x32_bf16 v[28:31], v[148:151], v[170:173], 0
	v_mfma_f32_16x16x32_bf16 v[24:27], v[162:165], v[170:173], 0
	v_mfma_f32_16x16x32_bf16 v[20:23], v[148:151], v[178:181], 0
	v_mfma_f32_16x16x32_bf16 v[16:19], v[162:165], v[178:181], 0
	v_mfma_f32_16x16x32_bf16 v[12:15], v[148:151], v[186:189], 0
	v_mfma_f32_16x16x32_bf16 v[8:11], v[162:165], v[186:189], 0
	v_mfma_f32_16x16x32_bf16 v[4:7], v[148:151], v[210:213], 0
	v_mfma_f32_16x16x32_bf16 v[0:3], v[162:165], v[210:213], 0
	v_mfma_f32_16x16x32_bf16 v[28:31], v[158:161], v[174:177], v[28:31]
	v_mfma_f32_16x16x32_bf16 v[24:27], v[166:169], v[174:177], v[24:27]
	v_mfma_f32_16x16x32_bf16 v[20:23], v[158:161], v[182:185], v[20:23]
	v_mfma_f32_16x16x32_bf16 v[16:19], v[166:169], v[182:185], v[16:19]
	v_mfma_f32_16x16x32_bf16 v[12:15], v[158:161], v[206:209], v[12:15]
	v_mfma_f32_16x16x32_bf16 v[8:11], v[166:169], v[206:209], v[8:11]
	v_mfma_f32_16x16x32_bf16 v[4:7], v[158:161], v[214:217], v[4:7]
	v_mfma_f32_16x16x32_bf16 v[0:3], v[166:169], v[214:217], v[0:3]
	s_setprio 0
	s_barrier
	ds_read_b128 v[132:135], v204
	ds_read_b128 v[136:139], v204 offset:1024
	ds_read_b128 v[140:143], v204 offset:2048
	ds_read_b128 v[144:147], v204 offset:3072
	ds_read_b128 v[148:151], v205
	ds_read_b128 v[158:161], v205 offset:1024
	ds_read_b128 v[162:165], v205 offset:2048
	ds_read_b128 v[166:169], v205 offset:3072
	s_mov_b32 m0, s78
	v_lshl_add_u64 v[222:223], v[220:221], 0, s[10:11]
	ds_read_b128 v[170:173], v191 offset:32768
	ds_read_b128 v[174:177], v191 offset:33792
	ds_read_b128 v[178:181], v201 offset:32768
	ds_read_b128 v[182:185], v201 offset:33792
	ds_read_b128 v[186:189], v202 offset:32768
	ds_read_b128 v[206:209], v202 offset:33792
	ds_read_b128 v[210:213], v203 offset:32768
	ds_read_b128 v[214:217], v203 offset:33792
	global_load_lds_dwordx4 v[222:223], off
	v_lshl_add_u64 v[222:223], v[220:221], 0, s[12:13]
	s_mov_b32 m0, s33
	s_nop 0
	global_load_lds_dwordx4 v[222:223], off
	s_waitcnt vmcnt(8)
	s_waitcnt lgkmcnt(0)
	s_barrier
	s_setprio 1
	s_waitcnt lgkmcnt(0)
	v_mfma_f32_16x16x32_bf16 v[124:127], v[132:135], v[170:173], v[124:127]
	v_mfma_f32_16x16x32_bf16 v[120:123], v[140:143], v[170:173], v[120:123]
	v_mfma_f32_16x16x32_bf16 v[116:119], v[132:135], v[178:181], v[116:119]
	v_mfma_f32_16x16x32_bf16 v[112:115], v[140:143], v[178:181], v[112:115]
	v_mfma_f32_16x16x32_bf16 v[108:111], v[132:135], v[186:189], v[108:111]
	v_mfma_f32_16x16x32_bf16 v[104:107], v[140:143], v[186:189], v[104:107]
	v_mfma_f32_16x16x32_bf16 v[100:103], v[132:135], v[210:213], v[100:103]
	v_mfma_f32_16x16x32_bf16 v[96:99], v[140:143], v[210:213], v[96:99]
	v_mfma_f32_16x16x32_bf16 v[124:127], v[136:139], v[174:177], v[124:127]
	v_mfma_f32_16x16x32_bf16 v[120:123], v[144:147], v[174:177], v[120:123]
	v_mfma_f32_16x16x32_bf16 v[116:119], v[136:139], v[182:185], v[116:119]
	v_mfma_f32_16x16x32_bf16 v[112:115], v[144:147], v[182:185], v[112:115]
	v_mfma_f32_16x16x32_bf16 v[108:111], v[136:139], v[206:209], v[108:111]
	v_mfma_f32_16x16x32_bf16 v[104:107], v[144:147], v[206:209], v[104:107]
	v_mfma_f32_16x16x32_bf16 v[100:103], v[136:139], v[214:217], v[100:103]
	v_mfma_f32_16x16x32_bf16 v[96:99], v[144:147], v[214:217], v[96:99]
	s_setprio 0
	s_setprio 1
	v_mfma_f32_16x16x32_bf16 v[92:95], v[148:151], v[170:173], v[92:95]
	v_mfma_f32_16x16x32_bf16 v[88:91], v[162:165], v[170:173], v[88:91]
	v_mfma_f32_16x16x32_bf16 v[84:87], v[148:151], v[178:181], v[84:87]
	v_mfma_f32_16x16x32_bf16 v[80:83], v[162:165], v[178:181], v[80:83]
	v_mfma_f32_16x16x32_bf16 v[76:79], v[148:151], v[186:189], v[76:79]
	v_mfma_f32_16x16x32_bf16 v[72:75], v[162:165], v[186:189], v[72:75]
	v_mfma_f32_16x16x32_bf16 v[68:71], v[148:151], v[210:213], v[68:71]
	v_mfma_f32_16x16x32_bf16 v[64:67], v[162:165], v[210:213], v[64:67]
	v_mfma_f32_16x16x32_bf16 v[92:95], v[158:161], v[174:177], v[92:95]
	v_mfma_f32_16x16x32_bf16 v[88:91], v[166:169], v[174:177], v[88:91]
	v_mfma_f32_16x16x32_bf16 v[84:87], v[158:161], v[182:185], v[84:87]
	v_mfma_f32_16x16x32_bf16 v[80:83], v[166:169], v[182:185], v[80:83]
	v_mfma_f32_16x16x32_bf16 v[76:79], v[158:161], v[206:209], v[76:79]
	v_mfma_f32_16x16x32_bf16 v[72:75], v[166:169], v[206:209], v[72:75]
	v_mfma_f32_16x16x32_bf16 v[68:71], v[158:161], v[214:217], v[68:71]
	v_mfma_f32_16x16x32_bf16 v[64:67], v[166:169], v[214:217], v[64:67]
	s_setprio 0
	s_barrier
	v_lshl_add_u64 v[222:223], v[218:219], 0, s[48:49]
	s_add_i32 m0, s75, 0x18000
	ds_read_b128 v[170:173], v191 offset:49152
	ds_read_b128 v[174:177], v191 offset:50176
	ds_read_b128 v[178:181], v201 offset:49152
	ds_read_b128 v[182:185], v201 offset:50176
	ds_read_b128 v[186:189], v202 offset:49152
	ds_read_b128 v[206:209], v202 offset:50176
	ds_read_b128 v[210:213], v203 offset:49152
	ds_read_b128 v[214:217], v203 offset:50176
	global_load_lds_dwordx4 v[222:223], off
	v_lshl_add_u64 v[222:223], v[218:219], 0, s[14:15]
	s_add_i32 m0, s75, 0x1a000
	s_nop 0
	global_load_lds_dwordx4 v[222:223], off
	v_lshl_add_u64 v[222:223], v[218:219], 0, s[56:57]
	s_add_i32 m0, s75, 0x1c000
	v_lshl_add_u64 v[218:219], v[218:219], 0, s[62:63]
	global_load_lds_dwordx4 v[222:223], off
	s_add_i32 m0, s75, 0x1e000
	s_nop 0
	global_load_lds_dwordx4 v[218:219], off
	v_lshl_add_u64 v[218:219], v[220:221], 0, s[48:49]
	s_mov_b32 m0, s85
	s_nop 0
	global_load_lds_dwordx4 v[218:219], off
	v_lshl_add_u64 v[218:219], v[220:221], 0, s[14:15]
	s_mov_b32 m0, s79
	s_nop 0
	global_load_lds_dwordx4 v[218:219], off
	s_waitcnt vmcnt(8)
	s_waitcnt lgkmcnt(0)
	s_barrier
	s_setprio 1
	s_waitcnt lgkmcnt(0)
	v_mfma_f32_16x16x32_bf16 v[60:63], v[132:135], v[170:173], v[60:63]
	v_mfma_f32_16x16x32_bf16 v[56:59], v[140:143], v[170:173], v[56:59]
	v_mfma_f32_16x16x32_bf16 v[52:55], v[132:135], v[178:181], v[52:55]
	v_mfma_f32_16x16x32_bf16 v[48:51], v[140:143], v[178:181], v[48:51]
	v_mfma_f32_16x16x32_bf16 v[44:47], v[132:135], v[186:189], v[44:47]
	v_mfma_f32_16x16x32_bf16 v[40:43], v[140:143], v[186:189], v[40:43]
	v_mfma_f32_16x16x32_bf16 v[36:39], v[132:135], v[210:213], v[36:39]
	v_mfma_f32_16x16x32_bf16 v[32:35], v[140:143], v[210:213], v[32:35]
	v_mfma_f32_16x16x32_bf16 v[60:63], v[136:139], v[174:177], v[60:63]
	v_mfma_f32_16x16x32_bf16 v[56:59], v[144:147], v[174:177], v[56:59]
	v_mfma_f32_16x16x32_bf16 v[52:55], v[136:139], v[182:185], v[52:55]
	v_mfma_f32_16x16x32_bf16 v[48:51], v[144:147], v[182:185], v[48:51]
	v_mfma_f32_16x16x32_bf16 v[44:47], v[136:139], v[206:209], v[44:47]
	v_mfma_f32_16x16x32_bf16 v[40:43], v[144:147], v[206:209], v[40:43]
	v_mfma_f32_16x16x32_bf16 v[36:39], v[136:139], v[214:217], v[36:39]
	v_mfma_f32_16x16x32_bf16 v[32:35], v[144:147], v[214:217], v[32:35]
	s_setprio 0
	s_setprio 1
	v_mfma_f32_16x16x32_bf16 v[28:31], v[148:151], v[170:173], v[28:31]
	v_mfma_f32_16x16x32_bf16 v[24:27], v[162:165], v[170:173], v[24:27]
	v_mfma_f32_16x16x32_bf16 v[20:23], v[148:151], v[178:181], v[20:23]
	v_mfma_f32_16x16x32_bf16 v[16:19], v[162:165], v[178:181], v[16:19]
	v_mfma_f32_16x16x32_bf16 v[12:15], v[148:151], v[186:189], v[12:15]
	v_mfma_f32_16x16x32_bf16 v[8:11], v[162:165], v[186:189], v[8:11]
	v_mfma_f32_16x16x32_bf16 v[4:7], v[148:151], v[210:213], v[4:7]
	v_mfma_f32_16x16x32_bf16 v[0:3], v[162:165], v[210:213], v[0:3]
	v_mfma_f32_16x16x32_bf16 v[28:31], v[158:161], v[174:177], v[28:31]
	v_mfma_f32_16x16x32_bf16 v[24:27], v[166:169], v[174:177], v[24:27]
	v_mfma_f32_16x16x32_bf16 v[20:23], v[158:161], v[182:185], v[20:23]
	v_mfma_f32_16x16x32_bf16 v[16:19], v[166:169], v[182:185], v[16:19]
	v_mfma_f32_16x16x32_bf16 v[12:15], v[158:161], v[206:209], v[12:15]
	v_mfma_f32_16x16x32_bf16 v[8:11], v[166:169], v[206:209], v[8:11]
	v_mfma_f32_16x16x32_bf16 v[4:7], v[158:161], v[214:217], v[4:7]
	v_mfma_f32_16x16x32_bf16 v[0:3], v[166:169], v[214:217], v[0:3]
	s_setprio 0
	s_barrier
	s_add_i32 s29, s29, 2
	s_add_u32 s46, s46, 0x100
	s_addc_u32 s47, s47, 0
	s_add_u32 s1, s1, 0x100
	s_addc_u32 s28, s28, 0
	s_cmp_lt_u32 s29, 14
